# K-loop MFMA segment edges: redundant lgkmcnt(0) behind each pre-MFMA barrier removed, priority drop moved behind the closing barrier
# speedup vs baseline: 1.0108x; 1.0064x over previous
; #define PG8_STAGE(bufoff, gbase, voff) do { _Pragma("unroll") for (int _i = 0; _i < 2; ++_i) \
;         __builtin_amdgcn_global_load_lds((const unsigned*)((const char*)(gbase) + (voff)[_i]), (PG8_LAS unsigned*)(lds + (bufoff) + ldsw + _i * 8192), 16, 0, 0); } while (0)
; #define PG8_LDA(dst, b, h) do { _Pragma("unroll") for (int m = 0; m < 4; ++m) _Pragma("unroll") for (int k = 0; k < 2; ++k) dst[m][k] = *(const PG8_LAS bf16x8*)(lds + PG8_SA(b, h) + aoff + m * 2048 + k * 1024); } while (0)
; #define PG8_LDB(dst, b, h) do { _Pragma("unroll") for (int n = 0; n < 2; ++n) _Pragma("unroll") for (int k = 0; k < 2; ++k) dst[n][k] = *(const PG8_LAS bf16x8*)(lds + PG8_SB(b, h) + boff + n * 2048 + k * 1024); } while (0)
; #define PG8_MMA(ai, bj, At, Bt) do { __builtin_amdgcn_s_setprio(1); _Pragma("unroll") for (int m = 0; m < 4; ++m) _Pragma("unroll") for (int n = 0; n < 2; ++n) _Pragma("unroll") for (int k = 0; k < 2; ++k) \
;         acc[ai][bj][m][n] = __builtin_amdgcn_mfma_f32_16x16x32_bf16(Bt[n][k], At[m][k], acc[ai][bj][m][n], 0, 0, 0); __builtin_amdgcn_s_setprio(0); } while (0)
; #define PG8_WAIT_V(n) asm volatile("s_waitcnt vmcnt(" #n ")" ::: "memory")
; #define PG8_WAIT_L(n) asm volatile("s_waitcnt lgkmcnt(" #n ")" ::: "memory")
; #define PG8_BAR __builtin_amdgcn_s_barrier()
; #define PG8_SCHED __builtin_amdgcn_sched_barrier(0)
; template <class Epi, class Sched, bool ALIGN_EPI = false, bool SP2 = false>
; __device__ __forceinline__ void gemm_phase(PG8_LAS unsigned char* lds, const Gemm g, const Sched& S, const Epi& E) {
;     ...
;             PG8_LDB(B0, 0, 0); PG8_LDB(B1, 0, 1); PG8_SCHED; PG8_LDA(At, 0, 0); PG8_STAGE(PG8_SA(1, 1), a1 + hstep, voffA);
;             PG8_WAIT_V(8); PG8_WAIT_L(0); PG8_BAR; PG8_MMA(0, 0, At, B0); PG8_MMA(0, 1, At, B1); PG8_BAR; PG8_SCHED;
;             PG8_LDA(At, 0, 1); PG8_STAGE(PG8_SB(0, 0), b2, voffB); PG8_STAGE(PG8_SB(0, 1), b2 + hstep, voffB); PG8_STAGE(PG8_SA(0, 0), a2, voffA);
;             PG8_WAIT_V(8); PG8_WAIT_L(0); PG8_BAR; PG8_MMA(1, 0, At, B0); PG8_MMA(1, 1, At, B1); PG8_BAR; PG8_SCHED;
.LBB0_129:
	ds_read_b128 v[96:99], v173
	ds_read_b128 v[100:103], v173 offset:1024
	ds_read_b128 v[104:107], v173 offset:2048
	ds_read_b128 v[112:115], v173 offset:3072
	ds_read_b128 v[178:181], v175
	ds_read_b128 v[182:185], v175 offset:1024
	ds_read_b128 v[186:189], v175 offset:2048
	ds_read_b128 v[190:193], v175 offset:3072
	s_add_u32 s44, s8, 0xfff80080
	s_addc_u32 s45, s9, -1
	s_cmp_eq_u32 s54, 28
	s_cselect_b32 s47, s25, s45
	s_cselect_b32 s46, s35, s44
	s_cselect_b32 s45, s23, s49
	s_cselect_b32 s44, s43, s48
	v_lshl_add_u64 v[160:161], s[8:9], 0, v[154:155]
	s_add_i32 m0, s63, 0xc000
	ds_read_b128 v[198:201], v177
	ds_read_b128 v[202:205], v177 offset:1024
	ds_read_b128 v[206:209], v177 offset:2048
	ds_read_b128 v[210:213], v177 offset:3072
	ds_read_b128 v[214:217], v177 offset:4096
	ds_read_b128 v[218:221], v177 offset:5120
	ds_read_b128 v[222:225], v177 offset:6144
	ds_read_b128 v[226:229], v177 offset:7168
	global_load_lds_dwordx4 v[160:161], off
	v_lshl_add_u64 v[160:161], s[8:9], 0, v[156:157]
	s_add_i32 m0, s63, 0xe000
	s_nop 0
	global_load_lds_dwordx4 v[160:161], off
	s_waitcnt vmcnt(8)
	s_waitcnt lgkmcnt(0)
	s_barrier
	s_setprio 1
	v_mfma_f32_16x16x32_bf16 v[140:143], v[96:99], v[198:201], v[140:143]
	v_mfma_f32_16x16x32_bf16 v[132:135], v[104:107], v[198:201], v[132:135]
	v_mfma_f32_16x16x32_bf16 v[116:119], v[96:99], v[206:209], v[116:119]
	v_mfma_f32_16x16x32_bf16 v[124:127], v[104:107], v[206:209], v[124:127]
	v_mfma_f32_16x16x32_bf16 v[84:87], v[96:99], v[214:217], v[84:87]
	v_mfma_f32_16x16x32_bf16 v[92:95], v[104:107], v[214:217], v[92:95]
	v_mfma_f32_16x16x32_bf16 v[68:71], v[96:99], v[222:225], v[68:71]
	v_mfma_f32_16x16x32_bf16 v[76:79], v[104:107], v[222:225], v[76:79]
	v_mfma_f32_16x16x32_bf16 v[140:143], v[100:103], v[202:205], v[140:143]
	v_mfma_f32_16x16x32_bf16 v[132:135], v[112:115], v[202:205], v[132:135]
	v_mfma_f32_16x16x32_bf16 v[116:119], v[100:103], v[210:213], v[116:119]
	v_mfma_f32_16x16x32_bf16 v[124:127], v[112:115], v[210:213], v[124:127]
	v_mfma_f32_16x16x32_bf16 v[84:87], v[100:103], v[218:221], v[84:87]
	v_mfma_f32_16x16x32_bf16 v[92:95], v[112:115], v[218:221], v[92:95]
	v_mfma_f32_16x16x32_bf16 v[68:71], v[100:103], v[226:229], v[68:71]
	v_mfma_f32_16x16x32_bf16 v[76:79], v[112:115], v[226:229], v[76:79]
	s_setprio 0
	s_setprio 1
	v_mfma_f32_16x16x32_bf16 v[128:131], v[178:181], v[198:201], v[128:131]
	v_mfma_f32_16x16x32_bf16 v[136:139], v[186:189], v[198:201], v[136:139]
	v_mfma_f32_16x16x32_bf16 v[120:123], v[178:181], v[206:209], v[120:123]
	v_mfma_f32_16x16x32_bf16 v[108:111], v[186:189], v[206:209], v[108:111]
	v_mfma_f32_16x16x32_bf16 v[88:91], v[178:181], v[214:217], v[88:91]
	v_mfma_f32_16x16x32_bf16 v[80:83], v[186:189], v[214:217], v[80:83]
	v_mfma_f32_16x16x32_bf16 v[72:75], v[178:181], v[222:225], v[72:75]
	v_mfma_f32_16x16x32_bf16 v[64:67], v[186:189], v[222:225], v[64:67]
	v_mfma_f32_16x16x32_bf16 v[128:131], v[182:185], v[202:205], v[128:131]
	v_mfma_f32_16x16x32_bf16 v[136:139], v[190:193], v[202:205], v[136:139]
	v_mfma_f32_16x16x32_bf16 v[120:123], v[182:185], v[210:213], v[120:123]
	v_mfma_f32_16x16x32_bf16 v[108:111], v[190:193], v[210:213], v[108:111]
	v_mfma_f32_16x16x32_bf16 v[88:91], v[182:185], v[218:221], v[88:91]
	v_mfma_f32_16x16x32_bf16 v[80:83], v[190:193], v[218:221], v[80:83]
	v_mfma_f32_16x16x32_bf16 v[72:75], v[182:185], v[226:229], v[72:75]
	v_mfma_f32_16x16x32_bf16 v[64:67], v[190:193], v[226:229], v[64:67]
	s_barrier
	s_setprio 0
	s_add_i32 s55, s52, s62
	v_lshl_add_u64 v[160:161], s[44:45], 0, v[144:145]
	s_mov_b32 m0, s55
	ds_read_b128 v[198:201], v177 offset:16384
	ds_read_b128 v[202:205], v177 offset:17408
	ds_read_b128 v[206:209], v177 offset:18432
	ds_read_b128 v[210:213], v177 offset:19456
	ds_read_b128 v[214:217], v177 offset:20480
	ds_read_b128 v[218:221], v177 offset:21504
	ds_read_b128 v[222:225], v177 offset:22528
	ds_read_b128 v[226:229], v177 offset:23552
	global_load_lds_dwordx4 v[160:161], off
	s_add_i32 m0, s55, 0x2000
	s_add_u32 s56, s44, 0x80000
	v_lshl_add_u64 v[164:165], s[44:45], 0, v[146:147]
	s_addc_u32 s57, s45, 0
	s_add_i32 s55, s53, s62
	global_load_lds_dwordx4 v[164:165], off
	v_lshl_add_u64 v[170:171], s[56:57], 0, v[144:145]
	s_mov_b32 m0, s55
	v_lshl_add_u64 v[194:195], s[46:47], 0, v[146:147]
	global_load_lds_dwordx4 v[170:171], off
	v_lshl_add_u64 v[170:171], s[56:57], 0, v[146:147]
	s_add_i32 m0, s55, 0x2000
	s_nop 0
	global_load_lds_dwordx4 v[170:171], off
	v_lshl_add_u64 v[170:171], s[46:47], 0, v[144:145]
	s_mov_b32 m0, s63
	s_nop 0
	global_load_lds_dwordx4 v[170:171], off
	s_mov_b32 m0, s64
	s_nop 0
	global_load_lds_dwordx4 v[194:195], off
	s_waitcnt vmcnt(8)
	s_waitcnt lgkmcnt(0)
	s_barrier
; #define PG8_STAGE(bufoff, gbase, voff) do { _Pragma("unroll") for (int _i = 0; _i < 2; ++_i) \
;         __builtin_amdgcn_global_load_lds((const unsigned*)((const char*)(gbase) + (voff)[_i]), (PG8_LAS unsigned*)(lds + (bufoff) + ldsw + _i * 8192), 16, 0, 0); } while (0)
; #define PG8_LDA(dst, b, h) do { _Pragma("unroll") for (int m = 0; m < 4; ++m) _Pragma("unroll") for (int k = 0; k < 2; ++k) dst[m][k] = *(const PG8_LAS bf16x8*)(lds + PG8_SA(b, h) + aoff + m * 2048 + k * 1024); } while (0)
; #define PG8_LDB(dst, b, h) do { _Pragma("unroll") for (int n = 0; n < 2; ++n) _Pragma("unroll") for (int k = 0; k < 2; ++k) dst[n][k] = *(const PG8_LAS bf16x8*)(lds + PG8_SB(b, h) + boff + n * 2048 + k * 1024); } while (0)
; #define PG8_MMA(ai, bj, At, Bt) do { __builtin_amdgcn_s_setprio(1); _Pragma("unroll") for (int m = 0; m < 4; ++m) _Pragma("unroll") for (int n = 0; n < 2; ++n) _Pragma("unroll") for (int k = 0; k < 2; ++k) \
;         acc[ai][bj][m][n] = __builtin_amdgcn_mfma_f32_16x16x32_bf16(Bt[n][k], At[m][k], acc[ai][bj][m][n], 0, 0, 0); __builtin_amdgcn_s_setprio(0); } while (0)
; #define PG8_WAIT_V(n) asm volatile("s_waitcnt vmcnt(" #n ")" ::: "memory")
; #define PG8_WAIT_L(n) asm volatile("s_waitcnt lgkmcnt(" #n ")" ::: "memory")
; #define PG8_BAR __builtin_amdgcn_s_barrier()
; #define PG8_SCHED __builtin_amdgcn_sched_barrier(0)
; template <class Epi, class Sched, bool ALIGN_EPI = false, bool SP2 = false>
; __device__ __forceinline__ void gemm_phase(PG8_LAS unsigned char* lds, const Gemm g, const Sched& S, const Epi& E) {
;     ...
;             PG8_WAIT_V(8); PG8_WAIT_L(0); PG8_BAR; PG8_MMA(1, 0, At, B0); PG8_MMA(1, 1, At, B1); PG8_BAR; PG8_SCHED;
;             PG8_LDB(B0, 1, 0); PG8_LDB(B1, 1, 1); PG8_SCHED; PG8_LDA(At, 1, 0); PG8_STAGE(PG8_SA(0, 1), a2 + hstep, voffA);
;             PG8_WAIT_V(8); PG8_WAIT_L(0); PG8_BAR; PG8_MMA(0, 0, At, B0); PG8_MMA(0, 1, At, B1); PG8_BAR; PG8_SCHED;
	s_setprio 1
	v_mfma_f32_16x16x32_bf16 v[60:63], v[96:99], v[198:201], v[60:63]
	v_mfma_f32_16x16x32_bf16 v[52:55], v[104:107], v[198:201], v[52:55]
	v_mfma_f32_16x16x32_bf16 v[36:39], v[96:99], v[206:209], v[36:39]
	v_mfma_f32_16x16x32_bf16 v[44:47], v[104:107], v[206:209], v[44:47]
	v_mfma_f32_16x16x32_bf16 v[20:23], v[96:99], v[214:217], v[20:23]
	v_mfma_f32_16x16x32_bf16 v[28:31], v[104:107], v[214:217], v[28:31]
	v_mfma_f32_16x16x32_bf16 v[4:7], v[96:99], v[222:225], v[4:7]
	v_mfma_f32_16x16x32_bf16 v[12:15], v[104:107], v[222:225], v[12:15]
	v_mfma_f32_16x16x32_bf16 v[60:63], v[100:103], v[202:205], v[60:63]
	v_mfma_f32_16x16x32_bf16 v[52:55], v[112:115], v[202:205], v[52:55]
	v_mfma_f32_16x16x32_bf16 v[36:39], v[100:103], v[210:213], v[36:39]
	v_mfma_f32_16x16x32_bf16 v[44:47], v[112:115], v[210:213], v[44:47]
	v_mfma_f32_16x16x32_bf16 v[20:23], v[100:103], v[218:221], v[20:23]
	v_mfma_f32_16x16x32_bf16 v[28:31], v[112:115], v[218:221], v[28:31]
	v_mfma_f32_16x16x32_bf16 v[4:7], v[100:103], v[226:229], v[4:7]
	v_mfma_f32_16x16x32_bf16 v[12:15], v[112:115], v[226:229], v[12:15]
	s_setprio 0
	s_setprio 1
	v_mfma_f32_16x16x32_bf16 v[48:51], v[178:181], v[198:201], v[48:51]
	v_mfma_f32_16x16x32_bf16 v[56:59], v[186:189], v[198:201], v[56:59]
	v_mfma_f32_16x16x32_bf16 v[40:43], v[178:181], v[206:209], v[40:43]
	v_mfma_f32_16x16x32_bf16 v[32:35], v[186:189], v[206:209], v[32:35]
	v_mfma_f32_16x16x32_bf16 v[24:27], v[178:181], v[214:217], v[24:27]
	v_mfma_f32_16x16x32_bf16 v[16:19], v[186:189], v[214:217], v[16:19]
	v_mfma_f32_16x16x32_bf16 v[8:11], v[178:181], v[222:225], v[8:11]
	v_mfma_f32_16x16x32_bf16 v[0:3], v[186:189], v[222:225], v[0:3]
	v_mfma_f32_16x16x32_bf16 v[48:51], v[182:185], v[202:205], v[48:51]
	v_mfma_f32_16x16x32_bf16 v[56:59], v[190:193], v[202:205], v[56:59]
	v_mfma_f32_16x16x32_bf16 v[40:43], v[182:185], v[210:213], v[40:43]
	v_mfma_f32_16x16x32_bf16 v[32:35], v[190:193], v[210:213], v[32:35]
	v_mfma_f32_16x16x32_bf16 v[24:27], v[182:185], v[218:221], v[24:27]
	v_mfma_f32_16x16x32_bf16 v[16:19], v[190:193], v[218:221], v[16:19]
	v_mfma_f32_16x16x32_bf16 v[8:11], v[182:185], v[226:229], v[8:11]
	v_mfma_f32_16x16x32_bf16 v[0:3], v[190:193], v[226:229], v[0:3]
	s_barrier
	s_setprio 0
	s_add_i32 s55, 0, 0x18000
	s_add_i32 s56, 0, 0x1c000
	v_add_u32_e32 v112, s55, v167
	v_add_u32_e32 v162, s56, v167
	ds_read_b128 v[96:99], v112
	ds_read_b128 v[100:103], v112 offset:1024
	ds_read_b128 v[104:107], v112 offset:2048
	ds_read_b128 v[112:115], v112 offset:3072
	ds_read_b128 v[178:181], v162
	ds_read_b128 v[182:185], v162 offset:1024
	ds_read_b128 v[186:189], v162 offset:2048
	ds_read_b128 v[190:193], v162 offset:3072
	s_add_u32 s46, s46, 0x80000
	s_addc_u32 s47, s47, 0
	s_mov_b32 m0, s65
	v_lshl_add_u64 v[230:231], s[46:47], 0, v[144:145]
	ds_read_b128 v[198:201], v177 offset:32768
	ds_read_b128 v[202:205], v177 offset:33792
	ds_read_b128 v[206:209], v177 offset:34816
	ds_read_b128 v[210:213], v177 offset:35840
	ds_read_b128 v[214:217], v177 offset:36864
	ds_read_b128 v[218:221], v177 offset:37888
	ds_read_b128 v[222:225], v177 offset:38912
	ds_read_b128 v[226:229], v177 offset:39936
	global_load_lds_dwordx4 v[230:231], off
	v_lshl_add_u64 v[230:231], s[46:47], 0, v[146:147]
	s_mov_b32 m0, s66
	s_nop 0
	global_load_lds_dwordx4 v[230:231], off
	s_waitcnt vmcnt(8)
	s_waitcnt lgkmcnt(0)
	s_barrier
	s_setprio 1
	v_mfma_f32_16x16x32_bf16 v[140:143], v[96:99], v[198:201], v[140:143]
	v_mfma_f32_16x16x32_bf16 v[132:135], v[104:107], v[198:201], v[132:135]
	v_mfma_f32_16x16x32_bf16 v[116:119], v[96:99], v[206:209], v[116:119]
	v_mfma_f32_16x16x32_bf16 v[124:127], v[104:107], v[206:209], v[124:127]
	v_mfma_f32_16x16x32_bf16 v[84:87], v[96:99], v[214:217], v[84:87]
	v_mfma_f32_16x16x32_bf16 v[92:95], v[104:107], v[214:217], v[92:95]
	v_mfma_f32_16x16x32_bf16 v[68:71], v[96:99], v[222:225], v[68:71]
	v_mfma_f32_16x16x32_bf16 v[76:79], v[104:107], v[222:225], v[76:79]
	v_mfma_f32_16x16x32_bf16 v[140:143], v[100:103], v[202:205], v[140:143]
	v_mfma_f32_16x16x32_bf16 v[132:135], v[112:115], v[202:205], v[132:135]
	v_mfma_f32_16x16x32_bf16 v[116:119], v[100:103], v[210:213], v[116:119]
	v_mfma_f32_16x16x32_bf16 v[124:127], v[112:115], v[210:213], v[124:127]
	v_mfma_f32_16x16x32_bf16 v[84:87], v[100:103], v[218:221], v[84:87]
	v_mfma_f32_16x16x32_bf16 v[92:95], v[112:115], v[218:221], v[92:95]
	v_mfma_f32_16x16x32_bf16 v[68:71], v[100:103], v[226:229], v[68:71]
	v_mfma_f32_16x16x32_bf16 v[76:79], v[112:115], v[226:229], v[76:79]
	s_setprio 0
	s_setprio 1
	v_mfma_f32_16x16x32_bf16 v[128:131], v[178:181], v[198:201], v[128:131]
	v_mfma_f32_16x16x32_bf16 v[136:139], v[186:189], v[198:201], v[136:139]
	v_mfma_f32_16x16x32_bf16 v[120:123], v[178:181], v[206:209], v[120:123]
	v_mfma_f32_16x16x32_bf16 v[108:111], v[186:189], v[206:209], v[108:111]
	v_mfma_f32_16x16x32_bf16 v[88:91], v[178:181], v[214:217], v[88:91]
	v_mfma_f32_16x16x32_bf16 v[80:83], v[186:189], v[214:217], v[80:83]
	v_mfma_f32_16x16x32_bf16 v[72:75], v[178:181], v[222:225], v[72:75]
	v_mfma_f32_16x16x32_bf16 v[64:67], v[186:189], v[222:225], v[64:67]
	v_mfma_f32_16x16x32_bf16 v[128:131], v[182:185], v[202:205], v[128:131]
	v_mfma_f32_16x16x32_bf16 v[136:139], v[190:193], v[202:205], v[136:139]
	v_mfma_f32_16x16x32_bf16 v[120:123], v[182:185], v[210:213], v[120:123]
	v_mfma_f32_16x16x32_bf16 v[108:111], v[190:193], v[210:213], v[108:111]
	v_mfma_f32_16x16x32_bf16 v[88:91], v[182:185], v[218:221], v[88:91]
	v_mfma_f32_16x16x32_bf16 v[80:83], v[190:193], v[218:221], v[80:83]
	v_mfma_f32_16x16x32_bf16 v[72:75], v[182:185], v[226:229], v[72:75]
	v_mfma_f32_16x16x32_bf16 v[64:67], v[190:193], v[226:229], v[64:67]
	s_barrier
; #define PG8_STAGE(bufoff, gbase, voff) do { _Pragma("unroll") for (int _i = 0; _i < 2; ++_i) \
;         __builtin_amdgcn_global_load_lds((const unsigned*)((const char*)(gbase) + (voff)[_i]), (PG8_LAS unsigned*)(lds + (bufoff) + ldsw + _i * 8192), 16, 0, 0); } while (0)
; #define PG8_LDA(dst, b, h) do { _Pragma("unroll") for (int m = 0; m < 4; ++m) _Pragma("unroll") for (int k = 0; k < 2; ++k) dst[m][k] = *(const PG8_LAS bf16x8*)(lds + PG8_SA(b, h) + aoff + m * 2048 + k * 1024); } while (0)
; #define PG8_MMA(ai, bj, At, Bt) do { __builtin_amdgcn_s_setprio(1); _Pragma("unroll") for (int m = 0; m < 4; ++m) _Pragma("unroll") for (int n = 0; n < 2; ++n) _Pragma("unroll") for (int k = 0; k < 2; ++k) \
;         acc[ai][bj][m][n] = __builtin_amdgcn_mfma_f32_16x16x32_bf16(Bt[n][k], At[m][k], acc[ai][bj][m][n], 0, 0, 0); __builtin_amdgcn_s_setprio(0); } while (0)
; #define PG8_WAIT_V(n) asm volatile("s_waitcnt vmcnt(" #n ")" ::: "memory")
; #define PG8_WAIT_L(n) asm volatile("s_waitcnt lgkmcnt(" #n ")" ::: "memory")
; #define PG8_BAR __builtin_amdgcn_s_barrier()
; #define PG8_SCHED __builtin_amdgcn_sched_barrier(0)
; template <class Epi, class Sched, bool ALIGN_EPI = false, bool SP2 = false>
; __device__ __forceinline__ void gemm_phase(PG8_LAS unsigned char* lds, const Gemm g, const Sched& S, const Epi& E) {
;     ...
;             PG8_WAIT_V(8); PG8_WAIT_L(0); PG8_BAR; PG8_MMA(0, 0, At, B0); PG8_MMA(0, 1, At, B1); PG8_BAR; PG8_SCHED;
;             PG8_LDA(At, 1, 1); PG8_STAGE(PG8_SB(1, 0), b3, voffB); PG8_STAGE(PG8_SB(1, 1), b3 + hstep, voffB); PG8_STAGE(PG8_SA(1, 0), a3, voffA);
;             PG8_WAIT_V(8); PG8_WAIT_L(0); PG8_BAR; PG8_MMA(1, 0, At, B0); PG8_MMA(1, 1, At, B1); PG8_BAR; PG8_SCHED;
	s_setprio 0
	s_add_i32 s46, s55, s62
	v_lshl_add_u64 v[160:161], v[160:161], 0, s[12:13]
	s_mov_b32 m0, s46
	ds_read_b128 v[198:201], v177 offset:49152
	ds_read_b128 v[202:205], v177 offset:50176
	ds_read_b128 v[206:209], v177 offset:51200
	ds_read_b128 v[210:213], v177 offset:52224
	ds_read_b128 v[214:217], v177 offset:53248
	ds_read_b128 v[218:221], v177 offset:54272
	ds_read_b128 v[222:225], v177 offset:55296
	ds_read_b128 v[226:229], v177 offset:56320
	global_load_lds_dwordx4 v[160:161], off
	s_add_i32 m0, s46, 0x2000
	s_add_u32 s44, s44, 0x80080
	v_lshl_add_u64 v[160:161], v[164:165], 0, s[12:13]
	s_addc_u32 s45, s45, 0
	s_add_i32 s46, s56, s62
	global_load_lds_dwordx4 v[160:161], off
	v_lshl_add_u64 v[160:161], s[44:45], 0, v[144:145]
	s_mov_b32 m0, s46
	s_nop 0
	global_load_lds_dwordx4 v[160:161], off
	v_lshl_add_u64 v[160:161], s[44:45], 0, v[146:147]
	s_add_i32 m0, s46, 0x2000
	s_nop 0
	global_load_lds_dwordx4 v[160:161], off
	v_lshl_add_u64 v[160:161], v[170:171], 0, s[12:13]
	s_mov_b32 m0, s68
	s_nop 0
	global_load_lds_dwordx4 v[160:161], off
	v_lshl_add_u64 v[160:161], v[194:195], 0, s[12:13]
	s_mov_b32 m0, s69
	s_nop 0
	global_load_lds_dwordx4 v[160:161], off
	s_waitcnt vmcnt(8)
	s_waitcnt lgkmcnt(0)
	s_barrier
	s_setprio 1
	v_mfma_f32_16x16x32_bf16 v[60:63], v[96:99], v[198:201], v[60:63]
	v_mfma_f32_16x16x32_bf16 v[52:55], v[104:107], v[198:201], v[52:55]
	v_mfma_f32_16x16x32_bf16 v[36:39], v[96:99], v[206:209], v[36:39]
	v_mfma_f32_16x16x32_bf16 v[44:47], v[104:107], v[206:209], v[44:47]
	v_mfma_f32_16x16x32_bf16 v[20:23], v[96:99], v[214:217], v[20:23]
	v_mfma_f32_16x16x32_bf16 v[28:31], v[104:107], v[214:217], v[28:31]
	v_mfma_f32_16x16x32_bf16 v[4:7], v[96:99], v[222:225], v[4:7]
	v_mfma_f32_16x16x32_bf16 v[12:15], v[104:107], v[222:225], v[12:15]
	v_mfma_f32_16x16x32_bf16 v[60:63], v[100:103], v[202:205], v[60:63]
	v_mfma_f32_16x16x32_bf16 v[52:55], v[112:115], v[202:205], v[52:55]
	v_mfma_f32_16x16x32_bf16 v[36:39], v[100:103], v[210:213], v[36:39]
	v_mfma_f32_16x16x32_bf16 v[44:47], v[112:115], v[210:213], v[44:47]
	v_mfma_f32_16x16x32_bf16 v[20:23], v[100:103], v[218:221], v[20:23]
	v_mfma_f32_16x16x32_bf16 v[28:31], v[112:115], v[218:221], v[28:31]
	v_mfma_f32_16x16x32_bf16 v[4:7], v[100:103], v[226:229], v[4:7]
	v_mfma_f32_16x16x32_bf16 v[12:15], v[112:115], v[226:229], v[12:15]
	s_setprio 0
	s_setprio 1
	v_mfma_f32_16x16x32_bf16 v[48:51], v[178:181], v[198:201], v[48:51]
	v_mfma_f32_16x16x32_bf16 v[56:59], v[186:189], v[198:201], v[56:59]
	v_mfma_f32_16x16x32_bf16 v[40:43], v[178:181], v[206:209], v[40:43]
	v_mfma_f32_16x16x32_bf16 v[32:35], v[186:189], v[206:209], v[32:35]
	v_mfma_f32_16x16x32_bf16 v[24:27], v[178:181], v[214:217], v[24:27]
	v_mfma_f32_16x16x32_bf16 v[16:19], v[186:189], v[214:217], v[16:19]
	v_mfma_f32_16x16x32_bf16 v[8:11], v[178:181], v[222:225], v[8:11]
	v_mfma_f32_16x16x32_bf16 v[0:3], v[186:189], v[222:225], v[0:3]
	v_mfma_f32_16x16x32_bf16 v[48:51], v[182:185], v[202:205], v[48:51]
	v_mfma_f32_16x16x32_bf16 v[56:59], v[190:193], v[202:205], v[56:59]
	v_mfma_f32_16x16x32_bf16 v[40:43], v[182:185], v[210:213], v[40:43]
	v_mfma_f32_16x16x32_bf16 v[32:35], v[190:193], v[210:213], v[32:35]
	v_mfma_f32_16x16x32_bf16 v[24:27], v[182:185], v[218:221], v[24:27]
	v_mfma_f32_16x16x32_bf16 v[16:19], v[190:193], v[218:221], v[16:19]
	v_mfma_f32_16x16x32_bf16 v[8:11], v[182:185], v[226:229], v[8:11]
	v_mfma_f32_16x16x32_bf16 v[0:3], v[190:193], v[226:229], v[0:3]
	s_barrier
	s_setprio 0
	s_add_i32 s54, s54, 2
	s_add_u32 s8, s8, 0x100
	s_addc_u32 s9, s9, 0
	s_add_u32 s48, s48, 0x100
	s_addc_u32 s49, s49, 0
	s_cmp_gt_u32 s54, 29
	s_cbranch_scc0 .LBB0_129
	s_and_b64 vcc, exec, s[14:15]
	s_cbranch_vccz .LBB0_132
	s_barrier

; #define PG8_STAGE(bufoff, gbase, voff) do { _Pragma("unroll") for (int _i = 0; _i < 2; ++_i) \
;         __builtin_amdgcn_global_load_lds((const unsigned*)((const char*)(gbase) + (voff)[_i]), (PG8_LAS unsigned*)(lds + (bufoff) + ldsw + _i * 8192), 16, 0, 0); } while (0)
; #define PG8_LDA(dst, b, h) do { _Pragma("unroll") for (int m = 0; m < 4; ++m) _Pragma("unroll") for (int k = 0; k < 2; ++k) dst[m][k] = *(const PG8_LAS bf16x8*)(lds + PG8_SA(b, h) + aoff + m * 2048 + k * 1024); } while (0)
; #define PG8_LDB(dst, b, h) do { _Pragma("unroll") for (int n = 0; n < 2; ++n) _Pragma("unroll") for (int k = 0; k < 2; ++k) dst[n][k] = *(const PG8_LAS bf16x8*)(lds + PG8_SB(b, h) + boff + n * 2048 + k * 1024); } while (0)
; #define PG8_MMA(ai, bj, At, Bt) do { __builtin_amdgcn_s_setprio(1); _Pragma("unroll") for (int m = 0; m < 4; ++m) _Pragma("unroll") for (int n = 0; n < 2; ++n) _Pragma("unroll") for (int k = 0; k < 2; ++k) \
;         acc[ai][bj][m][n] = __builtin_amdgcn_mfma_f32_16x16x32_bf16(Bt[n][k], At[m][k], acc[ai][bj][m][n], 0, 0, 0); __builtin_amdgcn_s_setprio(0); } while (0)
; #define PG8_WAIT_V(n) asm volatile("s_waitcnt vmcnt(" #n ")" ::: "memory")
; #define PG8_WAIT_L(n) asm volatile("s_waitcnt lgkmcnt(" #n ")" ::: "memory")
; #define PG8_BAR __builtin_amdgcn_s_barrier()
; #define PG8_SCHED __builtin_amdgcn_sched_barrier(0)
; template <class Epi, class Sched, bool ALIGN_EPI = false, bool SP2 = false>
; __device__ __forceinline__ void gemm_phase(PG8_LAS unsigned char* lds, const Gemm g, const Sched& S, const Epi& E) {
;     ...
;             PG8_LDB(B0, 0, 0); PG8_LDB(B1, 0, 1); PG8_SCHED; PG8_LDA(At, 0, 0); PG8_STAGE(PG8_SA(1, 1), a1 + hstep, voffA);
;             PG8_WAIT_V(8); PG8_WAIT_L(0); PG8_BAR; PG8_MMA(0, 0, At, B0); PG8_MMA(0, 1, At, B1); PG8_BAR; PG8_SCHED;
;             PG8_LDA(At, 0, 1); PG8_STAGE(PG8_SB(0, 0), b2, voffB); PG8_STAGE(PG8_SB(0, 1), b2 + hstep, voffB); PG8_STAGE(PG8_SA(0, 0), a2, voffA);
;             PG8_WAIT_V(8); PG8_WAIT_L(0); PG8_BAR; PG8_MMA(1, 0, At, B0); PG8_MMA(1, 1, At, B1); PG8_BAR; PG8_SCHED;
.LBB0_307:
	ds_read_b128 v[128:131], v181
	ds_read_b128 v[132:135], v181 offset:1024
	ds_read_b128 v[136:139], v181 offset:2048
	ds_read_b128 v[140:143], v181 offset:3072
	ds_read_b128 v[144:147], v182
	ds_read_b128 v[148:151], v182 offset:1024
	ds_read_b128 v[168:171], v182 offset:2048
	ds_read_b128 v[172:175], v182 offset:3072
	s_add_u32 s28, s26, 0xfff80080
	s_addc_u32 s29, s27, -1
	s_cmp_eq_u32 s50, 28
	s_cselect_b32 s31, s7, s29
	s_cselect_b32 s30, s21, s28
	s_cselect_b32 s29, s19, s49
	s_cselect_b32 s28, s33, s48
	v_lshl_add_u64 v[176:177], s[26:27], 0, v[160:161]
	s_add_i32 m0, s35, 0xc000
	ds_read_b128 v[186:189], v183
	ds_read_b128 v[190:193], v183 offset:1024
	ds_read_b128 v[198:201], v183 offset:2048
	ds_read_b128 v[202:205], v183 offset:3072
	ds_read_b128 v[206:209], v183 offset:4096
	ds_read_b128 v[210:213], v183 offset:5120
	ds_read_b128 v[214:217], v183 offset:6144
	ds_read_b128 v[218:221], v183 offset:7168
	global_load_lds_dwordx4 v[176:177], off
	v_lshl_add_u64 v[176:177], s[26:27], 0, v[162:163]
	s_add_i32 m0, s35, 0xe000
	s_nop 0
	global_load_lds_dwordx4 v[176:177], off
	s_waitcnt vmcnt(8)
	s_waitcnt lgkmcnt(0)
	s_barrier
	s_setprio 1
	v_mfma_f32_16x16x32_bf16 v[124:127], v[128:131], v[186:189], v[124:127]
	v_mfma_f32_16x16x32_bf16 v[120:123], v[136:139], v[186:189], v[120:123]
	v_mfma_f32_16x16x32_bf16 v[104:107], v[128:131], v[198:201], v[104:107]
	v_mfma_f32_16x16x32_bf16 v[108:111], v[136:139], v[198:201], v[108:111]
	v_mfma_f32_16x16x32_bf16 v[88:91], v[128:131], v[206:209], v[88:91]
	v_mfma_f32_16x16x32_bf16 v[92:95], v[136:139], v[206:209], v[92:95]
	v_mfma_f32_16x16x32_bf16 v[72:75], v[128:131], v[214:217], v[72:75]
	v_mfma_f32_16x16x32_bf16 v[76:79], v[136:139], v[214:217], v[76:79]
	v_mfma_f32_16x16x32_bf16 v[124:127], v[132:135], v[190:193], v[124:127]
	v_mfma_f32_16x16x32_bf16 v[120:123], v[140:143], v[190:193], v[120:123]
	v_mfma_f32_16x16x32_bf16 v[104:107], v[132:135], v[202:205], v[104:107]
	v_mfma_f32_16x16x32_bf16 v[108:111], v[140:143], v[202:205], v[108:111]
	v_mfma_f32_16x16x32_bf16 v[88:91], v[132:135], v[210:213], v[88:91]
	v_mfma_f32_16x16x32_bf16 v[92:95], v[140:143], v[210:213], v[92:95]
	v_mfma_f32_16x16x32_bf16 v[72:75], v[132:135], v[218:221], v[72:75]
	v_mfma_f32_16x16x32_bf16 v[76:79], v[140:143], v[218:221], v[76:79]
	s_setprio 0
	s_setprio 1
	v_mfma_f32_16x16x32_bf16 v[116:119], v[144:147], v[186:189], v[116:119]
	v_mfma_f32_16x16x32_bf16 v[112:115], v[168:171], v[186:189], v[112:115]
	v_mfma_f32_16x16x32_bf16 v[100:103], v[144:147], v[198:201], v[100:103]
	v_mfma_f32_16x16x32_bf16 v[96:99], v[168:171], v[198:201], v[96:99]
	v_mfma_f32_16x16x32_bf16 v[84:87], v[144:147], v[206:209], v[84:87]
	v_mfma_f32_16x16x32_bf16 v[80:83], v[168:171], v[206:209], v[80:83]
	v_mfma_f32_16x16x32_bf16 v[68:71], v[144:147], v[214:217], v[68:71]
	v_mfma_f32_16x16x32_bf16 v[64:67], v[168:171], v[214:217], v[64:67]
	v_mfma_f32_16x16x32_bf16 v[116:119], v[148:151], v[190:193], v[116:119]
	v_mfma_f32_16x16x32_bf16 v[112:115], v[172:175], v[190:193], v[112:115]
	v_mfma_f32_16x16x32_bf16 v[100:103], v[148:151], v[202:205], v[100:103]
	v_mfma_f32_16x16x32_bf16 v[96:99], v[172:175], v[202:205], v[96:99]
	v_mfma_f32_16x16x32_bf16 v[84:87], v[148:151], v[210:213], v[84:87]
	v_mfma_f32_16x16x32_bf16 v[80:83], v[172:175], v[210:213], v[80:83]
	v_mfma_f32_16x16x32_bf16 v[68:71], v[148:151], v[218:221], v[68:71]
	v_mfma_f32_16x16x32_bf16 v[64:67], v[172:175], v[218:221], v[64:67]
	s_barrier
	s_setprio 0
	s_add_i32 s51, s62, s34
	v_lshl_add_u64 v[176:177], s[28:29], 0, v[154:155]
	s_mov_b32 m0, s51
	ds_read_b128 v[186:189], v183 offset:16384
	ds_read_b128 v[190:193], v183 offset:17408
	ds_read_b128 v[198:201], v183 offset:18432
	ds_read_b128 v[202:205], v183 offset:19456
	ds_read_b128 v[206:209], v183 offset:20480
	ds_read_b128 v[210:213], v183 offset:21504
	ds_read_b128 v[214:217], v183 offset:22528
	ds_read_b128 v[218:221], v183 offset:23552
	global_load_lds_dwordx4 v[176:177], off
	s_add_i32 m0, s51, 0x2000
	s_add_u32 s52, s28, 0x80000
	v_lshl_add_u64 v[194:195], s[28:29], 0, v[158:159]
	s_addc_u32 s53, s29, 0
	s_add_i32 s51, s63, s34
	global_load_lds_dwordx4 v[194:195], off
	v_lshl_add_u64 v[222:223], s[52:53], 0, v[154:155]
	s_mov_b32 m0, s51
	v_lshl_add_u64 v[224:225], s[30:31], 0, v[156:157]
	global_load_lds_dwordx4 v[222:223], off
	v_lshl_add_u64 v[222:223], s[52:53], 0, v[158:159]
	s_add_i32 m0, s51, 0x2000
	s_nop 0
	global_load_lds_dwordx4 v[222:223], off
	v_lshl_add_u64 v[222:223], s[30:31], 0, v[152:153]
	s_mov_b32 m0, s35
	s_nop 0
	global_load_lds_dwordx4 v[222:223], off
	s_mov_b32 m0, s37
	s_nop 0
	global_load_lds_dwordx4 v[224:225], off
	s_waitcnt vmcnt(8)
	s_waitcnt lgkmcnt(0)
	s_barrier
; #define PG8_STAGE(bufoff, gbase, voff) do { _Pragma("unroll") for (int _i = 0; _i < 2; ++_i) \
;         __builtin_amdgcn_global_load_lds((const unsigned*)((const char*)(gbase) + (voff)[_i]), (PG8_LAS unsigned*)(lds + (bufoff) + ldsw + _i * 8192), 16, 0, 0); } while (0)
; #define PG8_LDA(dst, b, h) do { _Pragma("unroll") for (int m = 0; m < 4; ++m) _Pragma("unroll") for (int k = 0; k < 2; ++k) dst[m][k] = *(const PG8_LAS bf16x8*)(lds + PG8_SA(b, h) + aoff + m * 2048 + k * 1024); } while (0)
; #define PG8_LDB(dst, b, h) do { _Pragma("unroll") for (int n = 0; n < 2; ++n) _Pragma("unroll") for (int k = 0; k < 2; ++k) dst[n][k] = *(const PG8_LAS bf16x8*)(lds + PG8_SB(b, h) + boff + n * 2048 + k * 1024); } while (0)
; #define PG8_MMA(ai, bj, At, Bt) do { __builtin_amdgcn_s_setprio(1); _Pragma("unroll") for (int m = 0; m < 4; ++m) _Pragma("unroll") for (int n = 0; n < 2; ++n) _Pragma("unroll") for (int k = 0; k < 2; ++k) \
;         acc[ai][bj][m][n] = __builtin_amdgcn_mfma_f32_16x16x32_bf16(Bt[n][k], At[m][k], acc[ai][bj][m][n], 0, 0, 0); __builtin_amdgcn_s_setprio(0); } while (0)
; #define PG8_WAIT_V(n) asm volatile("s_waitcnt vmcnt(" #n ")" ::: "memory")
; #define PG8_WAIT_L(n) asm volatile("s_waitcnt lgkmcnt(" #n ")" ::: "memory")
; #define PG8_BAR __builtin_amdgcn_s_barrier()
; #define PG8_SCHED __builtin_amdgcn_sched_barrier(0)
; template <class Epi, class Sched, bool ALIGN_EPI = false, bool SP2 = false>
; __device__ __forceinline__ void gemm_phase(PG8_LAS unsigned char* lds, const Gemm g, const Sched& S, const Epi& E) {
;     ...
;             PG8_WAIT_V(8); PG8_WAIT_L(0); PG8_BAR; PG8_MMA(1, 0, At, B0); PG8_MMA(1, 1, At, B1); PG8_BAR; PG8_SCHED;
;             PG8_LDB(B0, 1, 0); PG8_LDB(B1, 1, 1); PG8_SCHED; PG8_LDA(At, 1, 0); PG8_STAGE(PG8_SA(0, 1), a2 + hstep, voffA);
;             PG8_WAIT_V(8); PG8_WAIT_L(0); PG8_BAR; PG8_MMA(0, 0, At, B0); PG8_MMA(0, 1, At, B1); PG8_BAR; PG8_SCHED;
	s_setprio 1
	v_mfma_f32_16x16x32_bf16 v[56:59], v[128:131], v[186:189], v[56:59]
	v_mfma_f32_16x16x32_bf16 v[60:63], v[136:139], v[186:189], v[60:63]
	v_mfma_f32_16x16x32_bf16 v[40:43], v[128:131], v[198:201], v[40:43]
	v_mfma_f32_16x16x32_bf16 v[44:47], v[136:139], v[198:201], v[44:47]
	v_mfma_f32_16x16x32_bf16 v[24:27], v[128:131], v[206:209], v[24:27]
	v_mfma_f32_16x16x32_bf16 v[28:31], v[136:139], v[206:209], v[28:31]
	v_mfma_f32_16x16x32_bf16 v[8:11], v[128:131], v[214:217], v[8:11]
	v_mfma_f32_16x16x32_bf16 v[12:15], v[136:139], v[214:217], v[12:15]
	v_mfma_f32_16x16x32_bf16 v[56:59], v[132:135], v[190:193], v[56:59]
	v_mfma_f32_16x16x32_bf16 v[60:63], v[140:143], v[190:193], v[60:63]
	v_mfma_f32_16x16x32_bf16 v[40:43], v[132:135], v[202:205], v[40:43]
	v_mfma_f32_16x16x32_bf16 v[44:47], v[140:143], v[202:205], v[44:47]
	v_mfma_f32_16x16x32_bf16 v[24:27], v[132:135], v[210:213], v[24:27]
	v_mfma_f32_16x16x32_bf16 v[28:31], v[140:143], v[210:213], v[28:31]
	v_mfma_f32_16x16x32_bf16 v[8:11], v[132:135], v[218:221], v[8:11]
	v_mfma_f32_16x16x32_bf16 v[12:15], v[140:143], v[218:221], v[12:15]
	s_setprio 0
	s_setprio 1
	v_mfma_f32_16x16x32_bf16 v[52:55], v[144:147], v[186:189], v[52:55]
	v_mfma_f32_16x16x32_bf16 v[48:51], v[168:171], v[186:189], v[48:51]
	v_mfma_f32_16x16x32_bf16 v[36:39], v[144:147], v[198:201], v[36:39]
	v_mfma_f32_16x16x32_bf16 v[32:35], v[168:171], v[198:201], v[32:35]
	v_mfma_f32_16x16x32_bf16 v[20:23], v[144:147], v[206:209], v[20:23]
	v_mfma_f32_16x16x32_bf16 v[16:19], v[168:171], v[206:209], v[16:19]
	v_mfma_f32_16x16x32_bf16 v[4:7], v[144:147], v[214:217], v[4:7]
	v_mfma_f32_16x16x32_bf16 v[0:3], v[168:171], v[214:217], v[0:3]
	v_mfma_f32_16x16x32_bf16 v[52:55], v[148:151], v[190:193], v[52:55]
	v_mfma_f32_16x16x32_bf16 v[48:51], v[172:175], v[190:193], v[48:51]
	v_mfma_f32_16x16x32_bf16 v[36:39], v[148:151], v[202:205], v[36:39]
	v_mfma_f32_16x16x32_bf16 v[32:35], v[172:175], v[202:205], v[32:35]
	v_mfma_f32_16x16x32_bf16 v[20:23], v[148:151], v[210:213], v[20:23]
	v_mfma_f32_16x16x32_bf16 v[16:19], v[172:175], v[210:213], v[16:19]
	v_mfma_f32_16x16x32_bf16 v[4:7], v[148:151], v[218:221], v[4:7]
	v_mfma_f32_16x16x32_bf16 v[0:3], v[172:175], v[218:221], v[0:3]
	s_barrier
	s_setprio 0
	s_add_i32 s51, 0, 0x18000
	s_add_i32 s52, 0, 0x1c000
	v_add_u32_e32 v140, s51, v179
	v_add_u32_e32 v172, s52, v179
	ds_read_b128 v[128:131], v140
	ds_read_b128 v[132:135], v140 offset:1024
	ds_read_b128 v[136:139], v140 offset:2048
	ds_read_b128 v[140:143], v140 offset:3072
	ds_read_b128 v[144:147], v172
	ds_read_b128 v[148:151], v172 offset:1024
	ds_read_b128 v[168:171], v172 offset:2048
	ds_read_b128 v[172:175], v172 offset:3072
	s_add_u32 s30, s30, 0x80000
	s_addc_u32 s31, s31, 0
	s_mov_b32 m0, s39
	v_lshl_add_u64 v[226:227], s[30:31], 0, v[152:153]
	ds_read_b128 v[186:189], v183 offset:32768
	ds_read_b128 v[190:193], v183 offset:33792
	ds_read_b128 v[198:201], v183 offset:34816
	ds_read_b128 v[202:205], v183 offset:35840
	ds_read_b128 v[206:209], v183 offset:36864
	ds_read_b128 v[210:213], v183 offset:37888
	ds_read_b128 v[214:217], v183 offset:38912
	ds_read_b128 v[218:221], v183 offset:39936
	global_load_lds_dwordx4 v[226:227], off
	v_lshl_add_u64 v[226:227], s[30:31], 0, v[156:157]
	s_mov_b32 m0, s42
	s_nop 0
	global_load_lds_dwordx4 v[226:227], off
	s_waitcnt vmcnt(8)
	s_waitcnt lgkmcnt(0)
	s_barrier
	s_setprio 1
	v_mfma_f32_16x16x32_bf16 v[124:127], v[128:131], v[186:189], v[124:127]
	v_mfma_f32_16x16x32_bf16 v[120:123], v[136:139], v[186:189], v[120:123]
	v_mfma_f32_16x16x32_bf16 v[104:107], v[128:131], v[198:201], v[104:107]
	v_mfma_f32_16x16x32_bf16 v[108:111], v[136:139], v[198:201], v[108:111]
	v_mfma_f32_16x16x32_bf16 v[88:91], v[128:131], v[206:209], v[88:91]
	v_mfma_f32_16x16x32_bf16 v[92:95], v[136:139], v[206:209], v[92:95]
	v_mfma_f32_16x16x32_bf16 v[72:75], v[128:131], v[214:217], v[72:75]
	v_mfma_f32_16x16x32_bf16 v[76:79], v[136:139], v[214:217], v[76:79]
	v_mfma_f32_16x16x32_bf16 v[124:127], v[132:135], v[190:193], v[124:127]
	v_mfma_f32_16x16x32_bf16 v[120:123], v[140:143], v[190:193], v[120:123]
	v_mfma_f32_16x16x32_bf16 v[104:107], v[132:135], v[202:205], v[104:107]
	v_mfma_f32_16x16x32_bf16 v[108:111], v[140:143], v[202:205], v[108:111]
	v_mfma_f32_16x16x32_bf16 v[88:91], v[132:135], v[210:213], v[88:91]
	v_mfma_f32_16x16x32_bf16 v[92:95], v[140:143], v[210:213], v[92:95]
	v_mfma_f32_16x16x32_bf16 v[72:75], v[132:135], v[218:221], v[72:75]
	v_mfma_f32_16x16x32_bf16 v[76:79], v[140:143], v[218:221], v[76:79]
	s_setprio 0
	s_setprio 1
	v_mfma_f32_16x16x32_bf16 v[116:119], v[144:147], v[186:189], v[116:119]
	v_mfma_f32_16x16x32_bf16 v[112:115], v[168:171], v[186:189], v[112:115]
	v_mfma_f32_16x16x32_bf16 v[100:103], v[144:147], v[198:201], v[100:103]
	v_mfma_f32_16x16x32_bf16 v[96:99], v[168:171], v[198:201], v[96:99]
	v_mfma_f32_16x16x32_bf16 v[84:87], v[144:147], v[206:209], v[84:87]
	v_mfma_f32_16x16x32_bf16 v[80:83], v[168:171], v[206:209], v[80:83]
	v_mfma_f32_16x16x32_bf16 v[68:71], v[144:147], v[214:217], v[68:71]
	v_mfma_f32_16x16x32_bf16 v[64:67], v[168:171], v[214:217], v[64:67]
	v_mfma_f32_16x16x32_bf16 v[116:119], v[148:151], v[190:193], v[116:119]
	v_mfma_f32_16x16x32_bf16 v[112:115], v[172:175], v[190:193], v[112:115]
	v_mfma_f32_16x16x32_bf16 v[100:103], v[148:151], v[202:205], v[100:103]
	v_mfma_f32_16x16x32_bf16 v[96:99], v[172:175], v[202:205], v[96:99]
	v_mfma_f32_16x16x32_bf16 v[84:87], v[148:151], v[210:213], v[84:87]
	v_mfma_f32_16x16x32_bf16 v[80:83], v[172:175], v[210:213], v[80:83]
	v_mfma_f32_16x16x32_bf16 v[68:71], v[148:151], v[218:221], v[68:71]
	v_mfma_f32_16x16x32_bf16 v[64:67], v[172:175], v[218:221], v[64:67]
	s_barrier
; #define PG8_STAGE(bufoff, gbase, voff) do { _Pragma("unroll") for (int _i = 0; _i < 2; ++_i) \
;         __builtin_amdgcn_global_load_lds((const unsigned*)((const char*)(gbase) + (voff)[_i]), (PG8_LAS unsigned*)(lds + (bufoff) + ldsw + _i * 8192), 16, 0, 0); } while (0)
; #define PG8_LDA(dst, b, h) do { _Pragma("unroll") for (int m = 0; m < 4; ++m) _Pragma("unroll") for (int k = 0; k < 2; ++k) dst[m][k] = *(const PG8_LAS bf16x8*)(lds + PG8_SA(b, h) + aoff + m * 2048 + k * 1024); } while (0)
; #define PG8_MMA(ai, bj, At, Bt) do { __builtin_amdgcn_s_setprio(1); _Pragma("unroll") for (int m = 0; m < 4; ++m) _Pragma("unroll") for (int n = 0; n < 2; ++n) _Pragma("unroll") for (int k = 0; k < 2; ++k) \
;         acc[ai][bj][m][n] = __builtin_amdgcn_mfma_f32_16x16x32_bf16(Bt[n][k], At[m][k], acc[ai][bj][m][n], 0, 0, 0); __builtin_amdgcn_s_setprio(0); } while (0)
; #define PG8_WAIT_V(n) asm volatile("s_waitcnt vmcnt(" #n ")" ::: "memory")
; #define PG8_WAIT_L(n) asm volatile("s_waitcnt lgkmcnt(" #n ")" ::: "memory")
; #define PG8_BAR __builtin_amdgcn_s_barrier()
; #define PG8_SCHED __builtin_amdgcn_sched_barrier(0)
; template <class Epi, class Sched, bool ALIGN_EPI = false, bool SP2 = false>
; __device__ __forceinline__ void gemm_phase(PG8_LAS unsigned char* lds, const Gemm g, const Sched& S, const Epi& E) {
;     ...
;             PG8_WAIT_V(8); PG8_WAIT_L(0); PG8_BAR; PG8_MMA(0, 0, At, B0); PG8_MMA(0, 1, At, B1); PG8_BAR; PG8_SCHED;
;             PG8_LDA(At, 1, 1); PG8_STAGE(PG8_SB(1, 0), b3, voffB); PG8_STAGE(PG8_SB(1, 1), b3 + hstep, voffB); PG8_STAGE(PG8_SA(1, 0), a3, voffA);
;             PG8_WAIT_V(8); PG8_WAIT_L(0); PG8_BAR; PG8_MMA(1, 0, At, B0); PG8_MMA(1, 1, At, B1); PG8_BAR; PG8_SCHED;
	s_setprio 0
	s_add_i32 s30, s51, s34
	v_lshl_add_u64 v[176:177], v[176:177], 0, s[12:13]
	s_mov_b32 m0, s30
	ds_read_b128 v[186:189], v183 offset:49152
	ds_read_b128 v[190:193], v183 offset:50176
	ds_read_b128 v[198:201], v183 offset:51200
	ds_read_b128 v[202:205], v183 offset:52224
	ds_read_b128 v[206:209], v183 offset:53248
	ds_read_b128 v[210:213], v183 offset:54272
	ds_read_b128 v[214:217], v183 offset:55296
	ds_read_b128 v[218:221], v183 offset:56320
	global_load_lds_dwordx4 v[176:177], off
	s_add_i32 m0, s30, 0x2000
	s_add_u32 s28, s28, 0x80080
	v_lshl_add_u64 v[176:177], v[194:195], 0, s[12:13]
	s_addc_u32 s29, s29, 0
	s_add_i32 s30, s52, s34
	global_load_lds_dwordx4 v[176:177], off
	v_lshl_add_u64 v[176:177], s[28:29], 0, v[154:155]
	s_mov_b32 m0, s30
	s_nop 0
	global_load_lds_dwordx4 v[176:177], off
	v_lshl_add_u64 v[176:177], s[28:29], 0, v[158:159]
	s_add_i32 m0, s30, 0x2000
	s_nop 0
	global_load_lds_dwordx4 v[176:177], off
	v_lshl_add_u64 v[176:177], v[222:223], 0, s[12:13]
	s_mov_b32 m0, s44
	s_nop 0
	global_load_lds_dwordx4 v[176:177], off
	v_lshl_add_u64 v[176:177], v[224:225], 0, s[12:13]
	s_mov_b32 m0, s45
	s_nop 0
	global_load_lds_dwordx4 v[176:177], off
	s_waitcnt vmcnt(8)
	s_waitcnt lgkmcnt(0)
	s_barrier
	s_setprio 1
	v_mfma_f32_16x16x32_bf16 v[56:59], v[128:131], v[186:189], v[56:59]
	v_mfma_f32_16x16x32_bf16 v[60:63], v[136:139], v[186:189], v[60:63]
	v_mfma_f32_16x16x32_bf16 v[40:43], v[128:131], v[198:201], v[40:43]
	v_mfma_f32_16x16x32_bf16 v[44:47], v[136:139], v[198:201], v[44:47]
	v_mfma_f32_16x16x32_bf16 v[24:27], v[128:131], v[206:209], v[24:27]
	v_mfma_f32_16x16x32_bf16 v[28:31], v[136:139], v[206:209], v[28:31]
	v_mfma_f32_16x16x32_bf16 v[8:11], v[128:131], v[214:217], v[8:11]
	v_mfma_f32_16x16x32_bf16 v[12:15], v[136:139], v[214:217], v[12:15]
	v_mfma_f32_16x16x32_bf16 v[56:59], v[132:135], v[190:193], v[56:59]
	v_mfma_f32_16x16x32_bf16 v[60:63], v[140:143], v[190:193], v[60:63]
	v_mfma_f32_16x16x32_bf16 v[40:43], v[132:135], v[202:205], v[40:43]
	v_mfma_f32_16x16x32_bf16 v[44:47], v[140:143], v[202:205], v[44:47]
	v_mfma_f32_16x16x32_bf16 v[24:27], v[132:135], v[210:213], v[24:27]
	v_mfma_f32_16x16x32_bf16 v[28:31], v[140:143], v[210:213], v[28:31]
	v_mfma_f32_16x16x32_bf16 v[8:11], v[132:135], v[218:221], v[8:11]
	v_mfma_f32_16x16x32_bf16 v[12:15], v[140:143], v[218:221], v[12:15]
	s_setprio 0
	s_setprio 1
	v_mfma_f32_16x16x32_bf16 v[52:55], v[144:147], v[186:189], v[52:55]
	v_mfma_f32_16x16x32_bf16 v[48:51], v[168:171], v[186:189], v[48:51]
	v_mfma_f32_16x16x32_bf16 v[36:39], v[144:147], v[198:201], v[36:39]
	v_mfma_f32_16x16x32_bf16 v[32:35], v[168:171], v[198:201], v[32:35]
	v_mfma_f32_16x16x32_bf16 v[20:23], v[144:147], v[206:209], v[20:23]
	v_mfma_f32_16x16x32_bf16 v[16:19], v[168:171], v[206:209], v[16:19]
	v_mfma_f32_16x16x32_bf16 v[4:7], v[144:147], v[214:217], v[4:7]
	v_mfma_f32_16x16x32_bf16 v[0:3], v[168:171], v[214:217], v[0:3]
	v_mfma_f32_16x16x32_bf16 v[52:55], v[148:151], v[190:193], v[52:55]
	v_mfma_f32_16x16x32_bf16 v[48:51], v[172:175], v[190:193], v[48:51]
	v_mfma_f32_16x16x32_bf16 v[36:39], v[148:151], v[202:205], v[36:39]
	v_mfma_f32_16x16x32_bf16 v[32:35], v[172:175], v[202:205], v[32:35]
	v_mfma_f32_16x16x32_bf16 v[20:23], v[148:151], v[210:213], v[20:23]
	v_mfma_f32_16x16x32_bf16 v[16:19], v[172:175], v[210:213], v[16:19]
	v_mfma_f32_16x16x32_bf16 v[4:7], v[148:151], v[218:221], v[4:7]
	v_mfma_f32_16x16x32_bf16 v[0:3], v[172:175], v[218:221], v[0:3]
	s_barrier
	s_setprio 0
	s_add_i32 s50, s50, 2
	s_add_u32 s26, s26, 0x100
	s_addc_u32 s27, s27, 0
	s_add_u32 s48, s48, 0x100
	s_addc_u32 s49, s49, 0
	s_cmp_gt_u32 s50, 29
	s_cbranch_scc0 .LBB0_307
	s_and_b64 vcc, exec, s[14:15]
	s_cbranch_vccz .LBB0_310
	s_barrier

; #define PG8_STAGE(bufoff, gbase, voff) do { _Pragma("unroll") for (int _i = 0; _i < 2; ++_i) \
;         __builtin_amdgcn_global_load_lds((const unsigned*)((const char*)(gbase) + (voff)[_i]), (PG8_LAS unsigned*)(lds + (bufoff) + ldsw + _i * 8192), 16, 0, 0); } while (0)
; #define PG8_LDA(dst, b, h) do { _Pragma("unroll") for (int m = 0; m < 4; ++m) _Pragma("unroll") for (int k = 0; k < 2; ++k) dst[m][k] = *(const PG8_LAS bf16x8*)(lds + PG8_SA(b, h) + aoff + m * 2048 + k * 1024); } while (0)
; #define PG8_LDB(dst, b, h) do { _Pragma("unroll") for (int n = 0; n < 2; ++n) _Pragma("unroll") for (int k = 0; k < 2; ++k) dst[n][k] = *(const PG8_LAS bf16x8*)(lds + PG8_SB(b, h) + boff + n * 2048 + k * 1024); } while (0)
; #define PG8_MMA(ai, bj, At, Bt) do { __builtin_amdgcn_s_setprio(1); _Pragma("unroll") for (int m = 0; m < 4; ++m) _Pragma("unroll") for (int n = 0; n < 2; ++n) _Pragma("unroll") for (int k = 0; k < 2; ++k) \
;         acc[ai][bj][m][n] = __builtin_amdgcn_mfma_f32_16x16x32_bf16(Bt[n][k], At[m][k], acc[ai][bj][m][n], 0, 0, 0); __builtin_amdgcn_s_setprio(0); } while (0)
; #define PG8_WAIT_V(n) asm volatile("s_waitcnt vmcnt(" #n ")" ::: "memory")
; #define PG8_WAIT_L(n) asm volatile("s_waitcnt lgkmcnt(" #n ")" ::: "memory")
; #define PG8_BAR __builtin_amdgcn_s_barrier()
; #define PG8_SCHED __builtin_amdgcn_sched_barrier(0)
; template <class Epi, class Sched, bool ALIGN_EPI = false, bool SP2 = false>
; __device__ __forceinline__ void gemm_phase(PG8_LAS unsigned char* lds, const Gemm g, const Sched& S, const Epi& E) {
;     ...
;             PG8_LDB(B0, 0, 0); PG8_LDB(B1, 0, 1); PG8_SCHED; PG8_LDA(At, 0, 0); PG8_STAGE(PG8_SA(1, 1), a1 + hstep, voffA);
;             PG8_WAIT_V(8); PG8_WAIT_L(0); PG8_BAR; PG8_MMA(0, 0, At, B0); PG8_MMA(0, 1, At, B1); PG8_BAR; PG8_SCHED;
;             PG8_LDA(At, 0, 1); PG8_STAGE(PG8_SB(0, 0), b2, voffB); PG8_STAGE(PG8_SB(0, 1), b2 + hstep, voffB); PG8_STAGE(PG8_SA(0, 0), a2, voffA);
;             PG8_WAIT_V(8); PG8_WAIT_L(0); PG8_BAR; PG8_MMA(1, 0, At, B0); PG8_MMA(1, 1, At, B1); PG8_BAR; PG8_SCHED;
.LBB0_491:
	v_add_u32_e32 v140, s68, v163
	v_add_u32_e32 v152, s69, v163
	ds_read_b128 v[128:131], v140
	ds_read_b128 v[132:135], v140 offset:1024
	ds_read_b128 v[136:139], v140 offset:2048
	ds_read_b128 v[140:143], v140 offset:3072
	ds_read_b128 v[184:187], v152
	ds_read_b128 v[218:221], v152 offset:1024
	ds_read_b128 v[222:225], v152 offset:2048
	ds_read_b128 v[226:229], v152 offset:3072
	s_add_u32 s28, s0, 0xfff80080
	s_addc_u32 s29, s1, -1
	s_cmp_eq_u32 s48, 28
	s_cselect_b32 s31, s5, s29
	s_cselect_b32 s30, s21, s28
	s_cselect_b32 s29, s19, s45
	s_cselect_b32 s28, s33, s44
	v_lshl_add_u64 v[172:173], s[0:1], 0, v[156:157]
	s_add_i32 m0, s17, 0xc000
	ds_read_b128 v[230:233], v214
	ds_read_b128 v[234:237], v214 offset:1024
	ds_read_b128 v[238:241], v214 offset:2048
	ds_read_b128 v[242:245], v214 offset:3072
	ds_read_b128 v[246:249], v214 offset:4096
	ds_read_b128 v[250:253], v214 offset:5120
	ds_read_b128 v[206:209], v214 offset:6144
	ds_read_b128 v[210:213], v214 offset:7168
	global_load_lds_dwordx4 v[172:173], off
	v_lshl_add_u64 v[172:173], s[0:1], 0, v[158:159]
	s_add_i32 m0, s17, 0xe000
	s_nop 0
	global_load_lds_dwordx4 v[172:173], off
	s_waitcnt vmcnt(8)
	s_waitcnt lgkmcnt(0)
	s_barrier
	s_setprio 1
	v_mfma_f32_16x16x32_bf16 v[124:127], v[128:131], v[230:233], v[124:127]
	v_mfma_f32_16x16x32_bf16 v[120:123], v[136:139], v[230:233], v[120:123]
	v_mfma_f32_16x16x32_bf16 v[116:119], v[128:131], v[238:241], v[116:119]
	v_mfma_f32_16x16x32_bf16 v[108:111], v[136:139], v[238:241], v[108:111]
	v_mfma_f32_16x16x32_bf16 v[100:103], v[128:131], v[246:249], v[100:103]
	v_mfma_f32_16x16x32_bf16 v[92:95], v[136:139], v[246:249], v[92:95]
	v_mfma_f32_16x16x32_bf16 v[84:87], v[128:131], v[206:209], v[84:87]
	v_mfma_f32_16x16x32_bf16 v[76:79], v[136:139], v[206:209], v[76:79]
	v_mfma_f32_16x16x32_bf16 v[124:127], v[132:135], v[234:237], v[124:127]
	v_mfma_f32_16x16x32_bf16 v[120:123], v[140:143], v[234:237], v[120:123]
	v_mfma_f32_16x16x32_bf16 v[116:119], v[132:135], v[242:245], v[116:119]
	v_mfma_f32_16x16x32_bf16 v[108:111], v[140:143], v[242:245], v[108:111]
	v_mfma_f32_16x16x32_bf16 v[100:103], v[132:135], v[250:253], v[100:103]
	v_mfma_f32_16x16x32_bf16 v[92:95], v[140:143], v[250:253], v[92:95]
	v_mfma_f32_16x16x32_bf16 v[84:87], v[132:135], v[210:213], v[84:87]
	v_mfma_f32_16x16x32_bf16 v[76:79], v[140:143], v[210:213], v[76:79]
	s_setprio 0
	s_setprio 1
	v_mfma_f32_16x16x32_bf16 v[112:115], v[184:187], v[230:233], v[112:115]
	v_mfma_f32_16x16x32_bf16 v[104:107], v[222:225], v[230:233], v[104:107]
	v_mfma_f32_16x16x32_bf16 v[96:99], v[184:187], v[238:241], v[96:99]
	v_mfma_f32_16x16x32_bf16 v[88:91], v[222:225], v[238:241], v[88:91]
	v_mfma_f32_16x16x32_bf16 v[80:83], v[184:187], v[246:249], v[80:83]
	v_mfma_f32_16x16x32_bf16 v[72:75], v[222:225], v[246:249], v[72:75]
	v_mfma_f32_16x16x32_bf16 v[68:71], v[184:187], v[206:209], v[68:71]
	v_mfma_f32_16x16x32_bf16 v[64:67], v[222:225], v[206:209], v[64:67]
	v_mfma_f32_16x16x32_bf16 v[112:115], v[218:221], v[234:237], v[112:115]
	v_mfma_f32_16x16x32_bf16 v[104:107], v[226:229], v[234:237], v[104:107]
	v_mfma_f32_16x16x32_bf16 v[96:99], v[218:221], v[242:245], v[96:99]
	v_mfma_f32_16x16x32_bf16 v[88:91], v[226:229], v[242:245], v[88:91]
	v_mfma_f32_16x16x32_bf16 v[80:83], v[218:221], v[250:253], v[80:83]
	v_mfma_f32_16x16x32_bf16 v[72:75], v[226:229], v[250:253], v[72:75]
	v_mfma_f32_16x16x32_bf16 v[68:71], v[218:221], v[210:213], v[68:71]
	v_mfma_f32_16x16x32_bf16 v[64:67], v[226:229], v[210:213], v[64:67]
	s_barrier
	s_setprio 0
	s_add_i32 s49, s68, s34
	v_lshl_add_u64 v[172:173], s[28:29], 0, v[146:147]
	s_mov_b32 m0, s49
	ds_read_b128 v[206:209], v214 offset:16384
	ds_read_b128 v[210:213], v214 offset:17408
	ds_read_b128 v[230:233], v214 offset:18432
	ds_read_b128 v[234:237], v214 offset:19456
	ds_read_b128 v[238:241], v214 offset:20480
	ds_read_b128 v[242:245], v214 offset:21504
	ds_read_b128 v[246:249], v214 offset:22528
	ds_read_b128 v[250:253], v214 offset:23552
	global_load_lds_dwordx4 v[172:173], off
	s_add_i32 m0, s49, 0x2000
	s_add_u32 s50, s28, 0x80000
	v_lshl_add_u64 v[176:177], s[28:29], 0, v[150:151]
	s_addc_u32 s51, s29, 0
	s_add_i32 s49, s69, s34
	global_load_lds_dwordx4 v[176:177], off
	v_lshl_add_u64 v[180:181], s[50:51], 0, v[146:147]
	s_mov_b32 m0, s49
	v_lshl_add_u64 v[188:189], s[30:31], 0, v[148:149]
	global_load_lds_dwordx4 v[180:181], off
	v_lshl_add_u64 v[180:181], s[50:51], 0, v[150:151]
	s_add_i32 m0, s49, 0x2000
	s_nop 0
	global_load_lds_dwordx4 v[180:181], off
	v_lshl_add_u64 v[180:181], s[30:31], 0, v[144:145]
	s_mov_b32 m0, s17
	s_nop 0
	global_load_lds_dwordx4 v[180:181], off
	s_mov_b32 m0, s35
	s_nop 0
	global_load_lds_dwordx4 v[188:189], off
	s_waitcnt vmcnt(8)
	s_waitcnt lgkmcnt(0)
	s_barrier
; #define PG8_STAGE(bufoff, gbase, voff) do { _Pragma("unroll") for (int _i = 0; _i < 2; ++_i) \
;         __builtin_amdgcn_global_load_lds((const unsigned*)((const char*)(gbase) + (voff)[_i]), (PG8_LAS unsigned*)(lds + (bufoff) + ldsw + _i * 8192), 16, 0, 0); } while (0)
; #define PG8_LDA(dst, b, h) do { _Pragma("unroll") for (int m = 0; m < 4; ++m) _Pragma("unroll") for (int k = 0; k < 2; ++k) dst[m][k] = *(const PG8_LAS bf16x8*)(lds + PG8_SA(b, h) + aoff + m * 2048 + k * 1024); } while (0)
; #define PG8_LDB(dst, b, h) do { _Pragma("unroll") for (int n = 0; n < 2; ++n) _Pragma("unroll") for (int k = 0; k < 2; ++k) dst[n][k] = *(const PG8_LAS bf16x8*)(lds + PG8_SB(b, h) + boff + n * 2048 + k * 1024); } while (0)
; #define PG8_MMA(ai, bj, At, Bt) do { __builtin_amdgcn_s_setprio(1); _Pragma("unroll") for (int m = 0; m < 4; ++m) _Pragma("unroll") for (int n = 0; n < 2; ++n) _Pragma("unroll") for (int k = 0; k < 2; ++k) \
;         acc[ai][bj][m][n] = __builtin_amdgcn_mfma_f32_16x16x32_bf16(Bt[n][k], At[m][k], acc[ai][bj][m][n], 0, 0, 0); __builtin_amdgcn_s_setprio(0); } while (0)
; #define PG8_WAIT_V(n) asm volatile("s_waitcnt vmcnt(" #n ")" ::: "memory")
; #define PG8_WAIT_L(n) asm volatile("s_waitcnt lgkmcnt(" #n ")" ::: "memory")
; #define PG8_BAR __builtin_amdgcn_s_barrier()
; #define PG8_SCHED __builtin_amdgcn_sched_barrier(0)
; template <class Epi, class Sched, bool ALIGN_EPI = false, bool SP2 = false>
; __device__ __forceinline__ void gemm_phase(PG8_LAS unsigned char* lds, const Gemm g, const Sched& S, const Epi& E) {
;     ...
;             PG8_WAIT_V(8); PG8_WAIT_L(0); PG8_BAR; PG8_MMA(1, 0, At, B0); PG8_MMA(1, 1, At, B1); PG8_BAR; PG8_SCHED;
;             PG8_LDB(B0, 1, 0); PG8_LDB(B1, 1, 1); PG8_SCHED; PG8_LDA(At, 1, 0); PG8_STAGE(PG8_SA(0, 1), a2 + hstep, voffA);
;             PG8_WAIT_V(8); PG8_WAIT_L(0); PG8_BAR; PG8_MMA(0, 0, At, B0); PG8_MMA(0, 1, At, B1); PG8_BAR; PG8_SCHED;
	s_setprio 1
	v_mfma_f32_16x16x32_bf16 v[60:63], v[128:131], v[206:209], v[60:63]
	v_mfma_f32_16x16x32_bf16 v[56:59], v[136:139], v[206:209], v[56:59]
	v_mfma_f32_16x16x32_bf16 v[52:55], v[128:131], v[230:233], v[52:55]
	v_mfma_f32_16x16x32_bf16 v[44:47], v[136:139], v[230:233], v[44:47]
	v_mfma_f32_16x16x32_bf16 v[36:39], v[128:131], v[238:241], v[36:39]
	v_mfma_f32_16x16x32_bf16 v[28:31], v[136:139], v[238:241], v[28:31]
	v_mfma_f32_16x16x32_bf16 v[20:23], v[128:131], v[246:249], v[20:23]
	v_mfma_f32_16x16x32_bf16 v[12:15], v[136:139], v[246:249], v[12:15]
	v_mfma_f32_16x16x32_bf16 v[60:63], v[132:135], v[210:213], v[60:63]
	v_mfma_f32_16x16x32_bf16 v[56:59], v[140:143], v[210:213], v[56:59]
	v_mfma_f32_16x16x32_bf16 v[52:55], v[132:135], v[234:237], v[52:55]
	v_mfma_f32_16x16x32_bf16 v[44:47], v[140:143], v[234:237], v[44:47]
	v_mfma_f32_16x16x32_bf16 v[36:39], v[132:135], v[242:245], v[36:39]
	v_mfma_f32_16x16x32_bf16 v[28:31], v[140:143], v[242:245], v[28:31]
	v_mfma_f32_16x16x32_bf16 v[20:23], v[132:135], v[250:253], v[20:23]
	v_mfma_f32_16x16x32_bf16 v[12:15], v[140:143], v[250:253], v[12:15]
	s_setprio 0
	s_setprio 1
	v_mfma_f32_16x16x32_bf16 v[48:51], v[184:187], v[206:209], v[48:51]
	v_mfma_f32_16x16x32_bf16 v[40:43], v[222:225], v[206:209], v[40:43]
	v_mfma_f32_16x16x32_bf16 v[32:35], v[184:187], v[230:233], v[32:35]
	v_mfma_f32_16x16x32_bf16 v[24:27], v[222:225], v[230:233], v[24:27]
	v_mfma_f32_16x16x32_bf16 v[16:19], v[184:187], v[238:241], v[16:19]
	v_mfma_f32_16x16x32_bf16 v[8:11], v[222:225], v[238:241], v[8:11]
	v_mfma_f32_16x16x32_bf16 v[4:7], v[184:187], v[246:249], v[4:7]
	v_mfma_f32_16x16x32_bf16 v[0:3], v[222:225], v[246:249], v[0:3]
	v_mfma_f32_16x16x32_bf16 v[48:51], v[218:221], v[210:213], v[48:51]
	v_mfma_f32_16x16x32_bf16 v[40:43], v[226:229], v[210:213], v[40:43]
	v_mfma_f32_16x16x32_bf16 v[32:35], v[218:221], v[234:237], v[32:35]
	v_mfma_f32_16x16x32_bf16 v[24:27], v[226:229], v[234:237], v[24:27]
	v_mfma_f32_16x16x32_bf16 v[16:19], v[218:221], v[242:245], v[16:19]
	v_mfma_f32_16x16x32_bf16 v[8:11], v[226:229], v[242:245], v[8:11]
	v_mfma_f32_16x16x32_bf16 v[4:7], v[218:221], v[250:253], v[4:7]
	v_mfma_f32_16x16x32_bf16 v[0:3], v[226:229], v[250:253], v[0:3]
	s_barrier
	s_setprio 0
	s_add_i32 s49, 0, 0x18000
	s_add_i32 s50, 0, 0x1c000
	v_add_u32_e32 v140, s49, v163
	v_add_u32_e32 v152, s50, v163
	ds_read_b128 v[128:131], v140
	ds_read_b128 v[132:135], v140 offset:1024
	ds_read_b128 v[136:139], v140 offset:2048
	ds_read_b128 v[140:143], v140 offset:3072
	ds_read_b128 v[184:187], v152
	ds_read_b128 v[206:209], v152 offset:1024
	ds_read_b128 v[210:213], v152 offset:2048
	ds_read_b128 v[218:221], v152 offset:3072
	s_add_u32 s30, s30, 0x80000
	s_addc_u32 s31, s31, 0
	s_mov_b32 m0, s37
	v_lshl_add_u64 v[216:217], s[30:31], 0, v[144:145]
	ds_read_b128 v[222:225], v214 offset:32768
	ds_read_b128 v[226:229], v214 offset:33792
	ds_read_b128 v[230:233], v214 offset:34816
	ds_read_b128 v[234:237], v214 offset:35840
	ds_read_b128 v[238:241], v214 offset:36864
	ds_read_b128 v[242:245], v214 offset:37888
	ds_read_b128 v[246:249], v214 offset:38912
	ds_read_b128 v[250:253], v214 offset:39936
	global_load_lds_dwordx4 v[216:217], off
	v_lshl_add_u64 v[216:217], s[30:31], 0, v[148:149]
	s_mov_b32 m0, s39
	s_nop 0
	global_load_lds_dwordx4 v[216:217], off
	s_waitcnt vmcnt(8)
	s_waitcnt lgkmcnt(0)
	s_barrier
	s_setprio 1
	v_mfma_f32_16x16x32_bf16 v[124:127], v[128:131], v[222:225], v[124:127]
	v_mfma_f32_16x16x32_bf16 v[120:123], v[136:139], v[222:225], v[120:123]
	v_mfma_f32_16x16x32_bf16 v[116:119], v[128:131], v[230:233], v[116:119]
	v_mfma_f32_16x16x32_bf16 v[108:111], v[136:139], v[230:233], v[108:111]
	v_mfma_f32_16x16x32_bf16 v[100:103], v[128:131], v[238:241], v[100:103]
	v_mfma_f32_16x16x32_bf16 v[92:95], v[136:139], v[238:241], v[92:95]
	v_mfma_f32_16x16x32_bf16 v[84:87], v[128:131], v[246:249], v[84:87]
	v_mfma_f32_16x16x32_bf16 v[76:79], v[136:139], v[246:249], v[76:79]
	v_mfma_f32_16x16x32_bf16 v[124:127], v[132:135], v[226:229], v[124:127]
	v_mfma_f32_16x16x32_bf16 v[120:123], v[140:143], v[226:229], v[120:123]
	v_mfma_f32_16x16x32_bf16 v[116:119], v[132:135], v[234:237], v[116:119]
	v_mfma_f32_16x16x32_bf16 v[108:111], v[140:143], v[234:237], v[108:111]
	v_mfma_f32_16x16x32_bf16 v[100:103], v[132:135], v[242:245], v[100:103]
	v_mfma_f32_16x16x32_bf16 v[92:95], v[140:143], v[242:245], v[92:95]
	v_mfma_f32_16x16x32_bf16 v[84:87], v[132:135], v[250:253], v[84:87]
	v_mfma_f32_16x16x32_bf16 v[76:79], v[140:143], v[250:253], v[76:79]
	s_setprio 0
	s_setprio 1
	v_mfma_f32_16x16x32_bf16 v[112:115], v[184:187], v[222:225], v[112:115]
	v_mfma_f32_16x16x32_bf16 v[104:107], v[210:213], v[222:225], v[104:107]
	v_mfma_f32_16x16x32_bf16 v[96:99], v[184:187], v[230:233], v[96:99]
	v_mfma_f32_16x16x32_bf16 v[88:91], v[210:213], v[230:233], v[88:91]
	v_mfma_f32_16x16x32_bf16 v[80:83], v[184:187], v[238:241], v[80:83]
	v_mfma_f32_16x16x32_bf16 v[72:75], v[210:213], v[238:241], v[72:75]
	v_mfma_f32_16x16x32_bf16 v[68:71], v[184:187], v[246:249], v[68:71]
	v_mfma_f32_16x16x32_bf16 v[64:67], v[210:213], v[246:249], v[64:67]
	v_mfma_f32_16x16x32_bf16 v[112:115], v[206:209], v[226:229], v[112:115]
	v_mfma_f32_16x16x32_bf16 v[104:107], v[218:221], v[226:229], v[104:107]
	v_mfma_f32_16x16x32_bf16 v[96:99], v[206:209], v[234:237], v[96:99]
	v_mfma_f32_16x16x32_bf16 v[88:91], v[218:221], v[234:237], v[88:91]
	v_mfma_f32_16x16x32_bf16 v[80:83], v[206:209], v[242:245], v[80:83]
	v_mfma_f32_16x16x32_bf16 v[72:75], v[218:221], v[242:245], v[72:75]
	v_mfma_f32_16x16x32_bf16 v[68:71], v[206:209], v[250:253], v[68:71]
	v_mfma_f32_16x16x32_bf16 v[64:67], v[218:221], v[250:253], v[64:67]
	s_barrier
; #define PG8_STAGE(bufoff, gbase, voff) do { _Pragma("unroll") for (int _i = 0; _i < 2; ++_i) \
;         __builtin_amdgcn_global_load_lds((const unsigned*)((const char*)(gbase) + (voff)[_i]), (PG8_LAS unsigned*)(lds + (bufoff) + ldsw + _i * 8192), 16, 0, 0); } while (0)
; #define PG8_LDA(dst, b, h) do { _Pragma("unroll") for (int m = 0; m < 4; ++m) _Pragma("unroll") for (int k = 0; k < 2; ++k) dst[m][k] = *(const PG8_LAS bf16x8*)(lds + PG8_SA(b, h) + aoff + m * 2048 + k * 1024); } while (0)
; #define PG8_MMA(ai, bj, At, Bt) do { __builtin_amdgcn_s_setprio(1); _Pragma("unroll") for (int m = 0; m < 4; ++m) _Pragma("unroll") for (int n = 0; n < 2; ++n) _Pragma("unroll") for (int k = 0; k < 2; ++k) \
;         acc[ai][bj][m][n] = __builtin_amdgcn_mfma_f32_16x16x32_bf16(Bt[n][k], At[m][k], acc[ai][bj][m][n], 0, 0, 0); __builtin_amdgcn_s_setprio(0); } while (0)
; #define PG8_WAIT_V(n) asm volatile("s_waitcnt vmcnt(" #n ")" ::: "memory")
; #define PG8_WAIT_L(n) asm volatile("s_waitcnt lgkmcnt(" #n ")" ::: "memory")
; #define PG8_BAR __builtin_amdgcn_s_barrier()
; #define PG8_SCHED __builtin_amdgcn_sched_barrier(0)
; template <class Epi, class Sched, bool ALIGN_EPI = false, bool SP2 = false>
; __device__ __forceinline__ void gemm_phase(PG8_LAS unsigned char* lds, const Gemm g, const Sched& S, const Epi& E) {
;     ...
;             PG8_WAIT_V(8); PG8_WAIT_L(0); PG8_BAR; PG8_MMA(0, 0, At, B0); PG8_MMA(0, 1, At, B1); PG8_BAR; PG8_SCHED;
;             PG8_LDA(At, 1, 1); PG8_STAGE(PG8_SB(1, 0), b3, voffB); PG8_STAGE(PG8_SB(1, 1), b3 + hstep, voffB); PG8_STAGE(PG8_SA(1, 0), a3, voffA);
;             PG8_WAIT_V(8); PG8_WAIT_L(0); PG8_BAR; PG8_MMA(1, 0, At, B0); PG8_MMA(1, 1, At, B1); PG8_BAR; PG8_SCHED;
	s_setprio 0
	s_add_i32 s30, s49, s34
	v_lshl_add_u64 v[172:173], v[172:173], 0, s[10:11]
	s_mov_b32 m0, s30
	ds_read_b128 v[222:225], v214 offset:49152
	ds_read_b128 v[226:229], v214 offset:50176
	ds_read_b128 v[230:233], v214 offset:51200
	ds_read_b128 v[234:237], v214 offset:52224
	ds_read_b128 v[238:241], v214 offset:53248
	ds_read_b128 v[242:245], v214 offset:54272
	ds_read_b128 v[246:249], v214 offset:55296
	ds_read_b128 v[250:253], v214 offset:56320
	global_load_lds_dwordx4 v[172:173], off
	s_add_i32 m0, s30, 0x2000
	s_add_u32 s28, s28, 0x80080
	v_lshl_add_u64 v[172:173], v[176:177], 0, s[10:11]
	s_addc_u32 s29, s29, 0
	s_add_i32 s30, s50, s34
	global_load_lds_dwordx4 v[172:173], off
	v_lshl_add_u64 v[172:173], s[28:29], 0, v[146:147]
	s_mov_b32 m0, s30
	s_nop 0
	global_load_lds_dwordx4 v[172:173], off
	v_lshl_add_u64 v[172:173], s[28:29], 0, v[150:151]
	s_add_i32 m0, s30, 0x2000
	s_nop 0
	global_load_lds_dwordx4 v[172:173], off
	v_lshl_add_u64 v[172:173], v[180:181], 0, s[10:11]
	s_mov_b32 m0, s43
	s_nop 0
	global_load_lds_dwordx4 v[172:173], off
	v_lshl_add_u64 v[172:173], v[188:189], 0, s[10:11]
	s_mov_b32 m0, s46
	s_nop 0
	global_load_lds_dwordx4 v[172:173], off
	s_waitcnt vmcnt(8)
	s_waitcnt lgkmcnt(0)
	s_barrier
	s_setprio 1
	v_mfma_f32_16x16x32_bf16 v[60:63], v[128:131], v[222:225], v[60:63]
	v_mfma_f32_16x16x32_bf16 v[56:59], v[136:139], v[222:225], v[56:59]
	v_mfma_f32_16x16x32_bf16 v[52:55], v[128:131], v[230:233], v[52:55]
	v_mfma_f32_16x16x32_bf16 v[44:47], v[136:139], v[230:233], v[44:47]
	v_mfma_f32_16x16x32_bf16 v[36:39], v[128:131], v[238:241], v[36:39]
	v_mfma_f32_16x16x32_bf16 v[28:31], v[136:139], v[238:241], v[28:31]
	v_mfma_f32_16x16x32_bf16 v[20:23], v[128:131], v[246:249], v[20:23]
	v_mfma_f32_16x16x32_bf16 v[12:15], v[136:139], v[246:249], v[12:15]
	v_mfma_f32_16x16x32_bf16 v[60:63], v[132:135], v[226:229], v[60:63]
	v_mfma_f32_16x16x32_bf16 v[56:59], v[140:143], v[226:229], v[56:59]
	v_mfma_f32_16x16x32_bf16 v[52:55], v[132:135], v[234:237], v[52:55]
	v_mfma_f32_16x16x32_bf16 v[44:47], v[140:143], v[234:237], v[44:47]
	v_mfma_f32_16x16x32_bf16 v[36:39], v[132:135], v[242:245], v[36:39]
	v_mfma_f32_16x16x32_bf16 v[28:31], v[140:143], v[242:245], v[28:31]
	v_mfma_f32_16x16x32_bf16 v[20:23], v[132:135], v[250:253], v[20:23]
	v_mfma_f32_16x16x32_bf16 v[12:15], v[140:143], v[250:253], v[12:15]
	s_setprio 0
	s_setprio 1
	v_mfma_f32_16x16x32_bf16 v[48:51], v[184:187], v[222:225], v[48:51]
	v_mfma_f32_16x16x32_bf16 v[40:43], v[210:213], v[222:225], v[40:43]
	v_mfma_f32_16x16x32_bf16 v[32:35], v[184:187], v[230:233], v[32:35]
	v_mfma_f32_16x16x32_bf16 v[24:27], v[210:213], v[230:233], v[24:27]
	v_mfma_f32_16x16x32_bf16 v[16:19], v[184:187], v[238:241], v[16:19]
	v_mfma_f32_16x16x32_bf16 v[8:11], v[210:213], v[238:241], v[8:11]
	v_mfma_f32_16x16x32_bf16 v[4:7], v[184:187], v[246:249], v[4:7]
	v_mfma_f32_16x16x32_bf16 v[0:3], v[210:213], v[246:249], v[0:3]
	v_mfma_f32_16x16x32_bf16 v[48:51], v[206:209], v[226:229], v[48:51]
	v_mfma_f32_16x16x32_bf16 v[40:43], v[218:221], v[226:229], v[40:43]
	v_mfma_f32_16x16x32_bf16 v[32:35], v[206:209], v[234:237], v[32:35]
	v_mfma_f32_16x16x32_bf16 v[24:27], v[218:221], v[234:237], v[24:27]
	v_mfma_f32_16x16x32_bf16 v[16:19], v[206:209], v[242:245], v[16:19]
	v_mfma_f32_16x16x32_bf16 v[8:11], v[218:221], v[242:245], v[8:11]
	v_mfma_f32_16x16x32_bf16 v[4:7], v[206:209], v[250:253], v[4:7]
	v_mfma_f32_16x16x32_bf16 v[0:3], v[218:221], v[250:253], v[0:3]
	s_barrier
	s_setprio 0
	s_add_i32 s48, s48, 2
	s_add_u32 s0, s0, 0x100
	s_addc_u32 s1, s1, 0
	s_add_u32 s44, s44, 0x100
	s_addc_u32 s45, s45, 0
	s_cmp_gt_u32 s48, 29
	s_cbranch_scc0 .LBB0_491
	s_and_b64 vcc, exec, s[12:13]
	s_cbranch_vccz .LBB0_494
	s_barrier

; #define PG8_STAGE(bufoff, gbase, voff) do { _Pragma("unroll") for (int _i = 0; _i < 2; ++_i) \
;         __builtin_amdgcn_global_load_lds((const unsigned*)((const char*)(gbase) + (voff)[_i]), (PG8_LAS unsigned*)(lds + (bufoff) + ldsw + _i * 8192), 16, 0, 0); } while (0)
; #define PG8_LDA(dst, b, h) do { _Pragma("unroll") for (int m = 0; m < 4; ++m) _Pragma("unroll") for (int k = 0; k < 2; ++k) dst[m][k] = *(const PG8_LAS bf16x8*)(lds + PG8_SA(b, h) + aoff + m * 2048 + k * 1024); } while (0)
; #define PG8_LDB(dst, b, h) do { _Pragma("unroll") for (int n = 0; n < 2; ++n) _Pragma("unroll") for (int k = 0; k < 2; ++k) dst[n][k] = *(const PG8_LAS bf16x8*)(lds + PG8_SB(b, h) + boff + n * 2048 + k * 1024); } while (0)
; #define PG8_MMA(ai, bj, At, Bt) do { __builtin_amdgcn_s_setprio(1); _Pragma("unroll") for (int m = 0; m < 4; ++m) _Pragma("unroll") for (int n = 0; n < 2; ++n) _Pragma("unroll") for (int k = 0; k < 2; ++k) \
;         acc[ai][bj][m][n] = __builtin_amdgcn_mfma_f32_16x16x32_bf16(Bt[n][k], At[m][k], acc[ai][bj][m][n], 0, 0, 0); __builtin_amdgcn_s_setprio(0); } while (0)
; #define PG8_WAIT_V(n) asm volatile("s_waitcnt vmcnt(" #n ")" ::: "memory")
; #define PG8_WAIT_L(n) asm volatile("s_waitcnt lgkmcnt(" #n ")" ::: "memory")
; #define PG8_BAR __builtin_amdgcn_s_barrier()
; #define PG8_SCHED __builtin_amdgcn_sched_barrier(0)
; template <class Epi, class Sched, bool ALIGN_EPI = false, bool SP2 = false>
; __device__ __forceinline__ void gemm_phase(PG8_LAS unsigned char* lds, const Gemm g, const Sched& S, const Epi& E) {
;     ...
;             PG8_LDB(B0, 0, 0); PG8_LDB(B1, 0, 1); PG8_SCHED; PG8_LDA(At, 0, 0); PG8_STAGE(PG8_SA(1, 1), a1 + hstep, voffA);
;             PG8_WAIT_V(8); PG8_WAIT_L(0); PG8_BAR; PG8_MMA(0, 0, At, B0); PG8_MMA(0, 1, At, B1); PG8_BAR; PG8_SCHED;
;             PG8_LDA(At, 0, 1); PG8_STAGE(PG8_SB(0, 0), b2, voffB); PG8_STAGE(PG8_SB(0, 1), b2 + hstep, voffB); PG8_STAGE(PG8_SA(0, 0), a2, voffA);
;             PG8_WAIT_V(8); PG8_WAIT_L(0); PG8_BAR; PG8_MMA(1, 0, At, B0); PG8_MMA(1, 1, At, B1); PG8_BAR; PG8_SCHED;
.LBB0_763:
	ds_read_b128 v[128:131], v181
	ds_read_b128 v[132:135], v181 offset:1024
	ds_read_b128 v[136:139], v181 offset:2048
	ds_read_b128 v[140:143], v181 offset:3072
	ds_read_b128 v[144:147], v182
	ds_read_b128 v[148:151], v182 offset:1024
	ds_read_b128 v[168:171], v182 offset:2048
	ds_read_b128 v[172:175], v182 offset:3072
	s_add_u32 s28, s26, 0xfff00080
	s_addc_u32 s29, s27, -1
	s_cmp_eq_u32 s53, 60
	s_cselect_b32 s31, s7, s29
	s_cselect_b32 s30, s21, s28
	s_cselect_b32 s29, s19, s52
	s_cselect_b32 s28, s48, s49
	v_lshl_add_u64 v[176:177], s[26:27], 0, v[160:161]
	s_add_i32 m0, s35, 0xc000
	ds_read_b128 v[186:189], v183
	ds_read_b128 v[190:193], v183 offset:1024
	ds_read_b128 v[198:201], v183 offset:2048
	ds_read_b128 v[202:205], v183 offset:3072
	ds_read_b128 v[206:209], v183 offset:4096
	ds_read_b128 v[210:213], v183 offset:5120
	ds_read_b128 v[214:217], v183 offset:6144
	ds_read_b128 v[218:221], v183 offset:7168
	global_load_lds_dwordx4 v[176:177], off
	v_lshl_add_u64 v[176:177], s[26:27], 0, v[162:163]
	s_add_i32 m0, s35, 0xe000
	s_nop 0
	global_load_lds_dwordx4 v[176:177], off
	s_waitcnt vmcnt(8)
	s_waitcnt lgkmcnt(0)
	s_barrier
	s_setprio 1
	v_mfma_f32_16x16x32_bf16 v[124:127], v[128:131], v[186:189], v[124:127]
	v_mfma_f32_16x16x32_bf16 v[120:123], v[136:139], v[186:189], v[120:123]
	v_mfma_f32_16x16x32_bf16 v[104:107], v[128:131], v[198:201], v[104:107]
	v_mfma_f32_16x16x32_bf16 v[108:111], v[136:139], v[198:201], v[108:111]
	v_mfma_f32_16x16x32_bf16 v[88:91], v[128:131], v[206:209], v[88:91]
	v_mfma_f32_16x16x32_bf16 v[92:95], v[136:139], v[206:209], v[92:95]
	v_mfma_f32_16x16x32_bf16 v[72:75], v[128:131], v[214:217], v[72:75]
	v_mfma_f32_16x16x32_bf16 v[76:79], v[136:139], v[214:217], v[76:79]
	v_mfma_f32_16x16x32_bf16 v[124:127], v[132:135], v[190:193], v[124:127]
	v_mfma_f32_16x16x32_bf16 v[120:123], v[140:143], v[190:193], v[120:123]
	v_mfma_f32_16x16x32_bf16 v[104:107], v[132:135], v[202:205], v[104:107]
	v_mfma_f32_16x16x32_bf16 v[108:111], v[140:143], v[202:205], v[108:111]
	v_mfma_f32_16x16x32_bf16 v[88:91], v[132:135], v[210:213], v[88:91]
	v_mfma_f32_16x16x32_bf16 v[92:95], v[140:143], v[210:213], v[92:95]
	v_mfma_f32_16x16x32_bf16 v[72:75], v[132:135], v[218:221], v[72:75]
	v_mfma_f32_16x16x32_bf16 v[76:79], v[140:143], v[218:221], v[76:79]
	s_setprio 0
	s_setprio 1
	v_mfma_f32_16x16x32_bf16 v[116:119], v[144:147], v[186:189], v[116:119]
	v_mfma_f32_16x16x32_bf16 v[112:115], v[168:171], v[186:189], v[112:115]
	v_mfma_f32_16x16x32_bf16 v[100:103], v[144:147], v[198:201], v[100:103]
	v_mfma_f32_16x16x32_bf16 v[96:99], v[168:171], v[198:201], v[96:99]
	v_mfma_f32_16x16x32_bf16 v[84:87], v[144:147], v[206:209], v[84:87]
	v_mfma_f32_16x16x32_bf16 v[80:83], v[168:171], v[206:209], v[80:83]
	v_mfma_f32_16x16x32_bf16 v[68:71], v[144:147], v[214:217], v[68:71]
	v_mfma_f32_16x16x32_bf16 v[64:67], v[168:171], v[214:217], v[64:67]
	v_mfma_f32_16x16x32_bf16 v[116:119], v[148:151], v[190:193], v[116:119]
	v_mfma_f32_16x16x32_bf16 v[112:115], v[172:175], v[190:193], v[112:115]
	v_mfma_f32_16x16x32_bf16 v[100:103], v[148:151], v[202:205], v[100:103]
	v_mfma_f32_16x16x32_bf16 v[96:99], v[172:175], v[202:205], v[96:99]
	v_mfma_f32_16x16x32_bf16 v[84:87], v[148:151], v[210:213], v[84:87]
	v_mfma_f32_16x16x32_bf16 v[80:83], v[172:175], v[210:213], v[80:83]
	v_mfma_f32_16x16x32_bf16 v[68:71], v[148:151], v[218:221], v[68:71]
	v_mfma_f32_16x16x32_bf16 v[64:67], v[172:175], v[218:221], v[64:67]
	s_barrier
	s_setprio 0
	s_add_i32 s54, s47, s34
	v_lshl_add_u64 v[176:177], s[28:29], 0, v[154:155]
	s_mov_b32 m0, s54
	ds_read_b128 v[186:189], v183 offset:16384
	ds_read_b128 v[190:193], v183 offset:17408
	ds_read_b128 v[198:201], v183 offset:18432
	ds_read_b128 v[202:205], v183 offset:19456
	ds_read_b128 v[206:209], v183 offset:20480
	ds_read_b128 v[210:213], v183 offset:21504
	ds_read_b128 v[214:217], v183 offset:22528
	ds_read_b128 v[218:221], v183 offset:23552
	global_load_lds_dwordx4 v[176:177], off
	s_add_i32 m0, s54, 0x2000
	s_add_u32 s54, s28, 0x100000
	v_lshl_add_u64 v[194:195], s[28:29], 0, v[158:159]
	s_addc_u32 s55, s29, 0
	s_add_i32 s56, s50, s34
	global_load_lds_dwordx4 v[194:195], off
	v_lshl_add_u64 v[222:223], s[54:55], 0, v[154:155]
	s_mov_b32 m0, s56
	v_lshl_add_u64 v[224:225], s[30:31], 0, v[156:157]
	global_load_lds_dwordx4 v[222:223], off
	v_lshl_add_u64 v[222:223], s[54:55], 0, v[158:159]
	s_add_i32 m0, s56, 0x2000
	s_nop 0
	global_load_lds_dwordx4 v[222:223], off
	v_lshl_add_u64 v[222:223], s[30:31], 0, v[152:153]
	s_mov_b32 m0, s35
	s_nop 0
	global_load_lds_dwordx4 v[222:223], off
	s_mov_b32 m0, s33
	s_nop 0
	global_load_lds_dwordx4 v[224:225], off
	s_waitcnt vmcnt(8)
	s_waitcnt lgkmcnt(0)
	s_barrier
; #define PG8_STAGE(bufoff, gbase, voff) do { _Pragma("unroll") for (int _i = 0; _i < 2; ++_i) \
;         __builtin_amdgcn_global_load_lds((const unsigned*)((const char*)(gbase) + (voff)[_i]), (PG8_LAS unsigned*)(lds + (bufoff) + ldsw + _i * 8192), 16, 0, 0); } while (0)
; #define PG8_LDA(dst, b, h) do { _Pragma("unroll") for (int m = 0; m < 4; ++m) _Pragma("unroll") for (int k = 0; k < 2; ++k) dst[m][k] = *(const PG8_LAS bf16x8*)(lds + PG8_SA(b, h) + aoff + m * 2048 + k * 1024); } while (0)
; #define PG8_LDB(dst, b, h) do { _Pragma("unroll") for (int n = 0; n < 2; ++n) _Pragma("unroll") for (int k = 0; k < 2; ++k) dst[n][k] = *(const PG8_LAS bf16x8*)(lds + PG8_SB(b, h) + boff + n * 2048 + k * 1024); } while (0)
; #define PG8_MMA(ai, bj, At, Bt) do { __builtin_amdgcn_s_setprio(1); _Pragma("unroll") for (int m = 0; m < 4; ++m) _Pragma("unroll") for (int n = 0; n < 2; ++n) _Pragma("unroll") for (int k = 0; k < 2; ++k) \
;         acc[ai][bj][m][n] = __builtin_amdgcn_mfma_f32_16x16x32_bf16(Bt[n][k], At[m][k], acc[ai][bj][m][n], 0, 0, 0); __builtin_amdgcn_s_setprio(0); } while (0)
; #define PG8_WAIT_V(n) asm volatile("s_waitcnt vmcnt(" #n ")" ::: "memory")
; #define PG8_WAIT_L(n) asm volatile("s_waitcnt lgkmcnt(" #n ")" ::: "memory")
; #define PG8_BAR __builtin_amdgcn_s_barrier()
; #define PG8_SCHED __builtin_amdgcn_sched_barrier(0)
; template <class Epi, class Sched, bool ALIGN_EPI = false, bool SP2 = false>
; __device__ __forceinline__ void gemm_phase(PG8_LAS unsigned char* lds, const Gemm g, const Sched& S, const Epi& E) {
;     ...
;             PG8_WAIT_V(8); PG8_WAIT_L(0); PG8_BAR; PG8_MMA(1, 0, At, B0); PG8_MMA(1, 1, At, B1); PG8_BAR; PG8_SCHED;
;             PG8_LDB(B0, 1, 0); PG8_LDB(B1, 1, 1); PG8_SCHED; PG8_LDA(At, 1, 0); PG8_STAGE(PG8_SA(0, 1), a2 + hstep, voffA);
;             PG8_WAIT_V(8); PG8_WAIT_L(0); PG8_BAR; PG8_MMA(0, 0, At, B0); PG8_MMA(0, 1, At, B1); PG8_BAR; PG8_SCHED;
	s_setprio 1
	v_mfma_f32_16x16x32_bf16 v[56:59], v[128:131], v[186:189], v[56:59]
	v_mfma_f32_16x16x32_bf16 v[60:63], v[136:139], v[186:189], v[60:63]
	v_mfma_f32_16x16x32_bf16 v[40:43], v[128:131], v[198:201], v[40:43]
	v_mfma_f32_16x16x32_bf16 v[44:47], v[136:139], v[198:201], v[44:47]
	v_mfma_f32_16x16x32_bf16 v[24:27], v[128:131], v[206:209], v[24:27]
	v_mfma_f32_16x16x32_bf16 v[28:31], v[136:139], v[206:209], v[28:31]
	v_mfma_f32_16x16x32_bf16 v[8:11], v[128:131], v[214:217], v[8:11]
	v_mfma_f32_16x16x32_bf16 v[12:15], v[136:139], v[214:217], v[12:15]
	v_mfma_f32_16x16x32_bf16 v[56:59], v[132:135], v[190:193], v[56:59]
	v_mfma_f32_16x16x32_bf16 v[60:63], v[140:143], v[190:193], v[60:63]
	v_mfma_f32_16x16x32_bf16 v[40:43], v[132:135], v[202:205], v[40:43]
	v_mfma_f32_16x16x32_bf16 v[44:47], v[140:143], v[202:205], v[44:47]
	v_mfma_f32_16x16x32_bf16 v[24:27], v[132:135], v[210:213], v[24:27]
	v_mfma_f32_16x16x32_bf16 v[28:31], v[140:143], v[210:213], v[28:31]
	v_mfma_f32_16x16x32_bf16 v[8:11], v[132:135], v[218:221], v[8:11]
	v_mfma_f32_16x16x32_bf16 v[12:15], v[140:143], v[218:221], v[12:15]
	s_setprio 0
	s_setprio 1
	v_mfma_f32_16x16x32_bf16 v[52:55], v[144:147], v[186:189], v[52:55]
	v_mfma_f32_16x16x32_bf16 v[48:51], v[168:171], v[186:189], v[48:51]
	v_mfma_f32_16x16x32_bf16 v[36:39], v[144:147], v[198:201], v[36:39]
	v_mfma_f32_16x16x32_bf16 v[32:35], v[168:171], v[198:201], v[32:35]
	v_mfma_f32_16x16x32_bf16 v[20:23], v[144:147], v[206:209], v[20:23]
	v_mfma_f32_16x16x32_bf16 v[16:19], v[168:171], v[206:209], v[16:19]
	v_mfma_f32_16x16x32_bf16 v[4:7], v[144:147], v[214:217], v[4:7]
	v_mfma_f32_16x16x32_bf16 v[0:3], v[168:171], v[214:217], v[0:3]
	v_mfma_f32_16x16x32_bf16 v[52:55], v[148:151], v[190:193], v[52:55]
	v_mfma_f32_16x16x32_bf16 v[48:51], v[172:175], v[190:193], v[48:51]
	v_mfma_f32_16x16x32_bf16 v[36:39], v[148:151], v[202:205], v[36:39]
	v_mfma_f32_16x16x32_bf16 v[32:35], v[172:175], v[202:205], v[32:35]
	v_mfma_f32_16x16x32_bf16 v[20:23], v[148:151], v[210:213], v[20:23]
	v_mfma_f32_16x16x32_bf16 v[16:19], v[172:175], v[210:213], v[16:19]
	v_mfma_f32_16x16x32_bf16 v[4:7], v[148:151], v[218:221], v[4:7]
	v_mfma_f32_16x16x32_bf16 v[0:3], v[172:175], v[218:221], v[0:3]
	s_barrier
	s_setprio 0
	s_add_i32 s54, 0, 0x18000
	s_add_i32 s55, 0, 0x1c000
	v_add_u32_e32 v140, s54, v179
	v_add_u32_e32 v172, s55, v179
	ds_read_b128 v[128:131], v140
	ds_read_b128 v[132:135], v140 offset:1024
	ds_read_b128 v[136:139], v140 offset:2048
	ds_read_b128 v[140:143], v140 offset:3072
	ds_read_b128 v[144:147], v172
	ds_read_b128 v[148:151], v172 offset:1024
	ds_read_b128 v[168:171], v172 offset:2048
	ds_read_b128 v[172:175], v172 offset:3072
	s_add_u32 s30, s30, 0x100000
	s_addc_u32 s31, s31, 0
	s_mov_b32 m0, s37
	v_lshl_add_u64 v[226:227], s[30:31], 0, v[152:153]
	ds_read_b128 v[186:189], v183 offset:32768
	ds_read_b128 v[190:193], v183 offset:33792
	ds_read_b128 v[198:201], v183 offset:34816
	ds_read_b128 v[202:205], v183 offset:35840
	ds_read_b128 v[206:209], v183 offset:36864
	ds_read_b128 v[210:213], v183 offset:37888
	ds_read_b128 v[214:217], v183 offset:38912
	ds_read_b128 v[218:221], v183 offset:39936
	global_load_lds_dwordx4 v[226:227], off
	v_lshl_add_u64 v[226:227], s[30:31], 0, v[156:157]
	s_mov_b32 m0, s39
	s_nop 0
	global_load_lds_dwordx4 v[226:227], off
	s_waitcnt vmcnt(8)
	s_waitcnt lgkmcnt(0)
	s_barrier
	s_setprio 1
	v_mfma_f32_16x16x32_bf16 v[124:127], v[128:131], v[186:189], v[124:127]
	v_mfma_f32_16x16x32_bf16 v[120:123], v[136:139], v[186:189], v[120:123]
	v_mfma_f32_16x16x32_bf16 v[104:107], v[128:131], v[198:201], v[104:107]
	v_mfma_f32_16x16x32_bf16 v[108:111], v[136:139], v[198:201], v[108:111]
	v_mfma_f32_16x16x32_bf16 v[88:91], v[128:131], v[206:209], v[88:91]
	v_mfma_f32_16x16x32_bf16 v[92:95], v[136:139], v[206:209], v[92:95]
	v_mfma_f32_16x16x32_bf16 v[72:75], v[128:131], v[214:217], v[72:75]
	v_mfma_f32_16x16x32_bf16 v[76:79], v[136:139], v[214:217], v[76:79]
	v_mfma_f32_16x16x32_bf16 v[124:127], v[132:135], v[190:193], v[124:127]
	v_mfma_f32_16x16x32_bf16 v[120:123], v[140:143], v[190:193], v[120:123]
	v_mfma_f32_16x16x32_bf16 v[104:107], v[132:135], v[202:205], v[104:107]
	v_mfma_f32_16x16x32_bf16 v[108:111], v[140:143], v[202:205], v[108:111]
	v_mfma_f32_16x16x32_bf16 v[88:91], v[132:135], v[210:213], v[88:91]
	v_mfma_f32_16x16x32_bf16 v[92:95], v[140:143], v[210:213], v[92:95]
	v_mfma_f32_16x16x32_bf16 v[72:75], v[132:135], v[218:221], v[72:75]
	v_mfma_f32_16x16x32_bf16 v[76:79], v[140:143], v[218:221], v[76:79]
	s_setprio 0
	s_setprio 1
	v_mfma_f32_16x16x32_bf16 v[116:119], v[144:147], v[186:189], v[116:119]
	v_mfma_f32_16x16x32_bf16 v[112:115], v[168:171], v[186:189], v[112:115]
	v_mfma_f32_16x16x32_bf16 v[100:103], v[144:147], v[198:201], v[100:103]
	v_mfma_f32_16x16x32_bf16 v[96:99], v[168:171], v[198:201], v[96:99]
	v_mfma_f32_16x16x32_bf16 v[84:87], v[144:147], v[206:209], v[84:87]
	v_mfma_f32_16x16x32_bf16 v[80:83], v[168:171], v[206:209], v[80:83]
	v_mfma_f32_16x16x32_bf16 v[68:71], v[144:147], v[214:217], v[68:71]
	v_mfma_f32_16x16x32_bf16 v[64:67], v[168:171], v[214:217], v[64:67]
	v_mfma_f32_16x16x32_bf16 v[116:119], v[148:151], v[190:193], v[116:119]
	v_mfma_f32_16x16x32_bf16 v[112:115], v[172:175], v[190:193], v[112:115]
	v_mfma_f32_16x16x32_bf16 v[100:103], v[148:151], v[202:205], v[100:103]
	v_mfma_f32_16x16x32_bf16 v[96:99], v[172:175], v[202:205], v[96:99]
	v_mfma_f32_16x16x32_bf16 v[84:87], v[148:151], v[210:213], v[84:87]
	v_mfma_f32_16x16x32_bf16 v[80:83], v[172:175], v[210:213], v[80:83]
	v_mfma_f32_16x16x32_bf16 v[68:71], v[148:151], v[218:221], v[68:71]
	v_mfma_f32_16x16x32_bf16 v[64:67], v[172:175], v[218:221], v[64:67]
	s_barrier
; #define PG8_STAGE(bufoff, gbase, voff) do { _Pragma("unroll") for (int _i = 0; _i < 2; ++_i) \
;         __builtin_amdgcn_global_load_lds((const unsigned*)((const char*)(gbase) + (voff)[_i]), (PG8_LAS unsigned*)(lds + (bufoff) + ldsw + _i * 8192), 16, 0, 0); } while (0)
; #define PG8_LDA(dst, b, h) do { _Pragma("unroll") for (int m = 0; m < 4; ++m) _Pragma("unroll") for (int k = 0; k < 2; ++k) dst[m][k] = *(const PG8_LAS bf16x8*)(lds + PG8_SA(b, h) + aoff + m * 2048 + k * 1024); } while (0)
; #define PG8_MMA(ai, bj, At, Bt) do { __builtin_amdgcn_s_setprio(1); _Pragma("unroll") for (int m = 0; m < 4; ++m) _Pragma("unroll") for (int n = 0; n < 2; ++n) _Pragma("unroll") for (int k = 0; k < 2; ++k) \
;         acc[ai][bj][m][n] = __builtin_amdgcn_mfma_f32_16x16x32_bf16(Bt[n][k], At[m][k], acc[ai][bj][m][n], 0, 0, 0); __builtin_amdgcn_s_setprio(0); } while (0)
; #define PG8_WAIT_V(n) asm volatile("s_waitcnt vmcnt(" #n ")" ::: "memory")
; #define PG8_WAIT_L(n) asm volatile("s_waitcnt lgkmcnt(" #n ")" ::: "memory")
; #define PG8_BAR __builtin_amdgcn_s_barrier()
; #define PG8_SCHED __builtin_amdgcn_sched_barrier(0)
; template <class Epi, class Sched, bool ALIGN_EPI = false, bool SP2 = false>
; __device__ __forceinline__ void gemm_phase(PG8_LAS unsigned char* lds, const Gemm g, const Sched& S, const Epi& E) {
;     ...
;             PG8_WAIT_V(8); PG8_WAIT_L(0); PG8_BAR; PG8_MMA(0, 0, At, B0); PG8_MMA(0, 1, At, B1); PG8_BAR; PG8_SCHED;
;             PG8_LDA(At, 1, 1); PG8_STAGE(PG8_SB(1, 0), b3, voffB); PG8_STAGE(PG8_SB(1, 1), b3 + hstep, voffB); PG8_STAGE(PG8_SA(1, 0), a3, voffA);
;             PG8_WAIT_V(8); PG8_WAIT_L(0); PG8_BAR; PG8_MMA(1, 0, At, B0); PG8_MMA(1, 1, At, B1); PG8_BAR; PG8_SCHED;
	s_setprio 0
	s_add_i32 s30, s54, s34
	v_lshl_add_u64 v[176:177], v[176:177], 0, s[12:13]
	s_mov_b32 m0, s30
	ds_read_b128 v[186:189], v183 offset:49152
	ds_read_b128 v[190:193], v183 offset:50176
	ds_read_b128 v[198:201], v183 offset:51200
	ds_read_b128 v[202:205], v183 offset:52224
	ds_read_b128 v[206:209], v183 offset:53248
	ds_read_b128 v[210:213], v183 offset:54272
	ds_read_b128 v[214:217], v183 offset:55296
	ds_read_b128 v[218:221], v183 offset:56320
	global_load_lds_dwordx4 v[176:177], off
	s_add_i32 m0, s30, 0x2000
	s_add_u32 s28, s28, 0x100080
	v_lshl_add_u64 v[176:177], v[194:195], 0, s[12:13]
	s_addc_u32 s29, s29, 0
	s_add_i32 s30, s55, s34
	global_load_lds_dwordx4 v[176:177], off
	v_lshl_add_u64 v[176:177], s[28:29], 0, v[154:155]
	s_mov_b32 m0, s30
	s_nop 0
	global_load_lds_dwordx4 v[176:177], off
	v_lshl_add_u64 v[176:177], s[28:29], 0, v[158:159]
	s_add_i32 m0, s30, 0x2000
	s_nop 0
	global_load_lds_dwordx4 v[176:177], off
	v_lshl_add_u64 v[176:177], v[222:223], 0, s[12:13]
	s_mov_b32 m0, s43
	s_nop 0
	global_load_lds_dwordx4 v[176:177], off
	v_lshl_add_u64 v[176:177], v[224:225], 0, s[12:13]
	s_mov_b32 m0, s44
	s_nop 0
	global_load_lds_dwordx4 v[176:177], off
	s_waitcnt vmcnt(8)
	s_waitcnt lgkmcnt(0)
	s_barrier
	s_setprio 1
	v_mfma_f32_16x16x32_bf16 v[56:59], v[128:131], v[186:189], v[56:59]
	v_mfma_f32_16x16x32_bf16 v[60:63], v[136:139], v[186:189], v[60:63]
	v_mfma_f32_16x16x32_bf16 v[40:43], v[128:131], v[198:201], v[40:43]
	v_mfma_f32_16x16x32_bf16 v[44:47], v[136:139], v[198:201], v[44:47]
	v_mfma_f32_16x16x32_bf16 v[24:27], v[128:131], v[206:209], v[24:27]
	v_mfma_f32_16x16x32_bf16 v[28:31], v[136:139], v[206:209], v[28:31]
	v_mfma_f32_16x16x32_bf16 v[8:11], v[128:131], v[214:217], v[8:11]
	v_mfma_f32_16x16x32_bf16 v[12:15], v[136:139], v[214:217], v[12:15]
	v_mfma_f32_16x16x32_bf16 v[56:59], v[132:135], v[190:193], v[56:59]
	v_mfma_f32_16x16x32_bf16 v[60:63], v[140:143], v[190:193], v[60:63]
	v_mfma_f32_16x16x32_bf16 v[40:43], v[132:135], v[202:205], v[40:43]
	v_mfma_f32_16x16x32_bf16 v[44:47], v[140:143], v[202:205], v[44:47]
	v_mfma_f32_16x16x32_bf16 v[24:27], v[132:135], v[210:213], v[24:27]
	v_mfma_f32_16x16x32_bf16 v[28:31], v[140:143], v[210:213], v[28:31]
	v_mfma_f32_16x16x32_bf16 v[8:11], v[132:135], v[218:221], v[8:11]
	v_mfma_f32_16x16x32_bf16 v[12:15], v[140:143], v[218:221], v[12:15]
	s_setprio 0
	s_setprio 1
	v_mfma_f32_16x16x32_bf16 v[52:55], v[144:147], v[186:189], v[52:55]
	v_mfma_f32_16x16x32_bf16 v[48:51], v[168:171], v[186:189], v[48:51]
	v_mfma_f32_16x16x32_bf16 v[36:39], v[144:147], v[198:201], v[36:39]
	v_mfma_f32_16x16x32_bf16 v[32:35], v[168:171], v[198:201], v[32:35]
	v_mfma_f32_16x16x32_bf16 v[20:23], v[144:147], v[206:209], v[20:23]
	v_mfma_f32_16x16x32_bf16 v[16:19], v[168:171], v[206:209], v[16:19]
	v_mfma_f32_16x16x32_bf16 v[4:7], v[144:147], v[214:217], v[4:7]
	v_mfma_f32_16x16x32_bf16 v[0:3], v[168:171], v[214:217], v[0:3]
	v_mfma_f32_16x16x32_bf16 v[52:55], v[148:151], v[190:193], v[52:55]
	v_mfma_f32_16x16x32_bf16 v[48:51], v[172:175], v[190:193], v[48:51]
	v_mfma_f32_16x16x32_bf16 v[36:39], v[148:151], v[202:205], v[36:39]
	v_mfma_f32_16x16x32_bf16 v[32:35], v[172:175], v[202:205], v[32:35]
	v_mfma_f32_16x16x32_bf16 v[20:23], v[148:151], v[210:213], v[20:23]
	v_mfma_f32_16x16x32_bf16 v[16:19], v[172:175], v[210:213], v[16:19]
	v_mfma_f32_16x16x32_bf16 v[4:7], v[148:151], v[218:221], v[4:7]
	v_mfma_f32_16x16x32_bf16 v[0:3], v[172:175], v[218:221], v[0:3]
	s_barrier
	s_setprio 0
	s_add_i32 s53, s53, 2
	s_add_u32 s26, s26, 0x100
	s_addc_u32 s27, s27, 0
	s_add_u32 s49, s49, 0x100
	s_addc_u32 s52, s52, 0
	s_cmp_gt_u32 s53, 61
	s_cbranch_scc0 .LBB0_763
	s_and_b64 vcc, exec, s[14:15]
	s_cbranch_vccz .LBB0_766
	s_barrier

; #define PG8_STAGE(bufoff, gbase, voff) do { _Pragma("unroll") for (int _i = 0; _i < 2; ++_i) \
;         __builtin_amdgcn_global_load_lds((const unsigned*)((const char*)(gbase) + (voff)[_i]), (PG8_LAS unsigned*)(lds + (bufoff) + ldsw + _i * 8192), 16, 0, 0); } while (0)
; #define PG8_LDA(dst, b, h) do { _Pragma("unroll") for (int m = 0; m < 4; ++m) _Pragma("unroll") for (int k = 0; k < 2; ++k) dst[m][k] = *(const PG8_LAS bf16x8*)(lds + PG8_SA(b, h) + aoff + m * 2048 + k * 1024); } while (0)
; #define PG8_LDB(dst, b, h) do { _Pragma("unroll") for (int n = 0; n < 2; ++n) _Pragma("unroll") for (int k = 0; k < 2; ++k) dst[n][k] = *(const PG8_LAS bf16x8*)(lds + PG8_SB(b, h) + boff + n * 2048 + k * 1024); } while (0)
; #define PG8_MMA(ai, bj, At, Bt) do { __builtin_amdgcn_s_setprio(1); _Pragma("unroll") for (int m = 0; m < 4; ++m) _Pragma("unroll") for (int n = 0; n < 2; ++n) _Pragma("unroll") for (int k = 0; k < 2; ++k) \
;         acc[ai][bj][m][n] = __builtin_amdgcn_mfma_f32_16x16x32_bf16(Bt[n][k], At[m][k], acc[ai][bj][m][n], 0, 0, 0); __builtin_amdgcn_s_setprio(0); } while (0)
; #define PG8_WAIT_V(n) asm volatile("s_waitcnt vmcnt(" #n ")" ::: "memory")
; #define PG8_WAIT_L(n) asm volatile("s_waitcnt lgkmcnt(" #n ")" ::: "memory")
; #define PG8_BAR __builtin_amdgcn_s_barrier()
; #define PG8_SCHED __builtin_amdgcn_sched_barrier(0)
; template <class Epi, class Sched, bool ALIGN_EPI = false, bool SP2 = false>
; __device__ __forceinline__ void gemm_phase(PG8_LAS unsigned char* lds, const Gemm g, const Sched& S, const Epi& E) {
;     ...
;             PG8_LDB(B0, 0, 0); PG8_LDB(B1, 0, 1); PG8_SCHED; PG8_LDA(At, 0, 0); PG8_STAGE(PG8_SA(1, 1), a1 + hstep, voffA);
;             PG8_WAIT_V(8); PG8_WAIT_L(0); PG8_BAR; PG8_MMA(0, 0, At, B0); PG8_MMA(0, 1, At, B1); PG8_BAR; PG8_SCHED;
;             PG8_LDA(At, 0, 1); PG8_STAGE(PG8_SB(0, 0), b2, voffB); PG8_STAGE(PG8_SB(0, 1), b2 + hstep, voffB); PG8_STAGE(PG8_SA(0, 0), a2, voffA);
;             PG8_WAIT_V(8); PG8_WAIT_L(0); PG8_BAR; PG8_MMA(1, 0, At, B0); PG8_MMA(1, 1, At, B1); PG8_BAR; PG8_SCHED;
.LBB0_955:
	ds_read_b128 v[128:131], v209
	ds_read_b128 v[132:135], v209 offset:1024
	ds_read_b128 v[136:139], v209 offset:2048
	ds_read_b128 v[178:181], v209 offset:3072
	ds_read_b128 v[182:185], v210
	ds_read_b128 v[186:189], v210 offset:1024
	ds_read_b128 v[190:193], v210 offset:2048
	ds_read_b128 v[222:225], v210 offset:3072
	s_add_u32 s28, s26, 0xfff80080
	s_addc_u32 s29, s27, -1
	s_cmp_eq_u32 s45, 28
	s_cselect_b32 s31, s1, s29
	s_cselect_b32 s30, s5, s28
	s_cselect_b32 s29, s17, s44
	s_cselect_b32 s28, s19, s33
	v_lshl_add_u64 v[166:167], s[26:27], 0, v[150:151]
	s_add_i32 m0, s35, 0xc000
	ds_read_b128 v[226:229], v211
	ds_read_b128 v[230:233], v211 offset:1024
	ds_read_b128 v[234:237], v211 offset:2048
	ds_read_b128 v[238:241], v211 offset:3072
	ds_read_b128 v[242:245], v211 offset:4096
	ds_read_b128 v[246:249], v211 offset:5120
	ds_read_b128 v[250:253], v211 offset:6144
	ds_read_b128 v[160:163], v211 offset:7168
	global_load_lds_dwordx4 v[166:167], off
	v_lshl_add_u64 v[166:167], s[26:27], 0, v[152:153]
	s_add_i32 m0, s35, 0xe000
	s_nop 0
	global_load_lds_dwordx4 v[166:167], off
	s_waitcnt vmcnt(8)
	s_waitcnt lgkmcnt(0)
	s_barrier
	s_setprio 1
	v_mfma_f32_16x16x32_bf16 v[124:127], v[128:131], v[226:229], v[124:127]
	v_mfma_f32_16x16x32_bf16 v[120:123], v[136:139], v[226:229], v[120:123]
	v_mfma_f32_16x16x32_bf16 v[116:119], v[128:131], v[234:237], v[116:119]
	v_mfma_f32_16x16x32_bf16 v[108:111], v[136:139], v[234:237], v[108:111]
	v_mfma_f32_16x16x32_bf16 v[100:103], v[128:131], v[242:245], v[100:103]
	v_mfma_f32_16x16x32_bf16 v[92:95], v[136:139], v[242:245], v[92:95]
	v_mfma_f32_16x16x32_bf16 v[84:87], v[128:131], v[250:253], v[84:87]
	v_mfma_f32_16x16x32_bf16 v[76:79], v[136:139], v[250:253], v[76:79]
	v_mfma_f32_16x16x32_bf16 v[124:127], v[132:135], v[230:233], v[124:127]
	v_mfma_f32_16x16x32_bf16 v[120:123], v[178:181], v[230:233], v[120:123]
	v_mfma_f32_16x16x32_bf16 v[116:119], v[132:135], v[238:241], v[116:119]
	v_mfma_f32_16x16x32_bf16 v[108:111], v[178:181], v[238:241], v[108:111]
	v_mfma_f32_16x16x32_bf16 v[100:103], v[132:135], v[246:249], v[100:103]
	v_mfma_f32_16x16x32_bf16 v[92:95], v[178:181], v[246:249], v[92:95]
	v_mfma_f32_16x16x32_bf16 v[84:87], v[132:135], v[160:163], v[84:87]
	v_mfma_f32_16x16x32_bf16 v[76:79], v[178:181], v[160:163], v[76:79]
	s_setprio 0
	s_setprio 1
	v_mfma_f32_16x16x32_bf16 v[112:115], v[182:185], v[226:229], v[112:115]
	v_mfma_f32_16x16x32_bf16 v[104:107], v[190:193], v[226:229], v[104:107]
	v_mfma_f32_16x16x32_bf16 v[96:99], v[182:185], v[234:237], v[96:99]
	v_mfma_f32_16x16x32_bf16 v[88:91], v[190:193], v[234:237], v[88:91]
	v_mfma_f32_16x16x32_bf16 v[80:83], v[182:185], v[242:245], v[80:83]
	v_mfma_f32_16x16x32_bf16 v[72:75], v[190:193], v[242:245], v[72:75]
	v_mfma_f32_16x16x32_bf16 v[68:71], v[182:185], v[250:253], v[68:71]
	v_mfma_f32_16x16x32_bf16 v[64:67], v[190:193], v[250:253], v[64:67]
	v_mfma_f32_16x16x32_bf16 v[112:115], v[186:189], v[230:233], v[112:115]
	v_mfma_f32_16x16x32_bf16 v[104:107], v[222:225], v[230:233], v[104:107]
	v_mfma_f32_16x16x32_bf16 v[96:99], v[186:189], v[238:241], v[96:99]
	v_mfma_f32_16x16x32_bf16 v[88:91], v[222:225], v[238:241], v[88:91]
	v_mfma_f32_16x16x32_bf16 v[80:83], v[186:189], v[246:249], v[80:83]
	v_mfma_f32_16x16x32_bf16 v[72:75], v[222:225], v[246:249], v[72:75]
	v_mfma_f32_16x16x32_bf16 v[68:71], v[186:189], v[160:163], v[68:71]
	v_mfma_f32_16x16x32_bf16 v[64:67], v[222:225], v[160:163], v[64:67]
	s_barrier
	s_setprio 0
	s_add_i32 s48, s69, s34
	v_lshl_add_u64 v[166:167], s[28:29], 0, v[142:143]
	s_mov_b32 m0, s48
	ds_read_b128 v[160:163], v211 offset:16384
	ds_read_b128 v[226:229], v211 offset:17408
	ds_read_b128 v[230:233], v211 offset:18432
	ds_read_b128 v[234:237], v211 offset:19456
	ds_read_b128 v[238:241], v211 offset:20480
	ds_read_b128 v[242:245], v211 offset:21504
	ds_read_b128 v[246:249], v211 offset:22528
	ds_read_b128 v[250:253], v211 offset:23552
	global_load_lds_dwordx4 v[166:167], off
	s_add_i32 m0, s48, 0x2000
	s_add_u32 s48, s28, 0x80000
	v_lshl_add_u64 v[170:171], s[28:29], 0, v[146:147]
	s_addc_u32 s49, s29, 0
	s_add_i32 s50, s70, s34
	global_load_lds_dwordx4 v[170:171], off
	v_lshl_add_u64 v[174:175], s[48:49], 0, v[142:143]
	s_mov_b32 m0, s50
	v_lshl_add_u64 v[194:195], s[30:31], 0, v[144:145]
	global_load_lds_dwordx4 v[174:175], off
	v_lshl_add_u64 v[174:175], s[48:49], 0, v[146:147]
	s_add_i32 m0, s50, 0x2000
	s_nop 0
	global_load_lds_dwordx4 v[174:175], off
	v_lshl_add_u64 v[174:175], s[30:31], 0, v[140:141]
	s_mov_b32 m0, s35
	s_nop 0
	global_load_lds_dwordx4 v[174:175], off
	s_mov_b32 m0, s37
	s_nop 0
	global_load_lds_dwordx4 v[194:195], off
	s_waitcnt vmcnt(8)
	s_waitcnt lgkmcnt(0)
	s_barrier
; #define PG8_STAGE(bufoff, gbase, voff) do { _Pragma("unroll") for (int _i = 0; _i < 2; ++_i) \
;         __builtin_amdgcn_global_load_lds((const unsigned*)((const char*)(gbase) + (voff)[_i]), (PG8_LAS unsigned*)(lds + (bufoff) + ldsw + _i * 8192), 16, 0, 0); } while (0)
; #define PG8_LDA(dst, b, h) do { _Pragma("unroll") for (int m = 0; m < 4; ++m) _Pragma("unroll") for (int k = 0; k < 2; ++k) dst[m][k] = *(const PG8_LAS bf16x8*)(lds + PG8_SA(b, h) + aoff + m * 2048 + k * 1024); } while (0)
; #define PG8_LDB(dst, b, h) do { _Pragma("unroll") for (int n = 0; n < 2; ++n) _Pragma("unroll") for (int k = 0; k < 2; ++k) dst[n][k] = *(const PG8_LAS bf16x8*)(lds + PG8_SB(b, h) + boff + n * 2048 + k * 1024); } while (0)
; #define PG8_MMA(ai, bj, At, Bt) do { __builtin_amdgcn_s_setprio(1); _Pragma("unroll") for (int m = 0; m < 4; ++m) _Pragma("unroll") for (int n = 0; n < 2; ++n) _Pragma("unroll") for (int k = 0; k < 2; ++k) \
;         acc[ai][bj][m][n] = __builtin_amdgcn_mfma_f32_16x16x32_bf16(Bt[n][k], At[m][k], acc[ai][bj][m][n], 0, 0, 0); __builtin_amdgcn_s_setprio(0); } while (0)
; #define PG8_WAIT_V(n) asm volatile("s_waitcnt vmcnt(" #n ")" ::: "memory")
; #define PG8_WAIT_L(n) asm volatile("s_waitcnt lgkmcnt(" #n ")" ::: "memory")
; #define PG8_BAR __builtin_amdgcn_s_barrier()
; #define PG8_SCHED __builtin_amdgcn_sched_barrier(0)
; template <class Epi, class Sched, bool ALIGN_EPI = false, bool SP2 = false>
; __device__ __forceinline__ void gemm_phase(PG8_LAS unsigned char* lds, const Gemm g, const Sched& S, const Epi& E) {
;     ...
;             PG8_WAIT_V(8); PG8_WAIT_L(0); PG8_BAR; PG8_MMA(1, 0, At, B0); PG8_MMA(1, 1, At, B1); PG8_BAR; PG8_SCHED;
;             PG8_LDB(B0, 1, 0); PG8_LDB(B1, 1, 1); PG8_SCHED; PG8_LDA(At, 1, 0); PG8_STAGE(PG8_SA(0, 1), a2 + hstep, voffA);
;             PG8_WAIT_V(8); PG8_WAIT_L(0); PG8_BAR; PG8_MMA(0, 0, At, B0); PG8_MMA(0, 1, At, B1); PG8_BAR; PG8_SCHED;
	s_setprio 1
	v_mfma_f32_16x16x32_bf16 v[60:63], v[128:131], v[160:163], v[60:63]
	v_mfma_f32_16x16x32_bf16 v[56:59], v[136:139], v[160:163], v[56:59]
	v_mfma_f32_16x16x32_bf16 v[52:55], v[128:131], v[230:233], v[52:55]
	v_mfma_f32_16x16x32_bf16 v[44:47], v[136:139], v[230:233], v[44:47]
	v_mfma_f32_16x16x32_bf16 v[36:39], v[128:131], v[238:241], v[36:39]
	v_mfma_f32_16x16x32_bf16 v[28:31], v[136:139], v[238:241], v[28:31]
	v_mfma_f32_16x16x32_bf16 v[20:23], v[128:131], v[246:249], v[20:23]
	v_mfma_f32_16x16x32_bf16 v[12:15], v[136:139], v[246:249], v[12:15]
	v_mfma_f32_16x16x32_bf16 v[60:63], v[132:135], v[226:229], v[60:63]
	v_mfma_f32_16x16x32_bf16 v[56:59], v[178:181], v[226:229], v[56:59]
	v_mfma_f32_16x16x32_bf16 v[52:55], v[132:135], v[234:237], v[52:55]
	v_mfma_f32_16x16x32_bf16 v[44:47], v[178:181], v[234:237], v[44:47]
	v_mfma_f32_16x16x32_bf16 v[36:39], v[132:135], v[242:245], v[36:39]
	v_mfma_f32_16x16x32_bf16 v[28:31], v[178:181], v[242:245], v[28:31]
	v_mfma_f32_16x16x32_bf16 v[20:23], v[132:135], v[250:253], v[20:23]
	v_mfma_f32_16x16x32_bf16 v[12:15], v[178:181], v[250:253], v[12:15]
	s_setprio 0
	s_setprio 1
	v_mfma_f32_16x16x32_bf16 v[48:51], v[182:185], v[160:163], v[48:51]
	v_mfma_f32_16x16x32_bf16 v[40:43], v[190:193], v[160:163], v[40:43]
	v_mfma_f32_16x16x32_bf16 v[32:35], v[182:185], v[230:233], v[32:35]
	v_mfma_f32_16x16x32_bf16 v[24:27], v[190:193], v[230:233], v[24:27]
	v_mfma_f32_16x16x32_bf16 v[16:19], v[182:185], v[238:241], v[16:19]
	v_mfma_f32_16x16x32_bf16 v[8:11], v[190:193], v[238:241], v[8:11]
	v_mfma_f32_16x16x32_bf16 v[4:7], v[182:185], v[246:249], v[4:7]
	v_mfma_f32_16x16x32_bf16 v[0:3], v[190:193], v[246:249], v[0:3]
	v_mfma_f32_16x16x32_bf16 v[48:51], v[186:189], v[226:229], v[48:51]
	v_mfma_f32_16x16x32_bf16 v[40:43], v[222:225], v[226:229], v[40:43]
	v_mfma_f32_16x16x32_bf16 v[32:35], v[186:189], v[234:237], v[32:35]
	v_mfma_f32_16x16x32_bf16 v[24:27], v[222:225], v[234:237], v[24:27]
	v_mfma_f32_16x16x32_bf16 v[16:19], v[186:189], v[242:245], v[16:19]
	v_mfma_f32_16x16x32_bf16 v[8:11], v[222:225], v[242:245], v[8:11]
	v_mfma_f32_16x16x32_bf16 v[4:7], v[186:189], v[250:253], v[4:7]
	v_mfma_f32_16x16x32_bf16 v[0:3], v[222:225], v[250:253], v[0:3]
	s_barrier
	s_setprio 0
	s_add_i32 s48, 0, 0x18000
	v_add_u32_e32 v148, s48, v159
	s_add_i32 s49, 0, 0x1c000
	ds_read_b128 v[128:131], v148
	ds_read_b128 v[132:135], v148 offset:1024
	ds_read_b128 v[136:139], v148 offset:2048
	ds_read_b128 v[160:163], v148 offset:3072
	v_add_u32_e32 v148, s49, v159
	ds_read_b128 v[178:181], v148
	ds_read_b128 v[182:185], v148 offset:1024
	ds_read_b128 v[186:189], v148 offset:2048
	ds_read_b128 v[190:193], v148 offset:3072
	s_add_u32 s30, s30, 0x80000
	s_addc_u32 s31, s31, 0
	s_mov_b32 m0, s39
	v_lshl_add_u64 v[154:155], s[30:31], 0, v[140:141]
	ds_read_b128 v[222:225], v211 offset:32768
	ds_read_b128 v[226:229], v211 offset:33792
	ds_read_b128 v[230:233], v211 offset:34816
	ds_read_b128 v[234:237], v211 offset:35840
	ds_read_b128 v[238:241], v211 offset:36864
	ds_read_b128 v[242:245], v211 offset:37888
	ds_read_b128 v[246:249], v211 offset:38912
	ds_read_b128 v[250:253], v211 offset:39936
	global_load_lds_dwordx4 v[154:155], off
	v_lshl_add_u64 v[154:155], s[30:31], 0, v[144:145]
	s_mov_b32 m0, s42
	s_nop 0
	global_load_lds_dwordx4 v[154:155], off
	s_waitcnt vmcnt(8)
	s_waitcnt lgkmcnt(0)
	s_barrier
	s_setprio 1
	v_mfma_f32_16x16x32_bf16 v[124:127], v[128:131], v[222:225], v[124:127]
	v_mfma_f32_16x16x32_bf16 v[120:123], v[136:139], v[222:225], v[120:123]
	v_mfma_f32_16x16x32_bf16 v[116:119], v[128:131], v[230:233], v[116:119]
	v_mfma_f32_16x16x32_bf16 v[108:111], v[136:139], v[230:233], v[108:111]
	v_mfma_f32_16x16x32_bf16 v[100:103], v[128:131], v[238:241], v[100:103]
	v_mfma_f32_16x16x32_bf16 v[92:95], v[136:139], v[238:241], v[92:95]
	v_mfma_f32_16x16x32_bf16 v[84:87], v[128:131], v[246:249], v[84:87]
	v_mfma_f32_16x16x32_bf16 v[76:79], v[136:139], v[246:249], v[76:79]
	v_mfma_f32_16x16x32_bf16 v[124:127], v[132:135], v[226:229], v[124:127]
	v_mfma_f32_16x16x32_bf16 v[120:123], v[160:163], v[226:229], v[120:123]
	v_mfma_f32_16x16x32_bf16 v[116:119], v[132:135], v[234:237], v[116:119]
	v_mfma_f32_16x16x32_bf16 v[108:111], v[160:163], v[234:237], v[108:111]
	v_mfma_f32_16x16x32_bf16 v[100:103], v[132:135], v[242:245], v[100:103]
	v_mfma_f32_16x16x32_bf16 v[92:95], v[160:163], v[242:245], v[92:95]
	v_mfma_f32_16x16x32_bf16 v[84:87], v[132:135], v[250:253], v[84:87]
	v_mfma_f32_16x16x32_bf16 v[76:79], v[160:163], v[250:253], v[76:79]
	s_setprio 0
	s_setprio 1
	v_mfma_f32_16x16x32_bf16 v[112:115], v[178:181], v[222:225], v[112:115]
	v_mfma_f32_16x16x32_bf16 v[104:107], v[186:189], v[222:225], v[104:107]
	v_mfma_f32_16x16x32_bf16 v[96:99], v[178:181], v[230:233], v[96:99]
	v_mfma_f32_16x16x32_bf16 v[88:91], v[186:189], v[230:233], v[88:91]
	v_mfma_f32_16x16x32_bf16 v[80:83], v[178:181], v[238:241], v[80:83]
	v_mfma_f32_16x16x32_bf16 v[72:75], v[186:189], v[238:241], v[72:75]
	v_mfma_f32_16x16x32_bf16 v[68:71], v[178:181], v[246:249], v[68:71]
	v_mfma_f32_16x16x32_bf16 v[64:67], v[186:189], v[246:249], v[64:67]
	v_mfma_f32_16x16x32_bf16 v[112:115], v[182:185], v[226:229], v[112:115]
	v_mfma_f32_16x16x32_bf16 v[104:107], v[190:193], v[226:229], v[104:107]
	v_mfma_f32_16x16x32_bf16 v[96:99], v[182:185], v[234:237], v[96:99]
	v_mfma_f32_16x16x32_bf16 v[88:91], v[190:193], v[234:237], v[88:91]
	v_mfma_f32_16x16x32_bf16 v[80:83], v[182:185], v[242:245], v[80:83]
	v_mfma_f32_16x16x32_bf16 v[72:75], v[190:193], v[242:245], v[72:75]
	v_mfma_f32_16x16x32_bf16 v[68:71], v[182:185], v[250:253], v[68:71]
	v_mfma_f32_16x16x32_bf16 v[64:67], v[190:193], v[250:253], v[64:67]
	s_barrier
; #define PG8_STAGE(bufoff, gbase, voff) do { _Pragma("unroll") for (int _i = 0; _i < 2; ++_i) \
;         __builtin_amdgcn_global_load_lds((const unsigned*)((const char*)(gbase) + (voff)[_i]), (PG8_LAS unsigned*)(lds + (bufoff) + ldsw + _i * 8192), 16, 0, 0); } while (0)
; #define PG8_LDA(dst, b, h) do { _Pragma("unroll") for (int m = 0; m < 4; ++m) _Pragma("unroll") for (int k = 0; k < 2; ++k) dst[m][k] = *(const PG8_LAS bf16x8*)(lds + PG8_SA(b, h) + aoff + m * 2048 + k * 1024); } while (0)
; #define PG8_MMA(ai, bj, At, Bt) do { __builtin_amdgcn_s_setprio(1); _Pragma("unroll") for (int m = 0; m < 4; ++m) _Pragma("unroll") for (int n = 0; n < 2; ++n) _Pragma("unroll") for (int k = 0; k < 2; ++k) \
;         acc[ai][bj][m][n] = __builtin_amdgcn_mfma_f32_16x16x32_bf16(Bt[n][k], At[m][k], acc[ai][bj][m][n], 0, 0, 0); __builtin_amdgcn_s_setprio(0); } while (0)
; #define PG8_WAIT_V(n) asm volatile("s_waitcnt vmcnt(" #n ")" ::: "memory")
; #define PG8_WAIT_L(n) asm volatile("s_waitcnt lgkmcnt(" #n ")" ::: "memory")
; #define PG8_BAR __builtin_amdgcn_s_barrier()
; #define PG8_SCHED __builtin_amdgcn_sched_barrier(0)
; template <class Epi, class Sched, bool ALIGN_EPI = false, bool SP2 = false>
; __device__ __forceinline__ void gemm_phase(PG8_LAS unsigned char* lds, const Gemm g, const Sched& S, const Epi& E) {
;     ...
;             PG8_WAIT_V(8); PG8_WAIT_L(0); PG8_BAR; PG8_MMA(0, 0, At, B0); PG8_MMA(0, 1, At, B1); PG8_BAR; PG8_SCHED;
;             PG8_LDA(At, 1, 1); PG8_STAGE(PG8_SB(1, 0), b3, voffB); PG8_STAGE(PG8_SB(1, 1), b3 + hstep, voffB); PG8_STAGE(PG8_SA(1, 0), a3, voffA);
;             PG8_WAIT_V(8); PG8_WAIT_L(0); PG8_BAR; PG8_MMA(1, 0, At, B0); PG8_MMA(1, 1, At, B1); PG8_BAR; PG8_SCHED;
	s_setprio 0
	s_add_i32 s30, s48, s34
	v_lshl_add_u64 v[154:155], v[166:167], 0, s[10:11]
	s_mov_b32 m0, s30
	ds_read_b128 v[222:225], v211 offset:49152
	ds_read_b128 v[226:229], v211 offset:50176
	ds_read_b128 v[230:233], v211 offset:51200
	ds_read_b128 v[234:237], v211 offset:52224
	ds_read_b128 v[238:241], v211 offset:53248
	ds_read_b128 v[242:245], v211 offset:54272
	ds_read_b128 v[246:249], v211 offset:55296
	ds_read_b128 v[250:253], v211 offset:56320
	global_load_lds_dwordx4 v[154:155], off
	s_add_i32 m0, s30, 0x2000
	s_add_u32 s28, s28, 0x80080
	v_lshl_add_u64 v[154:155], v[170:171], 0, s[10:11]
	s_addc_u32 s29, s29, 0
	s_add_i32 s30, s49, s34
	global_load_lds_dwordx4 v[154:155], off
	v_lshl_add_u64 v[154:155], s[28:29], 0, v[142:143]
	s_mov_b32 m0, s30
	s_nop 0
	global_load_lds_dwordx4 v[154:155], off
	v_lshl_add_u64 v[154:155], s[28:29], 0, v[146:147]
	s_add_i32 m0, s30, 0x2000
	s_nop 0
	global_load_lds_dwordx4 v[154:155], off
	v_lshl_add_u64 v[154:155], v[174:175], 0, s[10:11]
	s_mov_b32 m0, s46
	s_nop 0
	global_load_lds_dwordx4 v[154:155], off
	v_lshl_add_u64 v[154:155], v[194:195], 0, s[10:11]
	s_mov_b32 m0, s47
	s_nop 0
	global_load_lds_dwordx4 v[154:155], off
	s_waitcnt vmcnt(8)
	s_waitcnt lgkmcnt(0)
	s_barrier
	s_setprio 1
	v_mfma_f32_16x16x32_bf16 v[60:63], v[128:131], v[222:225], v[60:63]
	v_mfma_f32_16x16x32_bf16 v[56:59], v[136:139], v[222:225], v[56:59]
	v_mfma_f32_16x16x32_bf16 v[52:55], v[128:131], v[230:233], v[52:55]
	v_mfma_f32_16x16x32_bf16 v[44:47], v[136:139], v[230:233], v[44:47]
	v_mfma_f32_16x16x32_bf16 v[36:39], v[128:131], v[238:241], v[36:39]
	v_mfma_f32_16x16x32_bf16 v[28:31], v[136:139], v[238:241], v[28:31]
	v_mfma_f32_16x16x32_bf16 v[20:23], v[128:131], v[246:249], v[20:23]
	v_mfma_f32_16x16x32_bf16 v[12:15], v[136:139], v[246:249], v[12:15]
	v_mfma_f32_16x16x32_bf16 v[60:63], v[132:135], v[226:229], v[60:63]
	v_mfma_f32_16x16x32_bf16 v[56:59], v[160:163], v[226:229], v[56:59]
	v_mfma_f32_16x16x32_bf16 v[52:55], v[132:135], v[234:237], v[52:55]
	v_mfma_f32_16x16x32_bf16 v[44:47], v[160:163], v[234:237], v[44:47]
	v_mfma_f32_16x16x32_bf16 v[36:39], v[132:135], v[242:245], v[36:39]
	v_mfma_f32_16x16x32_bf16 v[28:31], v[160:163], v[242:245], v[28:31]
	v_mfma_f32_16x16x32_bf16 v[20:23], v[132:135], v[250:253], v[20:23]
	v_mfma_f32_16x16x32_bf16 v[12:15], v[160:163], v[250:253], v[12:15]
	s_setprio 0
	s_setprio 1
	v_mfma_f32_16x16x32_bf16 v[48:51], v[178:181], v[222:225], v[48:51]
	v_mfma_f32_16x16x32_bf16 v[40:43], v[186:189], v[222:225], v[40:43]
	v_mfma_f32_16x16x32_bf16 v[32:35], v[178:181], v[230:233], v[32:35]
	v_mfma_f32_16x16x32_bf16 v[24:27], v[186:189], v[230:233], v[24:27]
	v_mfma_f32_16x16x32_bf16 v[16:19], v[178:181], v[238:241], v[16:19]
	v_mfma_f32_16x16x32_bf16 v[8:11], v[186:189], v[238:241], v[8:11]
	v_mfma_f32_16x16x32_bf16 v[4:7], v[178:181], v[246:249], v[4:7]
	v_mfma_f32_16x16x32_bf16 v[0:3], v[186:189], v[246:249], v[0:3]
	v_mfma_f32_16x16x32_bf16 v[48:51], v[182:185], v[226:229], v[48:51]
	v_mfma_f32_16x16x32_bf16 v[40:43], v[190:193], v[226:229], v[40:43]
	v_mfma_f32_16x16x32_bf16 v[32:35], v[182:185], v[234:237], v[32:35]
	v_mfma_f32_16x16x32_bf16 v[24:27], v[190:193], v[234:237], v[24:27]
	v_mfma_f32_16x16x32_bf16 v[16:19], v[182:185], v[242:245], v[16:19]
	v_mfma_f32_16x16x32_bf16 v[8:11], v[190:193], v[242:245], v[8:11]
	v_mfma_f32_16x16x32_bf16 v[4:7], v[182:185], v[250:253], v[4:7]
	v_mfma_f32_16x16x32_bf16 v[0:3], v[190:193], v[250:253], v[0:3]
	s_barrier
	s_setprio 0
	s_add_i32 s45, s45, 2
	s_add_u32 s26, s26, 0x100
	s_addc_u32 s27, s27, 0
	s_add_u32 s33, s33, 0x100
	s_addc_u32 s44, s44, 0
	s_cmp_gt_u32 s45, 29
	s_cbranch_scc0 .LBB0_955
	s_and_b64 vcc, exec, s[12:13]
	s_cbranch_vccz .LBB0_958
	s_barrier

; #define PG8_STAGE(bufoff, gbase, voff) do { _Pragma("unroll") for (int _i = 0; _i < 2; ++_i) \
;         __builtin_amdgcn_global_load_lds((const unsigned*)((const char*)(gbase) + (voff)[_i]), (PG8_LAS unsigned*)(lds + (bufoff) + ldsw + _i * 8192), 16, 0, 0); } while (0)
; #define PG8_LDA(dst, b, h) do { _Pragma("unroll") for (int m = 0; m < 4; ++m) _Pragma("unroll") for (int k = 0; k < 2; ++k) dst[m][k] = *(const PG8_LAS bf16x8*)(lds + PG8_SA(b, h) + aoff + m * 2048 + k * 1024); } while (0)
; #define PG8_LDB(dst, b, h) do { _Pragma("unroll") for (int n = 0; n < 2; ++n) _Pragma("unroll") for (int k = 0; k < 2; ++k) dst[n][k] = *(const PG8_LAS bf16x8*)(lds + PG8_SB(b, h) + boff + n * 2048 + k * 1024); } while (0)
; #define PG8_MMA(ai, bj, At, Bt) do { __builtin_amdgcn_s_setprio(1); _Pragma("unroll") for (int m = 0; m < 4; ++m) _Pragma("unroll") for (int n = 0; n < 2; ++n) _Pragma("unroll") for (int k = 0; k < 2; ++k) \
;         acc[ai][bj][m][n] = __builtin_amdgcn_mfma_f32_16x16x32_bf16(Bt[n][k], At[m][k], acc[ai][bj][m][n], 0, 0, 0); __builtin_amdgcn_s_setprio(0); } while (0)
; #define PG8_WAIT_V(n) asm volatile("s_waitcnt vmcnt(" #n ")" ::: "memory")
; #define PG8_WAIT_L(n) asm volatile("s_waitcnt lgkmcnt(" #n ")" ::: "memory")
; #define PG8_BAR __builtin_amdgcn_s_barrier()
; #define PG8_SCHED __builtin_amdgcn_sched_barrier(0)
; template <class Epi, class Sched, bool ALIGN_EPI = false, bool SP2 = false>
; __device__ __forceinline__ void gemm_phase(PG8_LAS unsigned char* lds, const Gemm g, const Sched& S, const Epi& E) {
;     ...
;             PG8_LDB(B0, 0, 0); PG8_LDB(B1, 0, 1); PG8_SCHED; PG8_LDA(At, 0, 0); PG8_STAGE(PG8_SA(1, 1), a1 + hstep, voffA);
;             PG8_WAIT_V(8); PG8_WAIT_L(0); PG8_BAR; PG8_MMA(0, 0, At, B0); PG8_MMA(0, 1, At, B1); PG8_BAR; PG8_SCHED;
;             PG8_LDA(At, 0, 1); PG8_STAGE(PG8_SB(0, 0), b2, voffB); PG8_STAGE(PG8_SB(0, 1), b2 + hstep, voffB); PG8_STAGE(PG8_SA(0, 0), a2, voffA);
;             PG8_WAIT_V(8); PG8_WAIT_L(0); PG8_BAR; PG8_MMA(1, 0, At, B0); PG8_MMA(1, 1, At, B1); PG8_BAR; PG8_SCHED;
.LBB0_1180:
	ds_read_b128 v[128:131], v181
	ds_read_b128 v[132:135], v181 offset:1024
	ds_read_b128 v[136:139], v181 offset:2048
	ds_read_b128 v[140:143], v181 offset:3072
	ds_read_b128 v[144:147], v182
	ds_read_b128 v[148:151], v182 offset:1024
	ds_read_b128 v[168:171], v182 offset:2048
	ds_read_b128 v[172:175], v182 offset:3072
	s_add_u32 s28, s26, 0xfff80080
	s_addc_u32 s29, s27, -1
	s_cmp_eq_u32 s49, 28
	s_cselect_b32 s31, s7, s29
	s_cselect_b32 s30, s21, s28
	s_cselect_b32 s29, s19, s48
	s_cselect_b32 s28, s46, s47
	v_lshl_add_u64 v[176:177], s[26:27], 0, v[160:161]
	s_add_i32 m0, s35, 0xc000
	ds_read_b128 v[186:189], v183
	ds_read_b128 v[190:193], v183 offset:1024
	ds_read_b128 v[198:201], v183 offset:2048
	ds_read_b128 v[202:205], v183 offset:3072
	ds_read_b128 v[206:209], v183 offset:4096
	ds_read_b128 v[210:213], v183 offset:5120
	ds_read_b128 v[214:217], v183 offset:6144
	ds_read_b128 v[218:221], v183 offset:7168
	global_load_lds_dwordx4 v[176:177], off
	v_lshl_add_u64 v[176:177], s[26:27], 0, v[162:163]
	s_add_i32 m0, s35, 0xe000
	s_nop 0
	global_load_lds_dwordx4 v[176:177], off
	s_waitcnt vmcnt(8)
	s_waitcnt lgkmcnt(0)
	s_barrier
	s_setprio 1
	v_mfma_f32_16x16x32_bf16 v[124:127], v[128:131], v[186:189], v[124:127]
	v_mfma_f32_16x16x32_bf16 v[120:123], v[136:139], v[186:189], v[120:123]
	v_mfma_f32_16x16x32_bf16 v[104:107], v[128:131], v[198:201], v[104:107]
	v_mfma_f32_16x16x32_bf16 v[108:111], v[136:139], v[198:201], v[108:111]
	v_mfma_f32_16x16x32_bf16 v[88:91], v[128:131], v[206:209], v[88:91]
	v_mfma_f32_16x16x32_bf16 v[92:95], v[136:139], v[206:209], v[92:95]
	v_mfma_f32_16x16x32_bf16 v[72:75], v[128:131], v[214:217], v[72:75]
	v_mfma_f32_16x16x32_bf16 v[76:79], v[136:139], v[214:217], v[76:79]
	v_mfma_f32_16x16x32_bf16 v[124:127], v[132:135], v[190:193], v[124:127]
	v_mfma_f32_16x16x32_bf16 v[120:123], v[140:143], v[190:193], v[120:123]
	v_mfma_f32_16x16x32_bf16 v[104:107], v[132:135], v[202:205], v[104:107]
	v_mfma_f32_16x16x32_bf16 v[108:111], v[140:143], v[202:205], v[108:111]
	v_mfma_f32_16x16x32_bf16 v[88:91], v[132:135], v[210:213], v[88:91]
	v_mfma_f32_16x16x32_bf16 v[92:95], v[140:143], v[210:213], v[92:95]
	v_mfma_f32_16x16x32_bf16 v[72:75], v[132:135], v[218:221], v[72:75]
	v_mfma_f32_16x16x32_bf16 v[76:79], v[140:143], v[218:221], v[76:79]
	s_setprio 0
	s_setprio 1
	v_mfma_f32_16x16x32_bf16 v[116:119], v[144:147], v[186:189], v[116:119]
	v_mfma_f32_16x16x32_bf16 v[112:115], v[168:171], v[186:189], v[112:115]
	v_mfma_f32_16x16x32_bf16 v[100:103], v[144:147], v[198:201], v[100:103]
	v_mfma_f32_16x16x32_bf16 v[96:99], v[168:171], v[198:201], v[96:99]
	v_mfma_f32_16x16x32_bf16 v[84:87], v[144:147], v[206:209], v[84:87]
	v_mfma_f32_16x16x32_bf16 v[80:83], v[168:171], v[206:209], v[80:83]
	v_mfma_f32_16x16x32_bf16 v[68:71], v[144:147], v[214:217], v[68:71]
	v_mfma_f32_16x16x32_bf16 v[64:67], v[168:171], v[214:217], v[64:67]
	v_mfma_f32_16x16x32_bf16 v[116:119], v[148:151], v[190:193], v[116:119]
	v_mfma_f32_16x16x32_bf16 v[112:115], v[172:175], v[190:193], v[112:115]
	v_mfma_f32_16x16x32_bf16 v[100:103], v[148:151], v[202:205], v[100:103]
	v_mfma_f32_16x16x32_bf16 v[96:99], v[172:175], v[202:205], v[96:99]
	v_mfma_f32_16x16x32_bf16 v[84:87], v[148:151], v[210:213], v[84:87]
	v_mfma_f32_16x16x32_bf16 v[80:83], v[172:175], v[210:213], v[80:83]
	v_mfma_f32_16x16x32_bf16 v[68:71], v[148:151], v[218:221], v[68:71]
	v_mfma_f32_16x16x32_bf16 v[64:67], v[172:175], v[218:221], v[64:67]
	s_barrier
	s_setprio 0
	s_add_i32 s50, s43, s34
	v_lshl_add_u64 v[176:177], s[28:29], 0, v[154:155]
	s_mov_b32 m0, s50
	ds_read_b128 v[186:189], v183 offset:16384
	ds_read_b128 v[190:193], v183 offset:17408
	ds_read_b128 v[198:201], v183 offset:18432
	ds_read_b128 v[202:205], v183 offset:19456
	ds_read_b128 v[206:209], v183 offset:20480
	ds_read_b128 v[210:213], v183 offset:21504
	ds_read_b128 v[214:217], v183 offset:22528
	ds_read_b128 v[218:221], v183 offset:23552
	global_load_lds_dwordx4 v[176:177], off
	s_add_i32 m0, s50, 0x2000
	s_add_u32 s50, s28, 0x80000
	v_lshl_add_u64 v[194:195], s[28:29], 0, v[158:159]
	s_addc_u32 s51, s29, 0
	s_add_i32 s52, s44, s34
	global_load_lds_dwordx4 v[194:195], off
	v_lshl_add_u64 v[222:223], s[50:51], 0, v[154:155]
	s_mov_b32 m0, s52
	v_lshl_add_u64 v[224:225], s[30:31], 0, v[156:157]
	global_load_lds_dwordx4 v[222:223], off
	v_lshl_add_u64 v[222:223], s[50:51], 0, v[158:159]
	s_add_i32 m0, s52, 0x2000
	s_nop 0
	global_load_lds_dwordx4 v[222:223], off
	v_lshl_add_u64 v[222:223], s[30:31], 0, v[152:153]
	s_mov_b32 m0, s35
	s_nop 0
	global_load_lds_dwordx4 v[222:223], off
	s_mov_b32 m0, s33
	s_nop 0
	global_load_lds_dwordx4 v[224:225], off
	s_waitcnt vmcnt(8)
	s_waitcnt lgkmcnt(0)
	s_barrier
; #define PG8_STAGE(bufoff, gbase, voff) do { _Pragma("unroll") for (int _i = 0; _i < 2; ++_i) \
;         __builtin_amdgcn_global_load_lds((const unsigned*)((const char*)(gbase) + (voff)[_i]), (PG8_LAS unsigned*)(lds + (bufoff) + ldsw + _i * 8192), 16, 0, 0); } while (0)
; #define PG8_LDA(dst, b, h) do { _Pragma("unroll") for (int m = 0; m < 4; ++m) _Pragma("unroll") for (int k = 0; k < 2; ++k) dst[m][k] = *(const PG8_LAS bf16x8*)(lds + PG8_SA(b, h) + aoff + m * 2048 + k * 1024); } while (0)
; #define PG8_LDB(dst, b, h) do { _Pragma("unroll") for (int n = 0; n < 2; ++n) _Pragma("unroll") for (int k = 0; k < 2; ++k) dst[n][k] = *(const PG8_LAS bf16x8*)(lds + PG8_SB(b, h) + boff + n * 2048 + k * 1024); } while (0)
; #define PG8_MMA(ai, bj, At, Bt) do { __builtin_amdgcn_s_setprio(1); _Pragma("unroll") for (int m = 0; m < 4; ++m) _Pragma("unroll") for (int n = 0; n < 2; ++n) _Pragma("unroll") for (int k = 0; k < 2; ++k) \
;         acc[ai][bj][m][n] = __builtin_amdgcn_mfma_f32_16x16x32_bf16(Bt[n][k], At[m][k], acc[ai][bj][m][n], 0, 0, 0); __builtin_amdgcn_s_setprio(0); } while (0)
; #define PG8_WAIT_V(n) asm volatile("s_waitcnt vmcnt(" #n ")" ::: "memory")
; #define PG8_WAIT_L(n) asm volatile("s_waitcnt lgkmcnt(" #n ")" ::: "memory")
; #define PG8_BAR __builtin_amdgcn_s_barrier()
; #define PG8_SCHED __builtin_amdgcn_sched_barrier(0)
; template <class Epi, class Sched, bool ALIGN_EPI = false, bool SP2 = false>
; __device__ __forceinline__ void gemm_phase(PG8_LAS unsigned char* lds, const Gemm g, const Sched& S, const Epi& E) {
;     ...
;             PG8_WAIT_V(8); PG8_WAIT_L(0); PG8_BAR; PG8_MMA(1, 0, At, B0); PG8_MMA(1, 1, At, B1); PG8_BAR; PG8_SCHED;
;             PG8_LDB(B0, 1, 0); PG8_LDB(B1, 1, 1); PG8_SCHED; PG8_LDA(At, 1, 0); PG8_STAGE(PG8_SA(0, 1), a2 + hstep, voffA);
;             PG8_WAIT_V(8); PG8_WAIT_L(0); PG8_BAR; PG8_MMA(0, 0, At, B0); PG8_MMA(0, 1, At, B1); PG8_BAR; PG8_SCHED;
	s_setprio 1
	v_mfma_f32_16x16x32_bf16 v[56:59], v[128:131], v[186:189], v[56:59]
	v_mfma_f32_16x16x32_bf16 v[60:63], v[136:139], v[186:189], v[60:63]
	v_mfma_f32_16x16x32_bf16 v[40:43], v[128:131], v[198:201], v[40:43]
	v_mfma_f32_16x16x32_bf16 v[44:47], v[136:139], v[198:201], v[44:47]
	v_mfma_f32_16x16x32_bf16 v[24:27], v[128:131], v[206:209], v[24:27]
	v_mfma_f32_16x16x32_bf16 v[28:31], v[136:139], v[206:209], v[28:31]
	v_mfma_f32_16x16x32_bf16 v[8:11], v[128:131], v[214:217], v[8:11]
	v_mfma_f32_16x16x32_bf16 v[12:15], v[136:139], v[214:217], v[12:15]
	v_mfma_f32_16x16x32_bf16 v[56:59], v[132:135], v[190:193], v[56:59]
	v_mfma_f32_16x16x32_bf16 v[60:63], v[140:143], v[190:193], v[60:63]
	v_mfma_f32_16x16x32_bf16 v[40:43], v[132:135], v[202:205], v[40:43]
	v_mfma_f32_16x16x32_bf16 v[44:47], v[140:143], v[202:205], v[44:47]
	v_mfma_f32_16x16x32_bf16 v[24:27], v[132:135], v[210:213], v[24:27]
	v_mfma_f32_16x16x32_bf16 v[28:31], v[140:143], v[210:213], v[28:31]
	v_mfma_f32_16x16x32_bf16 v[8:11], v[132:135], v[218:221], v[8:11]
	v_mfma_f32_16x16x32_bf16 v[12:15], v[140:143], v[218:221], v[12:15]
	s_setprio 0
	s_setprio 1
	v_mfma_f32_16x16x32_bf16 v[52:55], v[144:147], v[186:189], v[52:55]
	v_mfma_f32_16x16x32_bf16 v[48:51], v[168:171], v[186:189], v[48:51]
	v_mfma_f32_16x16x32_bf16 v[36:39], v[144:147], v[198:201], v[36:39]
	v_mfma_f32_16x16x32_bf16 v[32:35], v[168:171], v[198:201], v[32:35]
	v_mfma_f32_16x16x32_bf16 v[20:23], v[144:147], v[206:209], v[20:23]
	v_mfma_f32_16x16x32_bf16 v[16:19], v[168:171], v[206:209], v[16:19]
	v_mfma_f32_16x16x32_bf16 v[4:7], v[144:147], v[214:217], v[4:7]
	v_mfma_f32_16x16x32_bf16 v[0:3], v[168:171], v[214:217], v[0:3]
	v_mfma_f32_16x16x32_bf16 v[52:55], v[148:151], v[190:193], v[52:55]
	v_mfma_f32_16x16x32_bf16 v[48:51], v[172:175], v[190:193], v[48:51]
	v_mfma_f32_16x16x32_bf16 v[36:39], v[148:151], v[202:205], v[36:39]
	v_mfma_f32_16x16x32_bf16 v[32:35], v[172:175], v[202:205], v[32:35]
	v_mfma_f32_16x16x32_bf16 v[20:23], v[148:151], v[210:213], v[20:23]
	v_mfma_f32_16x16x32_bf16 v[16:19], v[172:175], v[210:213], v[16:19]
	v_mfma_f32_16x16x32_bf16 v[4:7], v[148:151], v[218:221], v[4:7]
	v_mfma_f32_16x16x32_bf16 v[0:3], v[172:175], v[218:221], v[0:3]
	s_barrier
	s_setprio 0
	s_add_i32 s50, 0, 0x18000
	s_add_i32 s51, 0, 0x1c000
	v_add_u32_e32 v140, s50, v179
	v_add_u32_e32 v172, s51, v179
	ds_read_b128 v[128:131], v140
	ds_read_b128 v[132:135], v140 offset:1024
	ds_read_b128 v[136:139], v140 offset:2048
	ds_read_b128 v[140:143], v140 offset:3072
	ds_read_b128 v[144:147], v172
	ds_read_b128 v[148:151], v172 offset:1024
	ds_read_b128 v[168:171], v172 offset:2048
	ds_read_b128 v[172:175], v172 offset:3072
	s_add_u32 s30, s30, 0x80000
	s_addc_u32 s31, s31, 0
	s_mov_b32 m0, s36
	v_lshl_add_u64 v[226:227], s[30:31], 0, v[152:153]
	ds_read_b128 v[186:189], v183 offset:32768
	ds_read_b128 v[190:193], v183 offset:33792
	ds_read_b128 v[198:201], v183 offset:34816
	ds_read_b128 v[202:205], v183 offset:35840
	ds_read_b128 v[206:209], v183 offset:36864
	ds_read_b128 v[210:213], v183 offset:37888
	ds_read_b128 v[214:217], v183 offset:38912
	ds_read_b128 v[218:221], v183 offset:39936
	global_load_lds_dwordx4 v[226:227], off
	v_lshl_add_u64 v[226:227], s[30:31], 0, v[156:157]
	s_mov_b32 m0, s37
	s_nop 0
	global_load_lds_dwordx4 v[226:227], off
	s_waitcnt vmcnt(8)
	s_waitcnt lgkmcnt(0)
	s_barrier
	s_setprio 1
	v_mfma_f32_16x16x32_bf16 v[124:127], v[128:131], v[186:189], v[124:127]
	v_mfma_f32_16x16x32_bf16 v[120:123], v[136:139], v[186:189], v[120:123]
	v_mfma_f32_16x16x32_bf16 v[104:107], v[128:131], v[198:201], v[104:107]
	v_mfma_f32_16x16x32_bf16 v[108:111], v[136:139], v[198:201], v[108:111]
	v_mfma_f32_16x16x32_bf16 v[88:91], v[128:131], v[206:209], v[88:91]
	v_mfma_f32_16x16x32_bf16 v[92:95], v[136:139], v[206:209], v[92:95]
	v_mfma_f32_16x16x32_bf16 v[72:75], v[128:131], v[214:217], v[72:75]
	v_mfma_f32_16x16x32_bf16 v[76:79], v[136:139], v[214:217], v[76:79]
	v_mfma_f32_16x16x32_bf16 v[124:127], v[132:135], v[190:193], v[124:127]
	v_mfma_f32_16x16x32_bf16 v[120:123], v[140:143], v[190:193], v[120:123]
	v_mfma_f32_16x16x32_bf16 v[104:107], v[132:135], v[202:205], v[104:107]
	v_mfma_f32_16x16x32_bf16 v[108:111], v[140:143], v[202:205], v[108:111]
	v_mfma_f32_16x16x32_bf16 v[88:91], v[132:135], v[210:213], v[88:91]
	v_mfma_f32_16x16x32_bf16 v[92:95], v[140:143], v[210:213], v[92:95]
	v_mfma_f32_16x16x32_bf16 v[72:75], v[132:135], v[218:221], v[72:75]
	v_mfma_f32_16x16x32_bf16 v[76:79], v[140:143], v[218:221], v[76:79]
	s_setprio 0
	s_setprio 1
	v_mfma_f32_16x16x32_bf16 v[116:119], v[144:147], v[186:189], v[116:119]
	v_mfma_f32_16x16x32_bf16 v[112:115], v[168:171], v[186:189], v[112:115]
	v_mfma_f32_16x16x32_bf16 v[100:103], v[144:147], v[198:201], v[100:103]
	v_mfma_f32_16x16x32_bf16 v[96:99], v[168:171], v[198:201], v[96:99]
	v_mfma_f32_16x16x32_bf16 v[84:87], v[144:147], v[206:209], v[84:87]
	v_mfma_f32_16x16x32_bf16 v[80:83], v[168:171], v[206:209], v[80:83]
	v_mfma_f32_16x16x32_bf16 v[68:71], v[144:147], v[214:217], v[68:71]
	v_mfma_f32_16x16x32_bf16 v[64:67], v[168:171], v[214:217], v[64:67]
	v_mfma_f32_16x16x32_bf16 v[116:119], v[148:151], v[190:193], v[116:119]
	v_mfma_f32_16x16x32_bf16 v[112:115], v[172:175], v[190:193], v[112:115]
	v_mfma_f32_16x16x32_bf16 v[100:103], v[148:151], v[202:205], v[100:103]
	v_mfma_f32_16x16x32_bf16 v[96:99], v[172:175], v[202:205], v[96:99]
	v_mfma_f32_16x16x32_bf16 v[84:87], v[148:151], v[210:213], v[84:87]
	v_mfma_f32_16x16x32_bf16 v[80:83], v[172:175], v[210:213], v[80:83]
	v_mfma_f32_16x16x32_bf16 v[68:71], v[148:151], v[218:221], v[68:71]
	v_mfma_f32_16x16x32_bf16 v[64:67], v[172:175], v[218:221], v[64:67]
	s_barrier
; #define PG8_STAGE(bufoff, gbase, voff) do { _Pragma("unroll") for (int _i = 0; _i < 2; ++_i) \
;         __builtin_amdgcn_global_load_lds((const unsigned*)((const char*)(gbase) + (voff)[_i]), (PG8_LAS unsigned*)(lds + (bufoff) + ldsw + _i * 8192), 16, 0, 0); } while (0)
; #define PG8_LDA(dst, b, h) do { _Pragma("unroll") for (int m = 0; m < 4; ++m) _Pragma("unroll") for (int k = 0; k < 2; ++k) dst[m][k] = *(const PG8_LAS bf16x8*)(lds + PG8_SA(b, h) + aoff + m * 2048 + k * 1024); } while (0)
; #define PG8_MMA(ai, bj, At, Bt) do { __builtin_amdgcn_s_setprio(1); _Pragma("unroll") for (int m = 0; m < 4; ++m) _Pragma("unroll") for (int n = 0; n < 2; ++n) _Pragma("unroll") for (int k = 0; k < 2; ++k) \
;         acc[ai][bj][m][n] = __builtin_amdgcn_mfma_f32_16x16x32_bf16(Bt[n][k], At[m][k], acc[ai][bj][m][n], 0, 0, 0); __builtin_amdgcn_s_setprio(0); } while (0)
; #define PG8_WAIT_V(n) asm volatile("s_waitcnt vmcnt(" #n ")" ::: "memory")
; #define PG8_WAIT_L(n) asm volatile("s_waitcnt lgkmcnt(" #n ")" ::: "memory")
; #define PG8_BAR __builtin_amdgcn_s_barrier()
; #define PG8_SCHED __builtin_amdgcn_sched_barrier(0)
; template <class Epi, class Sched, bool ALIGN_EPI = false, bool SP2 = false>
; __device__ __forceinline__ void gemm_phase(PG8_LAS unsigned char* lds, const Gemm g, const Sched& S, const Epi& E) {
;     ...
;             PG8_WAIT_V(8); PG8_WAIT_L(0); PG8_BAR; PG8_MMA(0, 0, At, B0); PG8_MMA(0, 1, At, B1); PG8_BAR; PG8_SCHED;
;             PG8_LDA(At, 1, 1); PG8_STAGE(PG8_SB(1, 0), b3, voffB); PG8_STAGE(PG8_SB(1, 1), b3 + hstep, voffB); PG8_STAGE(PG8_SA(1, 0), a3, voffA);
;             PG8_WAIT_V(8); PG8_WAIT_L(0); PG8_BAR; PG8_MMA(1, 0, At, B0); PG8_MMA(1, 1, At, B1); PG8_BAR; PG8_SCHED;
	s_setprio 0
	s_add_i32 s30, s50, s34
	v_lshl_add_u64 v[176:177], v[176:177], 0, s[12:13]
	s_mov_b32 m0, s30
	ds_read_b128 v[186:189], v183 offset:49152
	ds_read_b128 v[190:193], v183 offset:50176
	ds_read_b128 v[198:201], v183 offset:51200
	ds_read_b128 v[202:205], v183 offset:52224
	ds_read_b128 v[206:209], v183 offset:53248
	ds_read_b128 v[210:213], v183 offset:54272
	ds_read_b128 v[214:217], v183 offset:55296
	ds_read_b128 v[218:221], v183 offset:56320
	global_load_lds_dwordx4 v[176:177], off
	s_add_i32 m0, s30, 0x2000
	s_add_u32 s28, s28, 0x80080
	v_lshl_add_u64 v[176:177], v[194:195], 0, s[12:13]
	s_addc_u32 s29, s29, 0
	s_add_i32 s30, s51, s34
	global_load_lds_dwordx4 v[176:177], off
	v_lshl_add_u64 v[176:177], s[28:29], 0, v[154:155]
	s_mov_b32 m0, s30
	s_nop 0
	global_load_lds_dwordx4 v[176:177], off
	v_lshl_add_u64 v[176:177], s[28:29], 0, v[158:159]
	s_add_i32 m0, s30, 0x2000
	s_nop 0
	global_load_lds_dwordx4 v[176:177], off
	v_lshl_add_u64 v[176:177], v[222:223], 0, s[12:13]
	s_mov_b32 m0, s39
	s_nop 0
	global_load_lds_dwordx4 v[176:177], off
	v_lshl_add_u64 v[176:177], v[224:225], 0, s[12:13]
	s_mov_b32 m0, s40
	s_nop 0
	global_load_lds_dwordx4 v[176:177], off
	s_waitcnt vmcnt(8)
	s_waitcnt lgkmcnt(0)
	s_barrier
	s_setprio 1
	v_mfma_f32_16x16x32_bf16 v[56:59], v[128:131], v[186:189], v[56:59]
	v_mfma_f32_16x16x32_bf16 v[60:63], v[136:139], v[186:189], v[60:63]
	v_mfma_f32_16x16x32_bf16 v[40:43], v[128:131], v[198:201], v[40:43]
	v_mfma_f32_16x16x32_bf16 v[44:47], v[136:139], v[198:201], v[44:47]
	v_mfma_f32_16x16x32_bf16 v[24:27], v[128:131], v[206:209], v[24:27]
	v_mfma_f32_16x16x32_bf16 v[28:31], v[136:139], v[206:209], v[28:31]
	v_mfma_f32_16x16x32_bf16 v[8:11], v[128:131], v[214:217], v[8:11]
	v_mfma_f32_16x16x32_bf16 v[12:15], v[136:139], v[214:217], v[12:15]
	v_mfma_f32_16x16x32_bf16 v[56:59], v[132:135], v[190:193], v[56:59]
	v_mfma_f32_16x16x32_bf16 v[60:63], v[140:143], v[190:193], v[60:63]
	v_mfma_f32_16x16x32_bf16 v[40:43], v[132:135], v[202:205], v[40:43]
	v_mfma_f32_16x16x32_bf16 v[44:47], v[140:143], v[202:205], v[44:47]
	v_mfma_f32_16x16x32_bf16 v[24:27], v[132:135], v[210:213], v[24:27]
	v_mfma_f32_16x16x32_bf16 v[28:31], v[140:143], v[210:213], v[28:31]
	v_mfma_f32_16x16x32_bf16 v[8:11], v[132:135], v[218:221], v[8:11]
	v_mfma_f32_16x16x32_bf16 v[12:15], v[140:143], v[218:221], v[12:15]
	s_setprio 0
	s_setprio 1
	v_mfma_f32_16x16x32_bf16 v[52:55], v[144:147], v[186:189], v[52:55]
	v_mfma_f32_16x16x32_bf16 v[48:51], v[168:171], v[186:189], v[48:51]
	v_mfma_f32_16x16x32_bf16 v[36:39], v[144:147], v[198:201], v[36:39]
	v_mfma_f32_16x16x32_bf16 v[32:35], v[168:171], v[198:201], v[32:35]
	v_mfma_f32_16x16x32_bf16 v[20:23], v[144:147], v[206:209], v[20:23]
	v_mfma_f32_16x16x32_bf16 v[16:19], v[168:171], v[206:209], v[16:19]
	v_mfma_f32_16x16x32_bf16 v[4:7], v[144:147], v[214:217], v[4:7]
	v_mfma_f32_16x16x32_bf16 v[0:3], v[168:171], v[214:217], v[0:3]
	v_mfma_f32_16x16x32_bf16 v[52:55], v[148:151], v[190:193], v[52:55]
	v_mfma_f32_16x16x32_bf16 v[48:51], v[172:175], v[190:193], v[48:51]
	v_mfma_f32_16x16x32_bf16 v[36:39], v[148:151], v[202:205], v[36:39]
	v_mfma_f32_16x16x32_bf16 v[32:35], v[172:175], v[202:205], v[32:35]
	v_mfma_f32_16x16x32_bf16 v[20:23], v[148:151], v[210:213], v[20:23]
	v_mfma_f32_16x16x32_bf16 v[16:19], v[172:175], v[210:213], v[16:19]
	v_mfma_f32_16x16x32_bf16 v[4:7], v[148:151], v[218:221], v[4:7]
	v_mfma_f32_16x16x32_bf16 v[0:3], v[172:175], v[218:221], v[0:3]
	s_barrier
	s_setprio 0
	s_add_i32 s49, s49, 2
	s_add_u32 s26, s26, 0x100
	s_addc_u32 s27, s27, 0
	s_add_u32 s47, s47, 0x100
	s_addc_u32 s48, s48, 0
	s_cmp_gt_u32 s49, 29
	s_cbranch_scc0 .LBB0_1180
	s_and_b64 vcc, exec, s[14:15]
	s_cbranch_vccz .LBB0_1183
	s_barrier

; #define PG8_STAGE(bufoff, gbase, voff) do { _Pragma("unroll") for (int _i = 0; _i < 2; ++_i) \
;         __builtin_amdgcn_global_load_lds((const unsigned*)((const char*)(gbase) + (voff)[_i]), (PG8_LAS unsigned*)(lds + (bufoff) + ldsw + _i * 8192), 16, 0, 0); } while (0)
; #define PG8_LDA(dst, b, h) do { _Pragma("unroll") for (int m = 0; m < 4; ++m) _Pragma("unroll") for (int k = 0; k < 2; ++k) dst[m][k] = *(const PG8_LAS bf16x8*)(lds + PG8_SA(b, h) + aoff + m * 2048 + k * 1024); } while (0)
; #define PG8_LDB(dst, b, h) do { _Pragma("unroll") for (int n = 0; n < 2; ++n) _Pragma("unroll") for (int k = 0; k < 2; ++k) dst[n][k] = *(const PG8_LAS bf16x8*)(lds + PG8_SB(b, h) + boff + n * 2048 + k * 1024); } while (0)
; #define PG8_MMA(ai, bj, At, Bt) do { __builtin_amdgcn_s_setprio(1); _Pragma("unroll") for (int m = 0; m < 4; ++m) _Pragma("unroll") for (int n = 0; n < 2; ++n) _Pragma("unroll") for (int k = 0; k < 2; ++k) \
;         acc[ai][bj][m][n] = __builtin_amdgcn_mfma_f32_16x16x32_bf16(Bt[n][k], At[m][k], acc[ai][bj][m][n], 0, 0, 0); __builtin_amdgcn_s_setprio(0); } while (0)
; #define PG8_WAIT_V(n) asm volatile("s_waitcnt vmcnt(" #n ")" ::: "memory")
; #define PG8_WAIT_L(n) asm volatile("s_waitcnt lgkmcnt(" #n ")" ::: "memory")
; template <class Epi, class Sched, bool ALIGN_EPI = false, bool SP2 = false>
; __device__ __forceinline__ void gemm_phase(PG8_LAS unsigned char* lds, const Gemm g, const Sched& S, const Epi& E) {
;     ...
;             const bool last = (t == nt - 2);
;             const char* a1 = cA + (size_t)(t + 1) * kstep;
;             const char* a2 = last ? nA : cA + (size_t)(t + 2) * kstep; const char* b2 = last ? nB : cB + (size_t)(t + 2) * kstep;
;             const char* a3 = a2 + kstep; const char* b3 = b2 + kstep;
;             if (last && has_next) S.a_ready(nxt);
;             if constexpr (SP2) {
;             PG8_LDB(B0, 0, 0); PG8_LDB(B1, 0, 1); PG8_SCHED; PG8_LDA(At, 0, 0); PG8_STAGE(PG8_SA(1, 1), a1 + hstep, voffA);
;             PG8_WAIT_V(8); PG8_WAIT_L(0); PG8_BAR; PG8_MMA(0, 0, At, B0); PG8_MMA(0, 1, At, B1); PG8_BAR; PG8_SCHED;
;             PG8_LDA(At, 0, 1); PG8_STAGE(PG8_SB(0, 0), b2, voffB); PG8_STAGE(PG8_SB(0, 1), b2 + hstep, voffB); PG8_STAGE(PG8_SA(0, 0), a2, voffA);
;             PG8_WAIT_V(8); PG8_WAIT_L(0); PG8_BAR; PG8_MMA(1, 0, At, B0); PG8_MMA(1, 1, At, B1); PG8_BAR; PG8_SCHED;
.LBB0_1373:
	ds_read_b128 v[108:111], v173
	ds_read_b128 v[112:115], v173 offset:1024
	ds_read_b128 v[116:119], v173 offset:2048
	ds_read_b128 v[120:123], v173 offset:3072
	ds_read_b128 v[178:181], v175
	ds_read_b128 v[182:185], v175 offset:1024
	ds_read_b128 v[186:189], v175 offset:2048
	ds_read_b128 v[190:193], v175 offset:3072
	s_add_u32 s42, s8, 0xfff80080
	s_addc_u32 s43, s9, -1
	s_cmp_eq_u32 s66, 28
	s_cselect_b32 s45, s29, s43
	s_cselect_b32 s44, s39, s42
	s_cselect_b32 s43, s27, s49
	s_cselect_b32 s42, s41, s48
	v_lshl_add_u64 v[160:161], s[8:9], 0, v[154:155]
	s_add_i32 m0, s50, 0xc000
	ds_read_b128 v[198:201], v177
	ds_read_b128 v[202:205], v177 offset:1024
	ds_read_b128 v[206:209], v177 offset:2048
	ds_read_b128 v[210:213], v177 offset:3072
	ds_read_b128 v[214:217], v177 offset:4096
	ds_read_b128 v[218:221], v177 offset:5120
	ds_read_b128 v[222:225], v177 offset:6144
	ds_read_b128 v[226:229], v177 offset:7168
	global_load_lds_dwordx4 v[160:161], off
	v_lshl_add_u64 v[160:161], s[8:9], 0, v[156:157]
	s_add_i32 m0, s50, 0xe000
	s_nop 0
	global_load_lds_dwordx4 v[160:161], off
	s_waitcnt vmcnt(8)
	s_waitcnt lgkmcnt(0)
	s_barrier
	s_setprio 1
	v_mfma_f32_16x16x32_bf16 v[140:143], v[108:111], v[198:201], v[140:143]
	v_mfma_f32_16x16x32_bf16 v[136:139], v[116:119], v[198:201], v[136:139]
	v_mfma_f32_16x16x32_bf16 v[100:103], v[108:111], v[206:209], v[100:103]
	v_mfma_f32_16x16x32_bf16 v[124:127], v[116:119], v[206:209], v[124:127]
	v_mfma_f32_16x16x32_bf16 v[84:87], v[108:111], v[214:217], v[84:87]
	v_mfma_f32_16x16x32_bf16 v[92:95], v[116:119], v[214:217], v[92:95]
	v_mfma_f32_16x16x32_bf16 v[68:71], v[108:111], v[222:225], v[68:71]
	v_mfma_f32_16x16x32_bf16 v[76:79], v[116:119], v[222:225], v[76:79]
	v_mfma_f32_16x16x32_bf16 v[140:143], v[112:115], v[202:205], v[140:143]
	v_mfma_f32_16x16x32_bf16 v[136:139], v[120:123], v[202:205], v[136:139]
	v_mfma_f32_16x16x32_bf16 v[100:103], v[112:115], v[210:213], v[100:103]
	v_mfma_f32_16x16x32_bf16 v[124:127], v[120:123], v[210:213], v[124:127]
	v_mfma_f32_16x16x32_bf16 v[84:87], v[112:115], v[218:221], v[84:87]
	v_mfma_f32_16x16x32_bf16 v[92:95], v[120:123], v[218:221], v[92:95]
	v_mfma_f32_16x16x32_bf16 v[68:71], v[112:115], v[226:229], v[68:71]
	v_mfma_f32_16x16x32_bf16 v[76:79], v[120:123], v[226:229], v[76:79]
	s_setprio 0
	s_setprio 1
	v_mfma_f32_16x16x32_bf16 v[128:131], v[178:181], v[198:201], v[128:131]
	v_mfma_f32_16x16x32_bf16 v[132:135], v[186:189], v[198:201], v[132:135]
	v_mfma_f32_16x16x32_bf16 v[104:107], v[178:181], v[206:209], v[104:107]
	v_mfma_f32_16x16x32_bf16 v[96:99], v[186:189], v[206:209], v[96:99]
	v_mfma_f32_16x16x32_bf16 v[88:91], v[178:181], v[214:217], v[88:91]
	v_mfma_f32_16x16x32_bf16 v[80:83], v[186:189], v[214:217], v[80:83]
	v_mfma_f32_16x16x32_bf16 v[72:75], v[178:181], v[222:225], v[72:75]
	v_mfma_f32_16x16x32_bf16 v[64:67], v[186:189], v[222:225], v[64:67]
	v_mfma_f32_16x16x32_bf16 v[128:131], v[182:185], v[202:205], v[128:131]
	v_mfma_f32_16x16x32_bf16 v[132:135], v[190:193], v[202:205], v[132:135]
	v_mfma_f32_16x16x32_bf16 v[104:107], v[182:185], v[210:213], v[104:107]
	v_mfma_f32_16x16x32_bf16 v[96:99], v[190:193], v[210:213], v[96:99]
	v_mfma_f32_16x16x32_bf16 v[88:91], v[182:185], v[218:221], v[88:91]
	v_mfma_f32_16x16x32_bf16 v[80:83], v[190:193], v[218:221], v[80:83]
	v_mfma_f32_16x16x32_bf16 v[72:75], v[182:185], v[226:229], v[72:75]
	v_mfma_f32_16x16x32_bf16 v[64:67], v[190:193], v[226:229], v[64:67]
	s_barrier
	s_setprio 0
	s_add_i32 s67, s62, s47
	v_lshl_add_u64 v[160:161], s[42:43], 0, v[144:145]
	s_mov_b32 m0, s67
	ds_read_b128 v[198:201], v177 offset:16384
	ds_read_b128 v[202:205], v177 offset:17408
	ds_read_b128 v[206:209], v177 offset:18432
	ds_read_b128 v[210:213], v177 offset:19456
	ds_read_b128 v[214:217], v177 offset:20480
	ds_read_b128 v[218:221], v177 offset:21504
	ds_read_b128 v[222:225], v177 offset:22528
	ds_read_b128 v[226:229], v177 offset:23552
	global_load_lds_dwordx4 v[160:161], off
	s_add_i32 m0, s67, 0x2000
	s_add_u32 s68, s42, 0x80000
	v_lshl_add_u64 v[164:165], s[42:43], 0, v[146:147]
	s_addc_u32 s69, s43, 0
	s_add_i32 s67, s63, s47
	global_load_lds_dwordx4 v[164:165], off
	v_lshl_add_u64 v[170:171], s[68:69], 0, v[144:145]
	s_mov_b32 m0, s67
	v_lshl_add_u64 v[194:195], s[44:45], 0, v[146:147]
	global_load_lds_dwordx4 v[170:171], off
	v_lshl_add_u64 v[170:171], s[68:69], 0, v[146:147]
	s_add_i32 m0, s67, 0x2000
	s_nop 0
	global_load_lds_dwordx4 v[170:171], off
	v_lshl_add_u64 v[170:171], s[44:45], 0, v[144:145]
	s_mov_b32 m0, s50
	s_nop 0
	global_load_lds_dwordx4 v[170:171], off
	s_mov_b32 m0, s51
	s_nop 0
	global_load_lds_dwordx4 v[194:195], off
	s_waitcnt vmcnt(8)
	s_waitcnt lgkmcnt(0)
	s_barrier
; #define PG8_STAGE(bufoff, gbase, voff) do { _Pragma("unroll") for (int _i = 0; _i < 2; ++_i) \
;         __builtin_amdgcn_global_load_lds((const unsigned*)((const char*)(gbase) + (voff)[_i]), (PG8_LAS unsigned*)(lds + (bufoff) + ldsw + _i * 8192), 16, 0, 0); } while (0)
; #define PG8_LDA(dst, b, h) do { _Pragma("unroll") for (int m = 0; m < 4; ++m) _Pragma("unroll") for (int k = 0; k < 2; ++k) dst[m][k] = *(const PG8_LAS bf16x8*)(lds + PG8_SA(b, h) + aoff + m * 2048 + k * 1024); } while (0)
; #define PG8_LDB(dst, b, h) do { _Pragma("unroll") for (int n = 0; n < 2; ++n) _Pragma("unroll") for (int k = 0; k < 2; ++k) dst[n][k] = *(const PG8_LAS bf16x8*)(lds + PG8_SB(b, h) + boff + n * 2048 + k * 1024); } while (0)
; #define PG8_MMA(ai, bj, At, Bt) do { __builtin_amdgcn_s_setprio(1); _Pragma("unroll") for (int m = 0; m < 4; ++m) _Pragma("unroll") for (int n = 0; n < 2; ++n) _Pragma("unroll") for (int k = 0; k < 2; ++k) \
;         acc[ai][bj][m][n] = __builtin_amdgcn_mfma_f32_16x16x32_bf16(Bt[n][k], At[m][k], acc[ai][bj][m][n], 0, 0, 0); __builtin_amdgcn_s_setprio(0); } while (0)
; #define PG8_WAIT_V(n) asm volatile("s_waitcnt vmcnt(" #n ")" ::: "memory")
; #define PG8_WAIT_L(n) asm volatile("s_waitcnt lgkmcnt(" #n ")" ::: "memory")
; #define PG8_BAR __builtin_amdgcn_s_barrier()
; #define PG8_SCHED __builtin_amdgcn_sched_barrier(0)
; template <class Epi, class Sched, bool ALIGN_EPI = false, bool SP2 = false>
; __device__ __forceinline__ void gemm_phase(PG8_LAS unsigned char* lds, const Gemm g, const Sched& S, const Epi& E) {
;     ...
;             PG8_WAIT_V(8); PG8_WAIT_L(0); PG8_BAR; PG8_MMA(1, 0, At, B0); PG8_MMA(1, 1, At, B1); PG8_BAR; PG8_SCHED;
;             PG8_LDB(B0, 1, 0); PG8_LDB(B1, 1, 1); PG8_SCHED; PG8_LDA(At, 1, 0); PG8_STAGE(PG8_SA(0, 1), a2 + hstep, voffA);
;             PG8_WAIT_V(8); PG8_WAIT_L(0); PG8_BAR; PG8_MMA(0, 0, At, B0); PG8_MMA(0, 1, At, B1); PG8_BAR; PG8_SCHED;
;             PG8_LDA(At, 1, 1); PG8_STAGE(PG8_SB(1, 0), b3, voffB); PG8_STAGE(PG8_SB(1, 1), b3 + hstep, voffB); PG8_STAGE(PG8_SA(1, 0), a3, voffA);
;             PG8_WAIT_V(8); PG8_WAIT_L(0); PG8_BAR; PG8_MMA(1, 0, At, B0); PG8_MMA(1, 1, At, B1); PG8_BAR; PG8_SCHED;
	s_setprio 1
	v_mfma_f32_16x16x32_bf16 v[60:63], v[108:111], v[198:201], v[60:63]
	v_mfma_f32_16x16x32_bf16 v[56:59], v[116:119], v[198:201], v[56:59]
	v_mfma_f32_16x16x32_bf16 v[36:39], v[108:111], v[206:209], v[36:39]
	v_mfma_f32_16x16x32_bf16 v[44:47], v[116:119], v[206:209], v[44:47]
	v_mfma_f32_16x16x32_bf16 v[20:23], v[108:111], v[214:217], v[20:23]
	v_mfma_f32_16x16x32_bf16 v[28:31], v[116:119], v[214:217], v[28:31]
	v_mfma_f32_16x16x32_bf16 v[4:7], v[108:111], v[222:225], v[4:7]
	v_mfma_f32_16x16x32_bf16 v[12:15], v[116:119], v[222:225], v[12:15]
	v_mfma_f32_16x16x32_bf16 v[60:63], v[112:115], v[202:205], v[60:63]
	v_mfma_f32_16x16x32_bf16 v[56:59], v[120:123], v[202:205], v[56:59]
	v_mfma_f32_16x16x32_bf16 v[36:39], v[112:115], v[210:213], v[36:39]
	v_mfma_f32_16x16x32_bf16 v[44:47], v[120:123], v[210:213], v[44:47]
	v_mfma_f32_16x16x32_bf16 v[20:23], v[112:115], v[218:221], v[20:23]
	v_mfma_f32_16x16x32_bf16 v[28:31], v[120:123], v[218:221], v[28:31]
	v_mfma_f32_16x16x32_bf16 v[4:7], v[112:115], v[226:229], v[4:7]
	v_mfma_f32_16x16x32_bf16 v[12:15], v[120:123], v[226:229], v[12:15]
	s_setprio 0
	s_setprio 1
	v_mfma_f32_16x16x32_bf16 v[48:51], v[178:181], v[198:201], v[48:51]
	v_mfma_f32_16x16x32_bf16 v[52:55], v[186:189], v[198:201], v[52:55]
	v_mfma_f32_16x16x32_bf16 v[40:43], v[178:181], v[206:209], v[40:43]
	v_mfma_f32_16x16x32_bf16 v[32:35], v[186:189], v[206:209], v[32:35]
	v_mfma_f32_16x16x32_bf16 v[24:27], v[178:181], v[214:217], v[24:27]
	v_mfma_f32_16x16x32_bf16 v[16:19], v[186:189], v[214:217], v[16:19]
	v_mfma_f32_16x16x32_bf16 v[8:11], v[178:181], v[222:225], v[8:11]
	v_mfma_f32_16x16x32_bf16 v[0:3], v[186:189], v[222:225], v[0:3]
	v_mfma_f32_16x16x32_bf16 v[48:51], v[182:185], v[202:205], v[48:51]
	v_mfma_f32_16x16x32_bf16 v[52:55], v[190:193], v[202:205], v[52:55]
	v_mfma_f32_16x16x32_bf16 v[40:43], v[182:185], v[210:213], v[40:43]
	v_mfma_f32_16x16x32_bf16 v[32:35], v[190:193], v[210:213], v[32:35]
	v_mfma_f32_16x16x32_bf16 v[24:27], v[182:185], v[218:221], v[24:27]
	v_mfma_f32_16x16x32_bf16 v[16:19], v[190:193], v[218:221], v[16:19]
	v_mfma_f32_16x16x32_bf16 v[8:11], v[182:185], v[226:229], v[8:11]
	v_mfma_f32_16x16x32_bf16 v[0:3], v[190:193], v[226:229], v[0:3]
	s_barrier
	s_setprio 0
	s_add_i32 s67, 0, 0x18000
	s_add_i32 s68, 0, 0x1c000
	v_add_u32_e32 v120, s67, v167
	v_add_u32_e32 v162, s68, v167
	ds_read_b128 v[108:111], v120
	ds_read_b128 v[112:115], v120 offset:1024
	ds_read_b128 v[116:119], v120 offset:2048
	ds_read_b128 v[120:123], v120 offset:3072
	ds_read_b128 v[178:181], v162
	ds_read_b128 v[182:185], v162 offset:1024
	ds_read_b128 v[186:189], v162 offset:2048
	ds_read_b128 v[190:193], v162 offset:3072
	s_add_u32 s44, s44, 0x80000
	s_addc_u32 s45, s45, 0
	s_mov_b32 m0, s52
	v_lshl_add_u64 v[230:231], s[44:45], 0, v[144:145]
	ds_read_b128 v[198:201], v177 offset:32768
	ds_read_b128 v[202:205], v177 offset:33792
	ds_read_b128 v[206:209], v177 offset:34816
	ds_read_b128 v[210:213], v177 offset:35840
	ds_read_b128 v[214:217], v177 offset:36864
	ds_read_b128 v[218:221], v177 offset:37888
	ds_read_b128 v[222:225], v177 offset:38912
	ds_read_b128 v[226:229], v177 offset:39936
	global_load_lds_dwordx4 v[230:231], off
	v_lshl_add_u64 v[230:231], s[44:45], 0, v[146:147]
	s_mov_b32 m0, s53
	s_nop 0
	global_load_lds_dwordx4 v[230:231], off
	s_waitcnt vmcnt(8)
	s_waitcnt lgkmcnt(0)
	s_barrier
	s_setprio 1
	v_mfma_f32_16x16x32_bf16 v[140:143], v[108:111], v[198:201], v[140:143]
	v_mfma_f32_16x16x32_bf16 v[136:139], v[116:119], v[198:201], v[136:139]
	v_mfma_f32_16x16x32_bf16 v[100:103], v[108:111], v[206:209], v[100:103]
	v_mfma_f32_16x16x32_bf16 v[124:127], v[116:119], v[206:209], v[124:127]
	v_mfma_f32_16x16x32_bf16 v[84:87], v[108:111], v[214:217], v[84:87]
	v_mfma_f32_16x16x32_bf16 v[92:95], v[116:119], v[214:217], v[92:95]
	v_mfma_f32_16x16x32_bf16 v[68:71], v[108:111], v[222:225], v[68:71]
	v_mfma_f32_16x16x32_bf16 v[76:79], v[116:119], v[222:225], v[76:79]
	v_mfma_f32_16x16x32_bf16 v[140:143], v[112:115], v[202:205], v[140:143]
	v_mfma_f32_16x16x32_bf16 v[136:139], v[120:123], v[202:205], v[136:139]
	v_mfma_f32_16x16x32_bf16 v[100:103], v[112:115], v[210:213], v[100:103]
	v_mfma_f32_16x16x32_bf16 v[124:127], v[120:123], v[210:213], v[124:127]
	v_mfma_f32_16x16x32_bf16 v[84:87], v[112:115], v[218:221], v[84:87]
	v_mfma_f32_16x16x32_bf16 v[92:95], v[120:123], v[218:221], v[92:95]
	v_mfma_f32_16x16x32_bf16 v[68:71], v[112:115], v[226:229], v[68:71]
	v_mfma_f32_16x16x32_bf16 v[76:79], v[120:123], v[226:229], v[76:79]
	s_setprio 0
	s_setprio 1
	v_mfma_f32_16x16x32_bf16 v[128:131], v[178:181], v[198:201], v[128:131]
	v_mfma_f32_16x16x32_bf16 v[132:135], v[186:189], v[198:201], v[132:135]
	v_mfma_f32_16x16x32_bf16 v[104:107], v[178:181], v[206:209], v[104:107]
	v_mfma_f32_16x16x32_bf16 v[96:99], v[186:189], v[206:209], v[96:99]
	v_mfma_f32_16x16x32_bf16 v[88:91], v[178:181], v[214:217], v[88:91]
	v_mfma_f32_16x16x32_bf16 v[80:83], v[186:189], v[214:217], v[80:83]
	v_mfma_f32_16x16x32_bf16 v[72:75], v[178:181], v[222:225], v[72:75]
	v_mfma_f32_16x16x32_bf16 v[64:67], v[186:189], v[222:225], v[64:67]
	v_mfma_f32_16x16x32_bf16 v[128:131], v[182:185], v[202:205], v[128:131]
	v_mfma_f32_16x16x32_bf16 v[132:135], v[190:193], v[202:205], v[132:135]
	v_mfma_f32_16x16x32_bf16 v[104:107], v[182:185], v[210:213], v[104:107]
	v_mfma_f32_16x16x32_bf16 v[96:99], v[190:193], v[210:213], v[96:99]
	v_mfma_f32_16x16x32_bf16 v[88:91], v[182:185], v[218:221], v[88:91]
	v_mfma_f32_16x16x32_bf16 v[80:83], v[190:193], v[218:221], v[80:83]
	v_mfma_f32_16x16x32_bf16 v[72:75], v[182:185], v[226:229], v[72:75]
	v_mfma_f32_16x16x32_bf16 v[64:67], v[190:193], v[226:229], v[64:67]
	s_barrier
; #define PG8_STAGE(bufoff, gbase, voff) do { _Pragma("unroll") for (int _i = 0; _i < 2; ++_i) \
;         __builtin_amdgcn_global_load_lds((const unsigned*)((const char*)(gbase) + (voff)[_i]), (PG8_LAS unsigned*)(lds + (bufoff) + ldsw + _i * 8192), 16, 0, 0); } while (0)
; #define PG8_LDA(dst, b, h) do { _Pragma("unroll") for (int m = 0; m < 4; ++m) _Pragma("unroll") for (int k = 0; k < 2; ++k) dst[m][k] = *(const PG8_LAS bf16x8*)(lds + PG8_SA(b, h) + aoff + m * 2048 + k * 1024); } while (0)
; #define PG8_MMA(ai, bj, At, Bt) do { __builtin_amdgcn_s_setprio(1); _Pragma("unroll") for (int m = 0; m < 4; ++m) _Pragma("unroll") for (int n = 0; n < 2; ++n) _Pragma("unroll") for (int k = 0; k < 2; ++k) \
;         acc[ai][bj][m][n] = __builtin_amdgcn_mfma_f32_16x16x32_bf16(Bt[n][k], At[m][k], acc[ai][bj][m][n], 0, 0, 0); __builtin_amdgcn_s_setprio(0); } while (0)
; #define PG8_WAIT_V(n) asm volatile("s_waitcnt vmcnt(" #n ")" ::: "memory")
; #define PG8_WAIT_L(n) asm volatile("s_waitcnt lgkmcnt(" #n ")" ::: "memory")
; #define PG8_BAR __builtin_amdgcn_s_barrier()
; #define PG8_SCHED __builtin_amdgcn_sched_barrier(0)
; template <class Epi, class Sched, bool ALIGN_EPI = false, bool SP2 = false>
; __device__ __forceinline__ void gemm_phase(PG8_LAS unsigned char* lds, const Gemm g, const Sched& S, const Epi& E) {
;     ...
;             PG8_WAIT_V(8); PG8_WAIT_L(0); PG8_BAR; PG8_MMA(0, 0, At, B0); PG8_MMA(0, 1, At, B1); PG8_BAR; PG8_SCHED;
;             PG8_LDA(At, 1, 1); PG8_STAGE(PG8_SB(1, 0), b3, voffB); PG8_STAGE(PG8_SB(1, 1), b3 + hstep, voffB); PG8_STAGE(PG8_SA(1, 0), a3, voffA);
;             PG8_WAIT_V(8); PG8_WAIT_L(0); PG8_BAR; PG8_MMA(1, 0, At, B0); PG8_MMA(1, 1, At, B1); PG8_BAR; PG8_SCHED;
;     ...
;         if constexpr (ALIGN_EPI) { if (wr == 0) PG8_BAR; }
	s_setprio 0
	s_add_i32 s44, s67, s47
	v_lshl_add_u64 v[160:161], v[160:161], 0, s[16:17]
	s_mov_b32 m0, s44
	ds_read_b128 v[198:201], v177 offset:49152
	ds_read_b128 v[202:205], v177 offset:50176
	ds_read_b128 v[206:209], v177 offset:51200
	ds_read_b128 v[210:213], v177 offset:52224
	ds_read_b128 v[214:217], v177 offset:53248
	ds_read_b128 v[218:221], v177 offset:54272
	ds_read_b128 v[222:225], v177 offset:55296
	ds_read_b128 v[226:229], v177 offset:56320
	global_load_lds_dwordx4 v[160:161], off
	s_add_i32 m0, s44, 0x2000
	s_add_u32 s42, s42, 0x80080
	v_lshl_add_u64 v[160:161], v[164:165], 0, s[16:17]
	s_addc_u32 s43, s43, 0
	s_add_i32 s44, s68, s47
	global_load_lds_dwordx4 v[160:161], off
	v_lshl_add_u64 v[160:161], s[42:43], 0, v[144:145]
	s_mov_b32 m0, s44
	s_nop 0
	global_load_lds_dwordx4 v[160:161], off
	v_lshl_add_u64 v[160:161], s[42:43], 0, v[146:147]
	s_add_i32 m0, s44, 0x2000
	s_nop 0
	global_load_lds_dwordx4 v[160:161], off
	v_lshl_add_u64 v[160:161], v[170:171], 0, s[16:17]
	s_mov_b32 m0, s55
	s_nop 0
	global_load_lds_dwordx4 v[160:161], off
	v_lshl_add_u64 v[160:161], v[194:195], 0, s[16:17]
	s_mov_b32 m0, s56
	s_nop 0
	global_load_lds_dwordx4 v[160:161], off
	s_waitcnt vmcnt(8)
	s_waitcnt lgkmcnt(0)
	s_barrier
	s_setprio 1
	v_mfma_f32_16x16x32_bf16 v[60:63], v[108:111], v[198:201], v[60:63]
	v_mfma_f32_16x16x32_bf16 v[56:59], v[116:119], v[198:201], v[56:59]
	v_mfma_f32_16x16x32_bf16 v[36:39], v[108:111], v[206:209], v[36:39]
	v_mfma_f32_16x16x32_bf16 v[44:47], v[116:119], v[206:209], v[44:47]
	v_mfma_f32_16x16x32_bf16 v[20:23], v[108:111], v[214:217], v[20:23]
	v_mfma_f32_16x16x32_bf16 v[28:31], v[116:119], v[214:217], v[28:31]
	v_mfma_f32_16x16x32_bf16 v[4:7], v[108:111], v[222:225], v[4:7]
	v_mfma_f32_16x16x32_bf16 v[12:15], v[116:119], v[222:225], v[12:15]
	v_mfma_f32_16x16x32_bf16 v[60:63], v[112:115], v[202:205], v[60:63]
	v_mfma_f32_16x16x32_bf16 v[56:59], v[120:123], v[202:205], v[56:59]
	v_mfma_f32_16x16x32_bf16 v[36:39], v[112:115], v[210:213], v[36:39]
	v_mfma_f32_16x16x32_bf16 v[44:47], v[120:123], v[210:213], v[44:47]
	v_mfma_f32_16x16x32_bf16 v[20:23], v[112:115], v[218:221], v[20:23]
	v_mfma_f32_16x16x32_bf16 v[28:31], v[120:123], v[218:221], v[28:31]
	v_mfma_f32_16x16x32_bf16 v[4:7], v[112:115], v[226:229], v[4:7]
	v_mfma_f32_16x16x32_bf16 v[12:15], v[120:123], v[226:229], v[12:15]
	s_setprio 0
	s_setprio 1
	v_mfma_f32_16x16x32_bf16 v[48:51], v[178:181], v[198:201], v[48:51]
	v_mfma_f32_16x16x32_bf16 v[52:55], v[186:189], v[198:201], v[52:55]
	v_mfma_f32_16x16x32_bf16 v[40:43], v[178:181], v[206:209], v[40:43]
	v_mfma_f32_16x16x32_bf16 v[32:35], v[186:189], v[206:209], v[32:35]
	v_mfma_f32_16x16x32_bf16 v[24:27], v[178:181], v[214:217], v[24:27]
	v_mfma_f32_16x16x32_bf16 v[16:19], v[186:189], v[214:217], v[16:19]
	v_mfma_f32_16x16x32_bf16 v[8:11], v[178:181], v[222:225], v[8:11]
	v_mfma_f32_16x16x32_bf16 v[0:3], v[186:189], v[222:225], v[0:3]
	v_mfma_f32_16x16x32_bf16 v[48:51], v[182:185], v[202:205], v[48:51]
	v_mfma_f32_16x16x32_bf16 v[52:55], v[190:193], v[202:205], v[52:55]
	v_mfma_f32_16x16x32_bf16 v[40:43], v[182:185], v[210:213], v[40:43]
	v_mfma_f32_16x16x32_bf16 v[32:35], v[190:193], v[210:213], v[32:35]
	v_mfma_f32_16x16x32_bf16 v[24:27], v[182:185], v[218:221], v[24:27]
	v_mfma_f32_16x16x32_bf16 v[16:19], v[190:193], v[218:221], v[16:19]
	v_mfma_f32_16x16x32_bf16 v[8:11], v[182:185], v[226:229], v[8:11]
	v_mfma_f32_16x16x32_bf16 v[0:3], v[190:193], v[226:229], v[0:3]
	s_barrier
	s_setprio 0
	s_add_i32 s66, s66, 2
	s_add_u32 s8, s8, 0x100
	s_addc_u32 s9, s9, 0
	s_add_u32 s48, s48, 0x100
	s_addc_u32 s49, s49, 0
	s_cmp_gt_u32 s66, 29
	s_cbranch_scc0 .LBB0_1373
	s_and_b64 vcc, exec, s[18:19]
	s_cbranch_vccz .LBB0_1376
	s_barrier

; #define PG8_STAGE(bufoff, gbase, voff) do { _Pragma("unroll") for (int _i = 0; _i < 2; ++_i) \
;         __builtin_amdgcn_global_load_lds((const unsigned*)((const char*)(gbase) + (voff)[_i]), (PG8_LAS unsigned*)(lds + (bufoff) + ldsw + _i * 8192), 16, 0, 0); } while (0)
; #define PG8_LDA(dst, b, h) do { _Pragma("unroll") for (int m = 0; m < 4; ++m) _Pragma("unroll") for (int k = 0; k < 2; ++k) dst[m][k] = *(const PG8_LAS bf16x8*)(lds + PG8_SA(b, h) + aoff + m * 2048 + k * 1024); } while (0)
; #define PG8_LDB(dst, b, h) do { _Pragma("unroll") for (int n = 0; n < 2; ++n) _Pragma("unroll") for (int k = 0; k < 2; ++k) dst[n][k] = *(const PG8_LAS bf16x8*)(lds + PG8_SB(b, h) + boff + n * 2048 + k * 1024); } while (0)
; #define PG8_MMA(ai, bj, At, Bt) do { __builtin_amdgcn_s_setprio(1); _Pragma("unroll") for (int m = 0; m < 4; ++m) _Pragma("unroll") for (int n = 0; n < 2; ++n) _Pragma("unroll") for (int k = 0; k < 2; ++k) \
;         acc[ai][bj][m][n] = __builtin_amdgcn_mfma_f32_16x16x32_bf16(Bt[n][k], At[m][k], acc[ai][bj][m][n], 0, 0, 0); __builtin_amdgcn_s_setprio(0); } while (0)
; #define PG8_WAIT_V(n) asm volatile("s_waitcnt vmcnt(" #n ")" ::: "memory")
; #define PG8_WAIT_L(n) asm volatile("s_waitcnt lgkmcnt(" #n ")" ::: "memory")
; template <class Epi, class Sched, bool ALIGN_EPI = false, bool SP2 = false>
; __device__ __forceinline__ void gemm_phase(PG8_LAS unsigned char* lds, const Gemm g, const Sched& S, const Epi& E) {
;     ...
;             const bool last = (t == nt - 2);
;             const char* a1 = cA + (size_t)(t + 1) * kstep;
;             const char* a2 = last ? nA : cA + (size_t)(t + 2) * kstep; const char* b2 = last ? nB : cB + (size_t)(t + 2) * kstep;
;             const char* a3 = a2 + kstep; const char* b3 = b2 + kstep;
;             if (last && has_next) S.a_ready(nxt);
;             if constexpr (SP2) {
;             PG8_LDB(B0, 0, 0); PG8_LDB(B1, 0, 1); PG8_SCHED; PG8_LDA(At, 0, 0); PG8_STAGE(PG8_SA(1, 1), a1 + hstep, voffA);
;             PG8_WAIT_V(8); PG8_WAIT_L(0); PG8_BAR; PG8_MMA(0, 0, At, B0); PG8_MMA(0, 1, At, B1); PG8_BAR; PG8_SCHED;
;             PG8_LDA(At, 0, 1); PG8_STAGE(PG8_SB(0, 0), b2, voffB); PG8_STAGE(PG8_SB(0, 1), b2 + hstep, voffB); PG8_STAGE(PG8_SA(0, 0), a2, voffA);
;             PG8_WAIT_V(8); PG8_WAIT_L(0); PG8_BAR; PG8_MMA(1, 0, At, B0); PG8_MMA(1, 1, At, B1); PG8_BAR; PG8_SCHED;
.LBB0_1549:
	ds_read_b128 v[144:147], v155
	ds_read_b128 v[148:151], v155 offset:1024
	ds_read_b128 v[158:161], v155 offset:2048
	ds_read_b128 v[162:165], v155 offset:3072
	ds_read_b128 v[166:169], v156
	ds_read_b128 v[170:173], v156 offset:1024
	ds_read_b128 v[174:177], v156 offset:2048
	ds_read_b128 v[178:181], v156 offset:3072
	s_add_u32 s22, s20, 0xfff80080
	s_addc_u32 s23, s21, -1
	s_cmp_eq_u32 s43, 28
	s_cselect_b32 s25, s13, s23
	s_cselect_b32 s24, s39, s22
	s_cselect_b32 s23, s11, s42
	s_cselect_b32 s22, s40, s41
	v_lshl_add_u64 v[214:215], s[20:21], 0, v[136:137]
	s_add_i32 m0, s19, 0xc000
	ds_read_b128 v[182:185], v157
	ds_read_b128 v[186:189], v157 offset:1024
	ds_read_b128 v[190:193], v157 offset:2048
	ds_read_b128 v[194:197], v157 offset:3072
	ds_read_b128 v[198:201], v157 offset:4096
	ds_read_b128 v[202:205], v157 offset:5120
	ds_read_b128 v[206:209], v157 offset:6144
	ds_read_b128 v[210:213], v157 offset:7168
	global_load_lds_dwordx4 v[214:215], off
	v_lshl_add_u64 v[214:215], s[20:21], 0, v[138:139]
	s_add_i32 m0, s19, 0xe000
	s_nop 0
	global_load_lds_dwordx4 v[214:215], off
	s_waitcnt vmcnt(8)
	s_waitcnt lgkmcnt(0)
	s_barrier
	s_setprio 1
	v_mfma_f32_16x16x32_bf16 v[124:127], v[144:147], v[182:185], v[124:127]
	v_mfma_f32_16x16x32_bf16 v[120:123], v[158:161], v[182:185], v[120:123]
	v_mfma_f32_16x16x32_bf16 v[108:111], v[144:147], v[190:193], v[108:111]
	v_mfma_f32_16x16x32_bf16 v[104:107], v[158:161], v[190:193], v[104:107]
	v_mfma_f32_16x16x32_bf16 v[88:91], v[144:147], v[198:201], v[88:91]
	v_mfma_f32_16x16x32_bf16 v[92:95], v[158:161], v[198:201], v[92:95]
	v_mfma_f32_16x16x32_bf16 v[72:75], v[144:147], v[206:209], v[72:75]
	v_mfma_f32_16x16x32_bf16 v[76:79], v[158:161], v[206:209], v[76:79]
	v_mfma_f32_16x16x32_bf16 v[124:127], v[148:151], v[186:189], v[124:127]
	v_mfma_f32_16x16x32_bf16 v[120:123], v[162:165], v[186:189], v[120:123]
	v_mfma_f32_16x16x32_bf16 v[108:111], v[148:151], v[194:197], v[108:111]
	v_mfma_f32_16x16x32_bf16 v[104:107], v[162:165], v[194:197], v[104:107]
	v_mfma_f32_16x16x32_bf16 v[88:91], v[148:151], v[202:205], v[88:91]
	v_mfma_f32_16x16x32_bf16 v[92:95], v[162:165], v[202:205], v[92:95]
	v_mfma_f32_16x16x32_bf16 v[72:75], v[148:151], v[210:213], v[72:75]
	v_mfma_f32_16x16x32_bf16 v[76:79], v[162:165], v[210:213], v[76:79]
	s_setprio 0
	s_setprio 1
	v_mfma_f32_16x16x32_bf16 v[116:119], v[166:169], v[182:185], v[116:119]
	v_mfma_f32_16x16x32_bf16 v[112:115], v[174:177], v[182:185], v[112:115]
	v_mfma_f32_16x16x32_bf16 v[96:99], v[166:169], v[190:193], v[96:99]
	v_mfma_f32_16x16x32_bf16 v[100:103], v[174:177], v[190:193], v[100:103]
	v_mfma_f32_16x16x32_bf16 v[80:83], v[166:169], v[198:201], v[80:83]
	v_mfma_f32_16x16x32_bf16 v[84:87], v[174:177], v[198:201], v[84:87]
	v_mfma_f32_16x16x32_bf16 v[64:67], v[166:169], v[206:209], v[64:67]
	v_mfma_f32_16x16x32_bf16 v[68:71], v[174:177], v[206:209], v[68:71]
	v_mfma_f32_16x16x32_bf16 v[116:119], v[170:173], v[186:189], v[116:119]
	v_mfma_f32_16x16x32_bf16 v[112:115], v[178:181], v[186:189], v[112:115]
	v_mfma_f32_16x16x32_bf16 v[96:99], v[170:173], v[194:197], v[96:99]
	v_mfma_f32_16x16x32_bf16 v[100:103], v[178:181], v[194:197], v[100:103]
	v_mfma_f32_16x16x32_bf16 v[80:83], v[170:173], v[202:205], v[80:83]
	v_mfma_f32_16x16x32_bf16 v[84:87], v[178:181], v[202:205], v[84:87]
	v_mfma_f32_16x16x32_bf16 v[64:67], v[170:173], v[210:213], v[64:67]
	v_mfma_f32_16x16x32_bf16 v[68:71], v[178:181], v[210:213], v[68:71]
	s_barrier
	s_setprio 0
	s_add_i32 s44, s36, s27
	v_lshl_add_u64 v[214:215], s[22:23], 0, v[130:131]
	s_mov_b32 m0, s44
	ds_read_b128 v[182:185], v157 offset:16384
	ds_read_b128 v[186:189], v157 offset:17408
	ds_read_b128 v[190:193], v157 offset:18432
	ds_read_b128 v[194:197], v157 offset:19456
	ds_read_b128 v[198:201], v157 offset:20480
	ds_read_b128 v[202:205], v157 offset:21504
	ds_read_b128 v[206:209], v157 offset:22528
	ds_read_b128 v[210:213], v157 offset:23552
	global_load_lds_dwordx4 v[214:215], off
	s_add_i32 m0, s44, 0x2000
	s_add_u32 s44, s22, 0x80000
	v_lshl_add_u64 v[216:217], s[22:23], 0, v[134:135]
	s_addc_u32 s45, s23, 0
	s_add_i32 s46, s37, s27
	global_load_lds_dwordx4 v[216:217], off
	v_lshl_add_u64 v[218:219], s[44:45], 0, v[130:131]
	s_mov_b32 m0, s46
	v_lshl_add_u64 v[220:221], s[24:25], 0, v[132:133]
	global_load_lds_dwordx4 v[218:219], off
	v_lshl_add_u64 v[218:219], s[44:45], 0, v[134:135]
	s_add_i32 m0, s46, 0x2000
	s_nop 0
	global_load_lds_dwordx4 v[218:219], off
	v_lshl_add_u64 v[218:219], s[24:25], 0, v[128:129]
	s_mov_b32 m0, s19
	s_nop 0
	global_load_lds_dwordx4 v[218:219], off
	s_mov_b32 m0, s28
	s_nop 0
	global_load_lds_dwordx4 v[220:221], off
	s_waitcnt vmcnt(8)
	s_waitcnt lgkmcnt(0)
	s_barrier
; #define PG8_STAGE(bufoff, gbase, voff) do { _Pragma("unroll") for (int _i = 0; _i < 2; ++_i) \
;         __builtin_amdgcn_global_load_lds((const unsigned*)((const char*)(gbase) + (voff)[_i]), (PG8_LAS unsigned*)(lds + (bufoff) + ldsw + _i * 8192), 16, 0, 0); } while (0)
; #define PG8_LDA(dst, b, h) do { _Pragma("unroll") for (int m = 0; m < 4; ++m) _Pragma("unroll") for (int k = 0; k < 2; ++k) dst[m][k] = *(const PG8_LAS bf16x8*)(lds + PG8_SA(b, h) + aoff + m * 2048 + k * 1024); } while (0)
; #define PG8_LDB(dst, b, h) do { _Pragma("unroll") for (int n = 0; n < 2; ++n) _Pragma("unroll") for (int k = 0; k < 2; ++k) dst[n][k] = *(const PG8_LAS bf16x8*)(lds + PG8_SB(b, h) + boff + n * 2048 + k * 1024); } while (0)
; #define PG8_MMA(ai, bj, At, Bt) do { __builtin_amdgcn_s_setprio(1); _Pragma("unroll") for (int m = 0; m < 4; ++m) _Pragma("unroll") for (int n = 0; n < 2; ++n) _Pragma("unroll") for (int k = 0; k < 2; ++k) \
;         acc[ai][bj][m][n] = __builtin_amdgcn_mfma_f32_16x16x32_bf16(Bt[n][k], At[m][k], acc[ai][bj][m][n], 0, 0, 0); __builtin_amdgcn_s_setprio(0); } while (0)
; #define PG8_WAIT_V(n) asm volatile("s_waitcnt vmcnt(" #n ")" ::: "memory")
; #define PG8_WAIT_L(n) asm volatile("s_waitcnt lgkmcnt(" #n ")" ::: "memory")
; #define PG8_BAR __builtin_amdgcn_s_barrier()
; #define PG8_SCHED __builtin_amdgcn_sched_barrier(0)
; template <class Epi, class Sched, bool ALIGN_EPI = false, bool SP2 = false>
; __device__ __forceinline__ void gemm_phase(PG8_LAS unsigned char* lds, const Gemm g, const Sched& S, const Epi& E) {
;     ...
;             PG8_WAIT_V(8); PG8_WAIT_L(0); PG8_BAR; PG8_MMA(1, 0, At, B0); PG8_MMA(1, 1, At, B1); PG8_BAR; PG8_SCHED;
;             PG8_LDB(B0, 1, 0); PG8_LDB(B1, 1, 1); PG8_SCHED; PG8_LDA(At, 1, 0); PG8_STAGE(PG8_SA(0, 1), a2 + hstep, voffA);
;             PG8_WAIT_V(8); PG8_WAIT_L(0); PG8_BAR; PG8_MMA(0, 0, At, B0); PG8_MMA(0, 1, At, B1); PG8_BAR; PG8_SCHED;
;             PG8_LDA(At, 1, 1); PG8_STAGE(PG8_SB(1, 0), b3, voffB); PG8_STAGE(PG8_SB(1, 1), b3 + hstep, voffB); PG8_STAGE(PG8_SA(1, 0), a3, voffA);
;             PG8_WAIT_V(8); PG8_WAIT_L(0); PG8_BAR; PG8_MMA(1, 0, At, B0); PG8_MMA(1, 1, At, B1); PG8_BAR; PG8_SCHED;
	s_setprio 1
	v_mfma_f32_16x16x32_bf16 v[56:59], v[144:147], v[182:185], v[56:59]
	v_mfma_f32_16x16x32_bf16 v[60:63], v[158:161], v[182:185], v[60:63]
	v_mfma_f32_16x16x32_bf16 v[40:43], v[144:147], v[190:193], v[40:43]
	v_mfma_f32_16x16x32_bf16 v[44:47], v[158:161], v[190:193], v[44:47]
	v_mfma_f32_16x16x32_bf16 v[24:27], v[144:147], v[198:201], v[24:27]
	v_mfma_f32_16x16x32_bf16 v[28:31], v[158:161], v[198:201], v[28:31]
	v_mfma_f32_16x16x32_bf16 v[8:11], v[144:147], v[206:209], v[8:11]
	v_mfma_f32_16x16x32_bf16 v[12:15], v[158:161], v[206:209], v[12:15]
	v_mfma_f32_16x16x32_bf16 v[56:59], v[148:151], v[186:189], v[56:59]
	v_mfma_f32_16x16x32_bf16 v[60:63], v[162:165], v[186:189], v[60:63]
	v_mfma_f32_16x16x32_bf16 v[40:43], v[148:151], v[194:197], v[40:43]
	v_mfma_f32_16x16x32_bf16 v[44:47], v[162:165], v[194:197], v[44:47]
	v_mfma_f32_16x16x32_bf16 v[24:27], v[148:151], v[202:205], v[24:27]
	v_mfma_f32_16x16x32_bf16 v[28:31], v[162:165], v[202:205], v[28:31]
	v_mfma_f32_16x16x32_bf16 v[8:11], v[148:151], v[210:213], v[8:11]
	v_mfma_f32_16x16x32_bf16 v[12:15], v[162:165], v[210:213], v[12:15]
	s_setprio 0
	s_setprio 1
	v_mfma_f32_16x16x32_bf16 v[48:51], v[166:169], v[182:185], v[48:51]
	v_mfma_f32_16x16x32_bf16 v[52:55], v[174:177], v[182:185], v[52:55]
	v_mfma_f32_16x16x32_bf16 v[32:35], v[166:169], v[190:193], v[32:35]
	v_mfma_f32_16x16x32_bf16 v[36:39], v[174:177], v[190:193], v[36:39]
	v_mfma_f32_16x16x32_bf16 v[16:19], v[166:169], v[198:201], v[16:19]
	v_mfma_f32_16x16x32_bf16 v[20:23], v[174:177], v[198:201], v[20:23]
	v_mfma_f32_16x16x32_bf16 v[0:3], v[166:169], v[206:209], v[0:3]
	v_mfma_f32_16x16x32_bf16 v[4:7], v[174:177], v[206:209], v[4:7]
	v_mfma_f32_16x16x32_bf16 v[48:51], v[170:173], v[186:189], v[48:51]
	v_mfma_f32_16x16x32_bf16 v[52:55], v[178:181], v[186:189], v[52:55]
	v_mfma_f32_16x16x32_bf16 v[32:35], v[170:173], v[194:197], v[32:35]
	v_mfma_f32_16x16x32_bf16 v[36:39], v[178:181], v[194:197], v[36:39]
	v_mfma_f32_16x16x32_bf16 v[16:19], v[170:173], v[202:205], v[16:19]
	v_mfma_f32_16x16x32_bf16 v[20:23], v[178:181], v[202:205], v[20:23]
	v_mfma_f32_16x16x32_bf16 v[0:3], v[170:173], v[210:213], v[0:3]
	v_mfma_f32_16x16x32_bf16 v[4:7], v[178:181], v[210:213], v[4:7]
	s_barrier
	s_setprio 0
	s_add_i32 s44, 0, 0x18000
	s_add_i32 s45, 0, 0x1c000
	v_add_u32_e32 v162, s44, v153
	v_add_u32_e32 v178, s45, v153
	ds_read_b128 v[144:147], v162
	ds_read_b128 v[148:151], v162 offset:1024
	ds_read_b128 v[158:161], v162 offset:2048
	ds_read_b128 v[162:165], v162 offset:3072
	ds_read_b128 v[166:169], v178
	ds_read_b128 v[170:173], v178 offset:1024
	ds_read_b128 v[174:177], v178 offset:2048
	ds_read_b128 v[178:181], v178 offset:3072
	s_add_u32 s24, s24, 0x80000
	s_addc_u32 s25, s25, 0
	s_mov_b32 m0, s29
	v_lshl_add_u64 v[222:223], s[24:25], 0, v[128:129]
	ds_read_b128 v[182:185], v157 offset:32768
	ds_read_b128 v[186:189], v157 offset:33792
	ds_read_b128 v[190:193], v157 offset:34816
	ds_read_b128 v[194:197], v157 offset:35840
	ds_read_b128 v[198:201], v157 offset:36864
	ds_read_b128 v[202:205], v157 offset:37888
	ds_read_b128 v[206:209], v157 offset:38912
	ds_read_b128 v[210:213], v157 offset:39936
	global_load_lds_dwordx4 v[222:223], off
	v_lshl_add_u64 v[222:223], s[24:25], 0, v[132:133]
	s_mov_b32 m0, s30
	s_nop 0
	global_load_lds_dwordx4 v[222:223], off
	s_waitcnt vmcnt(8)
	s_waitcnt lgkmcnt(0)
	s_barrier
	s_setprio 1
	v_mfma_f32_16x16x32_bf16 v[124:127], v[144:147], v[182:185], v[124:127]
	v_mfma_f32_16x16x32_bf16 v[120:123], v[158:161], v[182:185], v[120:123]
	v_mfma_f32_16x16x32_bf16 v[108:111], v[144:147], v[190:193], v[108:111]
	v_mfma_f32_16x16x32_bf16 v[104:107], v[158:161], v[190:193], v[104:107]
	v_mfma_f32_16x16x32_bf16 v[88:91], v[144:147], v[198:201], v[88:91]
	v_mfma_f32_16x16x32_bf16 v[92:95], v[158:161], v[198:201], v[92:95]
	v_mfma_f32_16x16x32_bf16 v[72:75], v[144:147], v[206:209], v[72:75]
	v_mfma_f32_16x16x32_bf16 v[76:79], v[158:161], v[206:209], v[76:79]
	v_mfma_f32_16x16x32_bf16 v[124:127], v[148:151], v[186:189], v[124:127]
	v_mfma_f32_16x16x32_bf16 v[120:123], v[162:165], v[186:189], v[120:123]
	v_mfma_f32_16x16x32_bf16 v[108:111], v[148:151], v[194:197], v[108:111]
	v_mfma_f32_16x16x32_bf16 v[104:107], v[162:165], v[194:197], v[104:107]
	v_mfma_f32_16x16x32_bf16 v[88:91], v[148:151], v[202:205], v[88:91]
	v_mfma_f32_16x16x32_bf16 v[92:95], v[162:165], v[202:205], v[92:95]
	v_mfma_f32_16x16x32_bf16 v[72:75], v[148:151], v[210:213], v[72:75]
	v_mfma_f32_16x16x32_bf16 v[76:79], v[162:165], v[210:213], v[76:79]
	s_setprio 0
	s_setprio 1
	v_mfma_f32_16x16x32_bf16 v[116:119], v[166:169], v[182:185], v[116:119]
	v_mfma_f32_16x16x32_bf16 v[112:115], v[174:177], v[182:185], v[112:115]
	v_mfma_f32_16x16x32_bf16 v[96:99], v[166:169], v[190:193], v[96:99]
	v_mfma_f32_16x16x32_bf16 v[100:103], v[174:177], v[190:193], v[100:103]
	v_mfma_f32_16x16x32_bf16 v[80:83], v[166:169], v[198:201], v[80:83]
	v_mfma_f32_16x16x32_bf16 v[84:87], v[174:177], v[198:201], v[84:87]
	v_mfma_f32_16x16x32_bf16 v[64:67], v[166:169], v[206:209], v[64:67]
	v_mfma_f32_16x16x32_bf16 v[68:71], v[174:177], v[206:209], v[68:71]
	v_mfma_f32_16x16x32_bf16 v[116:119], v[170:173], v[186:189], v[116:119]
	v_mfma_f32_16x16x32_bf16 v[112:115], v[178:181], v[186:189], v[112:115]
	v_mfma_f32_16x16x32_bf16 v[96:99], v[170:173], v[194:197], v[96:99]
	v_mfma_f32_16x16x32_bf16 v[100:103], v[178:181], v[194:197], v[100:103]
	v_mfma_f32_16x16x32_bf16 v[80:83], v[170:173], v[202:205], v[80:83]
	v_mfma_f32_16x16x32_bf16 v[84:87], v[178:181], v[202:205], v[84:87]
	v_mfma_f32_16x16x32_bf16 v[64:67], v[170:173], v[210:213], v[64:67]
	v_mfma_f32_16x16x32_bf16 v[68:71], v[178:181], v[210:213], v[68:71]
	s_barrier
; #define PG8_STAGE(bufoff, gbase, voff) do { _Pragma("unroll") for (int _i = 0; _i < 2; ++_i) \
;         __builtin_amdgcn_global_load_lds((const unsigned*)((const char*)(gbase) + (voff)[_i]), (PG8_LAS unsigned*)(lds + (bufoff) + ldsw + _i * 8192), 16, 0, 0); } while (0)
; #define PG8_LDA(dst, b, h) do { _Pragma("unroll") for (int m = 0; m < 4; ++m) _Pragma("unroll") for (int k = 0; k < 2; ++k) dst[m][k] = *(const PG8_LAS bf16x8*)(lds + PG8_SA(b, h) + aoff + m * 2048 + k * 1024); } while (0)
; #define PG8_MMA(ai, bj, At, Bt) do { __builtin_amdgcn_s_setprio(1); _Pragma("unroll") for (int m = 0; m < 4; ++m) _Pragma("unroll") for (int n = 0; n < 2; ++n) _Pragma("unroll") for (int k = 0; k < 2; ++k) \
;         acc[ai][bj][m][n] = __builtin_amdgcn_mfma_f32_16x16x32_bf16(Bt[n][k], At[m][k], acc[ai][bj][m][n], 0, 0, 0); __builtin_amdgcn_s_setprio(0); } while (0)
; #define PG8_WAIT_V(n) asm volatile("s_waitcnt vmcnt(" #n ")" ::: "memory")
; #define PG8_WAIT_L(n) asm volatile("s_waitcnt lgkmcnt(" #n ")" ::: "memory")
; #define PG8_BAR __builtin_amdgcn_s_barrier()
; #define PG8_SCHED __builtin_amdgcn_sched_barrier(0)
; template <class Epi, class Sched, bool ALIGN_EPI = false, bool SP2 = false>
; __device__ __forceinline__ void gemm_phase(PG8_LAS unsigned char* lds, const Gemm g, const Sched& S, const Epi& E) {
;     ...
;             PG8_WAIT_V(8); PG8_WAIT_L(0); PG8_BAR; PG8_MMA(0, 0, At, B0); PG8_MMA(0, 1, At, B1); PG8_BAR; PG8_SCHED;
;             PG8_LDA(At, 1, 1); PG8_STAGE(PG8_SB(1, 0), b3, voffB); PG8_STAGE(PG8_SB(1, 1), b3 + hstep, voffB); PG8_STAGE(PG8_SA(1, 0), a3, voffA);
;             PG8_WAIT_V(8); PG8_WAIT_L(0); PG8_BAR; PG8_MMA(1, 0, At, B0); PG8_MMA(1, 1, At, B1); PG8_BAR; PG8_SCHED;
;     ...
;         if constexpr (ALIGN_EPI) { if (wr == 0) PG8_BAR; }
	s_setprio 0
	s_add_i32 s24, s44, s27
	v_lshl_add_u64 v[214:215], v[214:215], 0, s[4:5]
	s_mov_b32 m0, s24
	ds_read_b128 v[182:185], v157 offset:49152
	ds_read_b128 v[186:189], v157 offset:50176
	ds_read_b128 v[190:193], v157 offset:51200
	ds_read_b128 v[194:197], v157 offset:52224
	ds_read_b128 v[198:201], v157 offset:53248
	ds_read_b128 v[202:205], v157 offset:54272
	ds_read_b128 v[206:209], v157 offset:55296
	ds_read_b128 v[210:213], v157 offset:56320
	global_load_lds_dwordx4 v[214:215], off
	s_add_i32 m0, s24, 0x2000
	s_add_u32 s22, s22, 0x80080
	v_lshl_add_u64 v[214:215], v[216:217], 0, s[4:5]
	s_addc_u32 s23, s23, 0
	s_add_i32 s24, s45, s27
	global_load_lds_dwordx4 v[214:215], off
	v_lshl_add_u64 v[214:215], s[22:23], 0, v[130:131]
	s_mov_b32 m0, s24
	s_nop 0
	global_load_lds_dwordx4 v[214:215], off
	v_lshl_add_u64 v[214:215], s[22:23], 0, v[134:135]
	s_add_i32 m0, s24, 0x2000
	s_nop 0
	global_load_lds_dwordx4 v[214:215], off
	v_lshl_add_u64 v[214:215], v[218:219], 0, s[4:5]
	s_mov_b32 m0, s33
	s_nop 0
	global_load_lds_dwordx4 v[214:215], off
	v_lshl_add_u64 v[214:215], v[220:221], 0, s[4:5]
	s_mov_b32 m0, s34
	s_nop 0
	global_load_lds_dwordx4 v[214:215], off
	s_waitcnt vmcnt(8)
	s_waitcnt lgkmcnt(0)
	s_barrier
	s_setprio 1
	v_mfma_f32_16x16x32_bf16 v[56:59], v[144:147], v[182:185], v[56:59]
	v_mfma_f32_16x16x32_bf16 v[60:63], v[158:161], v[182:185], v[60:63]
	v_mfma_f32_16x16x32_bf16 v[40:43], v[144:147], v[190:193], v[40:43]
	v_mfma_f32_16x16x32_bf16 v[44:47], v[158:161], v[190:193], v[44:47]
	v_mfma_f32_16x16x32_bf16 v[24:27], v[144:147], v[198:201], v[24:27]
	v_mfma_f32_16x16x32_bf16 v[28:31], v[158:161], v[198:201], v[28:31]
	v_mfma_f32_16x16x32_bf16 v[8:11], v[144:147], v[206:209], v[8:11]
	v_mfma_f32_16x16x32_bf16 v[12:15], v[158:161], v[206:209], v[12:15]
	v_mfma_f32_16x16x32_bf16 v[56:59], v[148:151], v[186:189], v[56:59]
	v_mfma_f32_16x16x32_bf16 v[60:63], v[162:165], v[186:189], v[60:63]
	v_mfma_f32_16x16x32_bf16 v[40:43], v[148:151], v[194:197], v[40:43]
	v_mfma_f32_16x16x32_bf16 v[44:47], v[162:165], v[194:197], v[44:47]
	v_mfma_f32_16x16x32_bf16 v[24:27], v[148:151], v[202:205], v[24:27]
	v_mfma_f32_16x16x32_bf16 v[28:31], v[162:165], v[202:205], v[28:31]
	v_mfma_f32_16x16x32_bf16 v[8:11], v[148:151], v[210:213], v[8:11]
	v_mfma_f32_16x16x32_bf16 v[12:15], v[162:165], v[210:213], v[12:15]
	s_setprio 0
	s_setprio 1
	v_mfma_f32_16x16x32_bf16 v[48:51], v[166:169], v[182:185], v[48:51]
	v_mfma_f32_16x16x32_bf16 v[52:55], v[174:177], v[182:185], v[52:55]
	v_mfma_f32_16x16x32_bf16 v[32:35], v[166:169], v[190:193], v[32:35]
	v_mfma_f32_16x16x32_bf16 v[36:39], v[174:177], v[190:193], v[36:39]
	v_mfma_f32_16x16x32_bf16 v[16:19], v[166:169], v[198:201], v[16:19]
	v_mfma_f32_16x16x32_bf16 v[20:23], v[174:177], v[198:201], v[20:23]
	v_mfma_f32_16x16x32_bf16 v[0:3], v[166:169], v[206:209], v[0:3]
	v_mfma_f32_16x16x32_bf16 v[4:7], v[174:177], v[206:209], v[4:7]
	v_mfma_f32_16x16x32_bf16 v[48:51], v[170:173], v[186:189], v[48:51]
	v_mfma_f32_16x16x32_bf16 v[52:55], v[178:181], v[186:189], v[52:55]
	v_mfma_f32_16x16x32_bf16 v[32:35], v[170:173], v[194:197], v[32:35]
	v_mfma_f32_16x16x32_bf16 v[36:39], v[178:181], v[194:197], v[36:39]
	v_mfma_f32_16x16x32_bf16 v[16:19], v[170:173], v[202:205], v[16:19]
	v_mfma_f32_16x16x32_bf16 v[20:23], v[178:181], v[202:205], v[20:23]
	v_mfma_f32_16x16x32_bf16 v[0:3], v[170:173], v[210:213], v[0:3]
	v_mfma_f32_16x16x32_bf16 v[4:7], v[178:181], v[210:213], v[4:7]
	s_barrier
	s_setprio 0
	s_add_i32 s43, s43, 2
	s_add_u32 s20, s20, 0x100
	s_addc_u32 s21, s21, 0
	s_add_u32 s41, s41, 0x100
	s_addc_u32 s42, s42, 0
	s_cmp_gt_u32 s43, 29
	s_cbranch_scc0 .LBB0_1549
	s_and_b64 vcc, exec, s[6:7]
	s_cbranch_vccz .LBB0_1552
	s_barrier
